# v-side: latency-critical token header and epilogue at s_setprio 3, dot4c body at 2
# baseline (speedup 1.0000x reference)
; __device__ void phase_gather(const Params& p) {
;     ...
;     const int id0 = idxg[(size_t)t * 128 + lane], id1 = idxg[(size_t)t * 128 + 64 + lane];
;     const float g0 = gg[(size_t)t * 128 + lane], g1 = gg[(size_t)t * 128 + 64 + lane];
;     const float su0 = scales[id0], su1 = scales[id1], sv0 = scales[16384 + id0], sv1 = scales[16384 + id1];
;     float* orow = p.out + (size_t)t * DM + lane * 32;
;     const float sx = ((const float*)(ws + OFF_WBUF + 8 * MIB))[t];
;     float sq = (lane < 32) ? ssq2[(size_t)t * 32 + lane] : 0.f;
;     sq = wave_sum(sq);
;     const float rs2 = rsqrtf(sq * (1.f / 2048.f) + EPSV);
;     const int* wbuf = (const int*)(ws + OFF_WBUF);
;     const int d0 = wbuf[(size_t)t * 128 + lane], d1 = wbuf[(size_t)t * 128 + 64 + lane];
;     const float w0 = gelu_((float)d0 * (su0 * sx * rs2)) * g0 * sv0;
;     const float w1 = gelu_((float)d1 * (su1 * sx * rs2)) * g1 * sv1;
;     float wmax = fmaxf(fabsf(w0), fabsf(w1));
; #pragma unroll
;     for (int o = 32; o > 0; o >>= 1) wmax = fmaxf(wmax, __shfl_xor(wmax, o));
;     const float sw = wmax * (1.f / 127.f);
;     const float winv = wmax > 0.f ? 127.f / wmax : 0.f;
;     const int q0 = __float2int_rn(w0 * winv), q1 = __float2int_rn(w1 * winv);
;     int wsumq = q0 + q1;
; #pragma unroll
;     for (int o = 32; o > 0; o >>= 1) wsumq += __shfl_xor(wsumq, o);
.LBB0_1320:
	s_or_b64 exec, exec, s[0:1]
	v_lshl_add_u64 v[0:1], v[0:1], 2, s[70:71]
	v_lshl_add_u64 v[2:3], v[2:3], 2, s[70:71]
	global_load_dword v4, v[0:1], off
	global_load_dword v5, v[2:3], off
	s_waitcnt vmcnt(2)
	ds_bpermute_b32 v0, v126, v13
	v_mul_f32_e32 v2, v11, v10
	s_mov_b32 s4, 0x42fe0000
	s_mov_b64 s[0:1], -1
	v_mov_b32_e32 v163, 0
	s_waitcnt lgkmcnt(0)
	v_add_f32_e32 v0, v13, v0
	ds_bpermute_b32 v1, v127, v0
	v_mov_b32_e32 v164, 0
	v_mov_b32_e32 v161, 0
	v_mov_b32_e32 v162, 0
	v_mov_b32_e32 v159, 0
	s_waitcnt lgkmcnt(0)
	v_add_f32_e32 v0, v0, v1
	ds_bpermute_b32 v1, v128, v0
	v_mov_b32_e32 v160, 0
	v_mov_b32_e32 v157, 0
	v_mov_b32_e32 v158, 0
	v_mov_b32_e32 v152, 0
	s_waitcnt lgkmcnt(0)
	v_add_f32_e32 v0, v0, v1
	ds_bpermute_b32 v1, v129, v0
	v_mov_b32_e32 v154, 0
	v_mov_b32_e32 v149, 0
	v_mov_b32_e32 v150, 0
	v_mov_b32_e32 v144, 0
	s_waitcnt lgkmcnt(0)
	v_add_f32_e32 v0, v0, v1
	ds_bpermute_b32 v1, v130, v0
	v_mov_b32_e32 v146, 0
	v_mov_b32_e32 v155, 0
	v_mov_b32_e32 v156, 0
	v_mov_b32_e32 v151, 0
	s_waitcnt lgkmcnt(0)
	v_add_f32_e32 v0, v0, v1
	ds_bpermute_b32 v1, v131, v0
	v_mov_b32_e32 v153, 0
	v_mov_b32_e32 v147, 0
	v_mov_b32_e32 v148, 0
	v_mov_b32_e32 v143, 0
	s_waitcnt lgkmcnt(0)
	v_add_f32_e32 v0, v0, v1
	v_fmamk_f32 v0, v0, 0x3a000000, v133
	v_mul_f32_e32 v1, 0x4b800000, v0
	v_cmp_gt_f32_e32 vcc, s55, v0
	v_mov_b32_e32 v145, 0
	v_mov_b32_e32 v141, 0
	v_cndmask_b32_e32 v0, v0, v1, vcc
	v_rsq_f32_e32 v0, v0
	v_mul_f32_e32 v1, v12, v10
	v_mov_b32_e32 v142, 0
	v_mov_b32_e32 v136, 0
	v_mul_f32_e32 v3, 0x45800000, v0
	v_cndmask_b32_e32 v0, v0, v3, vcc
	v_mul_f32_e32 v1, v1, v0
	v_mul_f32_e32 v0, v2, v0
	v_mov_b32_e32 v140, 0
	v_mov_b32_e32 v137, 0
	v_mov_b32_e32 v139, 0
	v_mov_b32_e32 v134, 0
	v_mov_b32_e32 v135, 0
	v_mov_b32_e32 v123, 0
	v_mov_b32_e32 v125, 0
	s_waitcnt vmcnt(1)
	v_cvt_f32_i32_e32 v3, v4
	s_waitcnt vmcnt(0)
	v_cvt_f32_i32_e32 v4, v5
	v_mul_f32_e32 v1, v1, v3
	v_mul_f32_e32 v0, v0, v4
	v_mul_f32_e32 v2, 0x3d372713, v1
	v_mul_f32_e32 v3, 0x3d372713, v0
	v_mul_f32_e32 v2, v1, v2
	v_mul_f32_e32 v3, v0, v3
	v_fma_f32 v2, v1, v2, v1
	v_fma_f32 v3, v0, v3, v0
	v_mul_f32_e32 v2, 0x3f4c422a, v2
	v_mul_f32_e32 v3, 0x3f4c422a, v3
	v_add_f32_e32 v2, v2, v2
	v_add_f32_e32 v3, v3, v3
	v_mul_f32_e32 v2, 0xbfb8aa3b, v2
	v_mul_f32_e32 v3, 0xbfb8aa3b, v3
	v_exp_f32_e32 v2, v2
	v_exp_f32_e32 v3, v3
	v_add_f32_e32 v2, 1.0, v2
	v_add_f32_e32 v3, 1.0, v3
	v_rcp_f32_e32 v2, v2
	v_rcp_f32_e32 v3, v3
	v_mul_f32_e32 v1, v1, v2
	v_mul_f32_e32 v0, v0, v3
	v_mul_f32_e32 v1, v6, v1
	v_mul_f32_e32 v0, v7, v0
	v_mul_f32_e32 v1, v8, v1
	v_mul_f32_e32 v0, v9, v0
	v_max_f32_e64 v2, |v1|, |v0|
	ds_bpermute_b32 v3, v126, v2
	s_waitcnt lgkmcnt(0)
	v_max_f32_e32 v3, v3, v3
	v_max_f32_e32 v2, v2, v3
	ds_bpermute_b32 v3, v127, v2
	s_waitcnt lgkmcnt(0)
	v_max_f32_e32 v3, v3, v3
	v_max_f32_e32 v2, v2, v3
	ds_bpermute_b32 v3, v128, v2
	s_waitcnt lgkmcnt(0)
	v_max_f32_e32 v3, v3, v3
	v_max_f32_e32 v2, v2, v3
	ds_bpermute_b32 v3, v129, v2
	s_waitcnt lgkmcnt(0)
	v_max_f32_e32 v3, v3, v3
	v_max_f32_e32 v2, v2, v3
	ds_bpermute_b32 v3, v130, v2
	s_waitcnt lgkmcnt(0)
	v_max_f32_e32 v3, v3, v3
	v_max_f32_e32 v2, v2, v3
	ds_bpermute_b32 v3, v131, v2
	s_waitcnt lgkmcnt(0)
	v_max_f32_e32 v3, v3, v3
	v_max_f32_e32 v165, v2, v3
	v_div_scale_f32 v2, s[2:3], v165, v165, s4
	v_rcp_f32_e32 v3, v2
	v_div_scale_f32 v4, vcc, s4, v165, s4
	v_fma_f32 v5, -v2, v3, 1.0
	v_fmac_f32_e32 v3, v5, v3
	v_mul_f32_e32 v5, v4, v3
	v_fma_f32 v6, -v2, v5, v4
	v_fmac_f32_e32 v5, v6, v3
	v_fma_f32 v2, -v2, v5, v4
	v_div_fmas_f32 v2, v2, v3, v5
	v_div_fixup_f32 v2, v2, v165, s4
	v_cmp_lt_f32_e32 vcc, 0, v165
	s_nop 1
	v_cndmask_b32_e32 v2, 0, v2, vcc
	v_mul_f32_e32 v1, v1, v2
	v_mul_f32_e32 v0, v0, v2
	v_rndne_f32_e32 v1, v1
	v_rndne_f32_e32 v0, v0
	v_cvt_i32_f32_e32 v1, v1
	v_cvt_i32_f32_e32 v0, v0
	v_bfe_i32 v222, v112, 11, 1
	v_and_b32_e32 v222, 3, v222
	v_lshrrev_b32_e32 v216, 12, v122
	v_lshrrev_b32_e32 v217, 12, v124
	v_xor_b32_e32 v216, v216, v222
	v_xor_b32_e32 v217, v217, v222
	v_and_b32_e32 v225, 7, v112
	v_lshlrev_b32_e32 v225, 10, v225
	v_lshl_add_u32 v226, v138, 2, v225
	s_mov_b32 s86, 0
	v_mov_b32_e32 v218, 0
	v_mov_b32_e32 v219, 0
	v_cmp_eq_u32_e64 s[82:83], 0, v216
	v_cmp_eq_u32_e64 s[84:85], 0, v217
	s_nop 3
	v_mbcnt_lo_u32_b32 v220, s82, 0
	v_mbcnt_hi_u32_b32 v220, s83, v220
	v_mbcnt_lo_u32_b32 v221, s84, 0
	v_mbcnt_hi_u32_b32 v221, s85, v221
	s_bcnt1_i32_b64 s87, s[82:83]
	s_bcnt1_i32_b64 s56, s[84:85]
	v_add_u32_e32 v220, s86, v220
	s_add_i32 s86, s86, s87
	v_add_u32_e32 v221, s86, v221
	s_add_i32 s86, s86, s56
	v_cndmask_b32_e64 v218, v218, v220, s[82:83]
	v_cndmask_b32_e64 v219, v219, v221, s[84:85]
	v_cmp_eq_u32_e64 s[82:83], 1, v216
	v_cmp_eq_u32_e64 s[84:85], 1, v217
	s_nop 3
	v_mbcnt_lo_u32_b32 v220, s82, 0
	v_mbcnt_hi_u32_b32 v220, s83, v220
	v_mbcnt_lo_u32_b32 v221, s84, 0
	v_mbcnt_hi_u32_b32 v221, s85, v221
	s_bcnt1_i32_b64 s87, s[82:83]
	s_bcnt1_i32_b64 s56, s[84:85]
	v_add_u32_e32 v220, s86, v220
	s_add_i32 s86, s86, s87
	v_add_u32_e32 v221, s86, v221
	s_add_i32 s86, s86, s56
	v_cndmask_b32_e64 v218, v218, v220, s[82:83]
	v_cndmask_b32_e64 v219, v219, v221, s[84:85]
	v_cmp_eq_u32_e64 s[82:83], 2, v216
	v_cmp_eq_u32_e64 s[84:85], 2, v217
	s_nop 3
	v_mbcnt_lo_u32_b32 v220, s82, 0
	v_mbcnt_hi_u32_b32 v220, s83, v220
	v_mbcnt_lo_u32_b32 v221, s84, 0
	v_mbcnt_hi_u32_b32 v221, s85, v221
	s_bcnt1_i32_b64 s87, s[82:83]
	s_bcnt1_i32_b64 s56, s[84:85]
	v_add_u32_e32 v220, s86, v220
	s_add_i32 s86, s86, s87
	v_add_u32_e32 v221, s86, v221
	s_add_i32 s86, s86, s56
	v_cndmask_b32_e64 v218, v218, v220, s[82:83]
	v_cndmask_b32_e64 v219, v219, v221, s[84:85]
	v_cmp_eq_u32_e64 s[82:83], 3, v216
	v_cmp_eq_u32_e64 s[84:85], 3, v217
	s_nop 3
	v_mbcnt_lo_u32_b32 v220, s82, 0
	v_mbcnt_hi_u32_b32 v220, s83, v220
	v_mbcnt_lo_u32_b32 v221, s84, 0
	v_mbcnt_hi_u32_b32 v221, s85, v221
	s_bcnt1_i32_b64 s87, s[82:83]
	s_bcnt1_i32_b64 s56, s[84:85]
	v_add_u32_e32 v220, s86, v220
	s_add_i32 s86, s86, s87
	v_add_u32_e32 v221, s86, v221
	s_add_i32 s86, s86, s56
	v_cndmask_b32_e64 v218, v218, v220, s[82:83]
	v_cndmask_b32_e64 v219, v219, v221, s[84:85]
	v_and_b32_e32 v220, 0xff, v1
	v_and_b32_e32 v221, 0xff, v0
	v_lshl_or_b32 v223, v122, 8, v220
	v_lshl_or_b32 v224, v124, 8, v221
	v_lshl_add_u32 v218, v218, 2, v225
	v_lshl_add_u32 v219, v219, 2, v225
	ds_write_b32 v218, v223
	ds_write_b32 v219, v224
	s_waitcnt lgkmcnt(0)
; __device__ void phase_gather(const Params& p) {
;     ...
;     int wsumq = q0 + q1;
; #pragma unroll
;     for (int o = 32; o > 0; o >>= 1) wsumq += __shfl_xor(wsumq, o);
;     int pk0 = (int)(((unsigned)q0 & 0xffu) << (8 * (lane & 3))), pk1 = (int)(((unsigned)q1 & 0xffu) << (8 * (lane & 3)));
;     pk0 |= __shfl_xor(pk0, 1); pk0 |= __shfl_xor(pk0, 2);
;     pk1 |= __shfl_xor(pk1, 1); pk1 |= __shfl_xor(pk1, 2);
;     int acc[32];
; #pragma unroll
;     for (int i = 0; i < 32; ++i) acc[i] = 0;
; #pragma unroll 1
;     for (int half = 0; half < 2; ++half) {
;       const int idv = half ? id1 : id0;
;       const int pkv = half ? pk1 : pk0;
;       u32x4 rr[3][GROWS];
; #pragma unroll
;       for (int k = 0; k < GROWS; ++k) {
;         const int e = __builtin_amdgcn_readlane(idv, k);
;         rr[0][k] = *(const u32x4*)(vb + (size_t)e * 1024 + lane * 16);
;         const int e2 = __builtin_amdgcn_readlane(idv, GROWS + k);
	ds_read_b32 v223, v226
	ds_read_b32 v224, v226 offset:256
	s_waitcnt lgkmcnt(0)
	v_lshrrev_b32_e32 v122, 8, v223
	v_lshrrev_b32_e32 v124, 8, v224
	v_bfe_i32 v1, v223, 0, 8
	v_bfe_i32 v0, v224, 0, 8
	v_add_u32_e32 v2, v1, v0
	ds_bpermute_b32 v3, v126, v2
	v_lshlrev_b32_sdwa v1, v132, v1 dst_sel:DWORD dst_unused:UNUSED_PAD src0_sel:DWORD src1_sel:BYTE_0
	v_lshlrev_b32_sdwa v0, v132, v0 dst_sel:DWORD dst_unused:UNUSED_PAD src0_sel:DWORD src1_sel:BYTE_0
	ds_bpermute_b32 v4, v131, v1
	ds_bpermute_b32 v5, v131, v0
	s_waitcnt lgkmcnt(2)
	v_add_u32_e32 v2, v2, v3
	ds_bpermute_b32 v3, v127, v2
	s_waitcnt lgkmcnt(2)
	v_or_b32_e32 v1, v1, v4
	s_waitcnt lgkmcnt(1)
	v_or_b32_e32 v0, v0, v5
	ds_bpermute_b32 v4, v130, v1
	s_waitcnt lgkmcnt(1)
	v_add_u32_e32 v2, v2, v3
	ds_bpermute_b32 v3, v128, v2
	ds_bpermute_b32 v5, v130, v0
	s_waitcnt lgkmcnt(2)
	v_or_b32_e32 v168, v1, v4
	s_waitcnt lgkmcnt(1)
	v_add_u32_e32 v2, v2, v3
	ds_bpermute_b32 v3, v129, v2
	s_waitcnt lgkmcnt(1)
	v_or_b32_e32 v169, v0, v5
	s_waitcnt lgkmcnt(0)
	v_add_u32_e32 v2, v2, v3
	ds_bpermute_b32 v3, v130, v2
	s_waitcnt lgkmcnt(0)
	v_add_u32_e32 v166, v2, v3
	ds_bpermute_b32 v167, v131, v166
	s_setprio 2
.LBB0_1321:
	v_cndmask_b32_e64 v1, v124, v122, s[0:1]
	v_cndmask_b32_e64 v0, 0, 1, s[0:1]
	v_readlane_b32 s56, v1, 24
	s_ashr_i32 s57, s56, 31
	s_lshl_b64 s[84:85], s[56:57], 10
	v_readlane_b32 s56, v1, 25
	s_ashr_i32 s57, s56, 31
	s_lshl_b64 s[82:83], s[56:57], 10
	v_readlane_b32 s56, v1, 26
	s_ashr_i32 s57, s56, 31
	s_lshl_b64 s[86:87], s[56:57], 10
	v_readlane_b32 s56, v1, 27
	s_ashr_i32 s57, s56, 31
	s_lshl_b64 s[88:89], s[56:57], 10
	v_readlane_b32 s56, v1, 28
	s_ashr_i32 s57, s56, 31
	s_lshl_b64 s[90:91], s[56:57], 10
	v_readlane_b32 s56, v1, 29
	s_ashr_i32 s57, s56, 31
	s_lshl_b64 s[92:93], s[56:57], 10
	v_readlane_b32 s56, v1, 30
	s_ashr_i32 s57, s56, 31
	s_lshl_b64 s[94:95], s[56:57], 10
	v_readlane_b32 s56, v1, 31
	s_ashr_i32 s57, s56, 31
	s_lshl_b64 s[96:97], s[56:57], 10
	v_readlane_b32 s56, v1, 32
	s_ashr_i32 s57, s56, 31
	s_lshl_b64 s[66:67], s[56:57], 10
	v_readlane_b32 s56, v1, 33
	s_ashr_i32 s57, s56, 31
	s_lshl_b64 s[68:69], s[56:57], 10
	v_readlane_b32 s56, v1, 34
	s_ashr_i32 s57, s56, 31
	s_lshl_b64 s[70:71], s[56:57], 10
	v_readlane_b32 s56, v1, 35
	s_ashr_i32 s57, s56, 31
	s_lshl_b64 s[72:73], s[56:57], 10
	v_readlane_b32 s56, v1, 36
	s_ashr_i32 s57, s56, 31
	s_lshl_b64 s[74:75], s[56:57], 10
	v_readlane_b32 s56, v1, 37
	s_ashr_i32 s57, s56, 31
	s_lshl_b64 s[76:77], s[56:57], 10
	v_readlane_b32 s56, v1, 38
	s_ashr_i32 s57, s56, 31
	s_lshl_b64 s[78:79], s[56:57], 10
	v_readlane_b32 s56, v1, 39
	s_ashr_i32 s57, s56, 31
	s_lshl_b64 s[80:81], s[56:57], 10
	v_readlane_b32 s56, v1, 40
	s_ashr_i32 s57, s56, 31
	s_lshl_b64 s[56:57], s[56:57], 10
	v_writelane_b32 v250, s56, 34
	v_readlane_b32 vcc_lo, v1, 48
	s_ashr_i32 vcc_hi, vcc_lo, 31
	v_writelane_b32 v250, s57, 35
	v_readlane_b32 s56, v1, 41
	s_ashr_i32 s57, s56, 31
	s_lshl_b64 s[56:57], s[56:57], 10
	v_writelane_b32 v250, s56, 36
	s_lshl_b64 vcc, vcc, 10
	v_readlane_b32 s2, v1, 0
	v_writelane_b32 v250, s57, 37
	v_readlane_b32 s56, v1, 42
	s_ashr_i32 s57, s56, 31
	s_lshl_b64 s[56:57], s[56:57], 10
	v_writelane_b32 v250, s56, 38
	s_ashr_i32 s3, s2, 31
	s_lshl_b64 s[50:51], s[2:3], 10
	v_writelane_b32 v250, s57, 39
	v_writelane_b32 v250, vcc_lo, 40
	v_readlane_b32 s2, v1, 8
	s_ashr_i32 s3, s2, 31
	v_writelane_b32 v250, vcc_hi, 41
	v_readlane_b32 vcc_lo, v1, 49
	s_ashr_i32 vcc_hi, vcc_lo, 31
	s_lshl_b64 vcc, vcc, 10
	v_writelane_b32 v250, vcc_lo, 42
	s_lshl_b64 s[48:49], s[2:3], 10
	v_readlane_b32 s2, v1, 1
	v_writelane_b32 v250, vcc_hi, 43
	v_readlane_b32 vcc_lo, v1, 50
	s_ashr_i32 vcc_hi, vcc_lo, 31
	s_lshl_b64 vcc, vcc, 10
	v_writelane_b32 v250, vcc_lo, 44
	s_ashr_i32 s3, s2, 31
	s_lshl_b64 s[46:47], s[2:3], 10
	v_writelane_b32 v250, vcc_hi, 45
	v_readlane_b32 vcc_lo, v1, 51
	s_ashr_i32 vcc_hi, vcc_lo, 31
	s_lshl_b64 vcc, vcc, 10
	v_writelane_b32 v250, vcc_lo, 46
	v_readlane_b32 s2, v1, 9
	s_ashr_i32 s3, s2, 31
	v_writelane_b32 v250, vcc_hi, 47
	v_readlane_b32 vcc_lo, v1, 52
	s_ashr_i32 vcc_hi, vcc_lo, 31
	s_lshl_b64 vcc, vcc, 10
	v_writelane_b32 v250, vcc_lo, 48
	s_lshl_b64 s[44:45], s[2:3], 10
	v_readlane_b32 s2, v1, 2
	v_writelane_b32 v250, vcc_hi, 49
	v_readlane_b32 vcc_lo, v1, 53
	s_ashr_i32 vcc_hi, vcc_lo, 31
	s_lshl_b64 vcc, vcc, 10
	v_writelane_b32 v250, vcc_lo, 50
	s_ashr_i32 s3, s2, 31
	s_lshl_b64 s[42:43], s[2:3], 10
	v_writelane_b32 v250, vcc_hi, 51
	v_readlane_b32 vcc_lo, v1, 54
	s_ashr_i32 vcc_hi, vcc_lo, 31
	s_lshl_b64 vcc, vcc, 10
	v_writelane_b32 v250, vcc_lo, 52
	v_readlane_b32 s2, v1, 10
	s_ashr_i32 s3, s2, 31
	v_writelane_b32 v250, vcc_hi, 53
	v_readlane_b32 vcc_lo, v1, 55
	s_ashr_i32 vcc_hi, vcc_lo, 31
	s_lshl_b64 s[40:41], s[2:3], 10
	v_readlane_b32 s2, v1, 3
	s_lshl_b64 vcc, vcc, 10
	s_ashr_i32 s3, s2, 31
	v_writelane_b32 v250, vcc_lo, 54
	s_lshl_b64 s[38:39], s[2:3], 10
	v_readlane_b32 s2, v1, 11
	v_writelane_b32 v250, vcc_hi, 55
	v_readlane_b32 vcc_lo, v1, 56
	s_ashr_i32 s3, s2, 31
	s_ashr_i32 vcc_hi, vcc_lo, 31
	s_lshl_b64 s[36:37], s[2:3], 10
	v_readlane_b32 s2, v1, 4
	s_lshl_b64 vcc, vcc, 10
	s_ashr_i32 s3, s2, 31
	v_writelane_b32 v250, vcc_lo, 6
	s_lshl_b64 s[34:35], s[2:3], 10
	v_readlane_b32 s2, v1, 12
	v_writelane_b32 v250, vcc_hi, 7
	v_readlane_b32 vcc_lo, v1, 57
	s_ashr_i32 s3, s2, 31
	s_ashr_i32 vcc_hi, vcc_lo, 31
	s_lshl_b64 s[30:31], s[2:3], 10
	v_readlane_b32 s2, v1, 5
	s_lshl_b64 vcc, vcc, 10
	s_ashr_i32 s3, s2, 31
	v_writelane_b32 v250, vcc_lo, 4
	s_lshl_b64 s[28:29], s[2:3], 10
	v_readlane_b32 s2, v1, 13
	v_writelane_b32 v250, vcc_hi, 5
	v_readlane_b32 vcc_lo, v1, 58
; __device__ void phase_gather(const Params& p) {
;     ...
;       const int idv = half ? id1 : id0;
;       const int pkv = half ? pk1 : pk0;
;       u32x4 rr[3][GROWS];
; #pragma unroll
;       for (int k = 0; k < GROWS; ++k) {
;         const int e = __builtin_amdgcn_readlane(idv, k);
;         rr[0][k] = *(const u32x4*)(vb + (size_t)e * 1024 + lane * 16);
;         const int e2 = __builtin_amdgcn_readlane(idv, GROWS + k);
;         rr[1][k] = *(const u32x4*)(vb + (size_t)e2 * 1024 + lane * 16);
;       }
;     ...
;           for (int m = 0; m < 4; ++m) {
;             unsigned lo[4], hi[4];
; #pragma unroll
;             for (int k = 0; k < 4; ++k) {
;               const unsigned w = rr[gi % 3][sub * 4 + k][m];
;               lo[k] = w & 0x0f0f0f0fu;
;               hi[k] = (w >> 4) & 0x0f0f0f0fu;
;             }
;             {
;               const unsigned p01l = __builtin_amdgcn_perm(lo[1], lo[0], 0x05010400u), p01h = __builtin_amdgcn_perm(lo[1], lo[0], 0x07030602u);
;               const unsigned p23l = __builtin_amdgcn_perm(lo[3], lo[2], 0x05010400u), p23h = __builtin_amdgcn_perm(lo[3], lo[2], 0x07030602u);
;               acc[m * 8 + 0] = __builtin_amdgcn_sdot4((int)__builtin_amdgcn_perm(p23l, p01l, 0x05040100u), W4, acc[m * 8 + 0], false);
	s_ashr_i32 s3, s2, 31
	s_ashr_i32 vcc_hi, vcc_lo, 31
	s_lshl_b64 s[26:27], s[2:3], 10
	v_readlane_b32 s2, v1, 6
	s_lshl_b64 vcc, vcc, 10
	s_ashr_i32 s3, s2, 31
	v_writelane_b32 v250, vcc_lo, 14
	s_lshl_b64 s[24:25], s[2:3], 10
	v_readlane_b32 s2, v1, 14
	v_writelane_b32 v250, vcc_hi, 15
	v_readlane_b32 vcc_lo, v1, 59
	s_ashr_i32 s3, s2, 31
	s_ashr_i32 vcc_hi, vcc_lo, 31
	s_lshl_b64 s[22:23], s[2:3], 10
	v_readlane_b32 s2, v1, 7
	s_lshl_b64 vcc, vcc, 10
	s_ashr_i32 s3, s2, 31
	v_writelane_b32 v250, vcc_lo, 10
	s_lshl_b64 s[20:21], s[2:3], 10
	v_readlane_b32 s2, v1, 15
	v_writelane_b32 v250, vcc_hi, 11
	v_readlane_b32 vcc_lo, v1, 60
	s_ashr_i32 s3, s2, 31
	s_ashr_i32 vcc_hi, vcc_lo, 31
	s_lshl_b64 s[18:19], s[2:3], 10
	v_readlane_b32 s2, v1, 16
	s_lshl_b64 vcc, vcc, 10
	s_ashr_i32 s3, s2, 31
	v_writelane_b32 v250, vcc_lo, 12
	s_lshl_b64 s[16:17], s[2:3], 10
	v_readlane_b32 s2, v1, 17
	v_writelane_b32 v250, vcc_hi, 13
	v_readlane_b32 vcc_lo, v1, 61
	s_ashr_i32 s3, s2, 31
	s_ashr_i32 vcc_hi, vcc_lo, 31
	s_lshl_b64 s[14:15], s[2:3], 10
	v_readlane_b32 s2, v1, 18
	s_lshl_b64 vcc, vcc, 10
	s_ashr_i32 s3, s2, 31
	v_writelane_b32 v250, vcc_lo, 2
	s_lshl_b64 s[12:13], s[2:3], 10
	v_readlane_b32 s2, v1, 19
	v_writelane_b32 v250, vcc_hi, 3
	v_readlane_b32 vcc_lo, v1, 62
	s_ashr_i32 s3, s2, 31
	s_ashr_i32 vcc_hi, vcc_lo, 31
	s_lshl_b64 s[10:11], s[2:3], 10
	v_readlane_b32 s2, v1, 20
	s_lshl_b64 vcc, vcc, 10
	s_ashr_i32 s3, s2, 31
	v_writelane_b32 v250, vcc_lo, 0
	s_lshl_b64 s[8:9], s[2:3], 10
	v_readlane_b32 s2, v1, 21
	v_writelane_b32 v250, vcc_hi, 1
	v_readlane_b32 vcc_lo, v1, 63
	s_ashr_i32 s3, s2, 31
	s_ashr_i32 vcc_hi, vcc_lo, 31
	s_lshl_b64 s[6:7], s[2:3], 10
	v_readlane_b32 s2, v1, 22
	s_lshl_b64 vcc, vcc, 10
	s_ashr_i32 s3, s2, 31
	v_writelane_b32 v250, vcc_lo, 16
	s_lshl_b64 s[4:5], s[2:3], 10
	v_readlane_b32 s2, v1, 23
	v_readlane_b32 s56, v1, 43
	v_readlane_b32 s58, v1, 44
	v_readlane_b32 s60, v1, 45
	v_readlane_b32 s62, v1, 46
	v_readlane_b32 s64, v1, 47
	v_writelane_b32 v250, vcc_hi, 17
	v_cmp_ne_u32_e32 vcc, 1, v0
	v_lshl_add_u64 v[0:1], v[116:117], 0, s[50:51]
	global_load_dwordx4 v[64:67], v[0:1], off
	v_lshl_add_u64 v[0:1], v[116:117], 0, s[48:49]
	global_load_dwordx4 v[80:83], v[0:1], off
	v_lshl_add_u64 v[0:1], v[116:117], 0, s[46:47]
	global_load_dwordx4 v[68:71], v[0:1], off
	v_lshl_add_u64 v[0:1], v[116:117], 0, s[44:45]
	global_load_dwordx4 v[84:87], v[0:1], off
	v_lshl_add_u64 v[0:1], v[116:117], 0, s[42:43]
	global_load_dwordx4 v[72:75], v[0:1], off
	v_lshl_add_u64 v[0:1], v[116:117], 0, s[40:41]
	global_load_dwordx4 v[88:91], v[0:1], off
	v_lshl_add_u64 v[0:1], v[116:117], 0, s[38:39]
	global_load_dwordx4 v[76:79], v[0:1], off
	v_lshl_add_u64 v[0:1], v[116:117], 0, s[36:37]
	global_load_dwordx4 v[92:95], v[0:1], off
	v_lshl_add_u64 v[0:1], v[116:117], 0, s[34:35]
	global_load_dwordx4 v[48:51], v[0:1], off
	v_lshl_add_u64 v[0:1], v[116:117], 0, s[30:31]
	global_load_dwordx4 v[32:35], v[0:1], off
	v_lshl_add_u64 v[0:1], v[116:117], 0, s[28:29]
	global_load_dwordx4 v[52:55], v[0:1], off
	v_lshl_add_u64 v[0:1], v[116:117], 0, s[26:27]
	global_load_dwordx4 v[36:39], v[0:1], off
	v_lshl_add_u64 v[0:1], v[116:117], 0, s[24:25]
	global_load_dwordx4 v[56:59], v[0:1], off
	v_lshl_add_u64 v[0:1], v[116:117], 0, s[22:23]
	global_load_dwordx4 v[40:43], v[0:1], off
	v_lshl_add_u64 v[0:1], v[116:117], 0, s[20:21]
	global_load_dwordx4 v[60:63], v[0:1], off
	v_cndmask_b32_e64 v170, v169, v168, s[0:1]
	v_lshl_add_u64 v[0:1], v[116:117], 0, s[18:19]
	v_readlane_b32 s0, v170, 0
	global_load_dwordx4 v[44:47], v[0:1], off
	s_ashr_i32 s63, s62, 31
	s_lshl_b64 s[62:63], s[62:63], 10
	s_ashr_i32 s65, s64, 31
	s_lshl_b64 s[64:65], s[64:65], 10
	s_ashr_i32 s3, s2, 31
	s_lshl_b64 s[2:3], s[2:3], 10
	s_ashr_i32 s57, s56, 31
	s_lshl_b64 s[56:57], s[56:57], 10
	s_ashr_i32 s59, s58, 31
	s_ashr_i32 s61, s60, 31
	s_lshl_b64 s[58:59], s[58:59], 10
	s_lshl_b64 s[60:61], s[60:61], 10
	s_and_b64 vcc, exec, vcc
	s_waitcnt vmcnt(15)
	v_and_b32_e32 v96, 0xf0f0f0f, v64
	v_lshrrev_b32_e32 v64, 4, v64
	v_and_b32_e32 v64, 0xf0f0f0f, v64
	s_waitcnt vmcnt(13)
	v_and_b32_e32 v97, 0xf0f0f0f, v68
	v_perm_b32 v100, v97, v96, s33
	v_perm_b32 v96, v97, v96, s52
	v_lshrrev_b32_e32 v68, 4, v68
	s_waitcnt vmcnt(11)
	v_and_b32_e32 v98, 0xf0f0f0f, v72
	v_lshrrev_b32_e32 v72, 4, v72
	v_and_b32_e32 v68, 0xf0f0f0f, v68
	v_and_b32_e32 v72, 0xf0f0f0f, v72
	s_waitcnt vmcnt(9)
; __device__ void phase_gather(const Params& p) {
;     ...
; #pragma unroll
;         for (int sub = 0; sub < GROWS / 4; ++sub) {
;           const int W4 = __builtin_amdgcn_readlane(pkv, j0 + 4 * sub);
; #pragma unroll
;           for (int m = 0; m < 4; ++m) {
;             unsigned lo[4], hi[4];
; #pragma unroll
;             for (int k = 0; k < 4; ++k) {
;               const unsigned w = rr[gi % 3][sub * 4 + k][m];
;               lo[k] = w & 0x0f0f0f0fu;
;               hi[k] = (w >> 4) & 0x0f0f0f0fu;
;             }
;             {
;               const unsigned p01l = __builtin_amdgcn_perm(lo[1], lo[0], 0x05010400u), p01h = __builtin_amdgcn_perm(lo[1], lo[0], 0x07030602u);
;               const unsigned p23l = __builtin_amdgcn_perm(lo[3], lo[2], 0x05010400u), p23h = __builtin_amdgcn_perm(lo[3], lo[2], 0x07030602u);
;               acc[m * 8 + 0] = __builtin_amdgcn_sdot4((int)__builtin_amdgcn_perm(p23l, p01l, 0x05040100u), W4, acc[m * 8 + 0], false);
;               acc[m * 8 + 1] = __builtin_amdgcn_sdot4((int)__builtin_amdgcn_perm(p23l, p01l, 0x07060302u), W4, acc[m * 8 + 1], false);
;               acc[m * 8 + 2] = __builtin_amdgcn_sdot4((int)__builtin_amdgcn_perm(p23h, p01h, 0x05040100u), W4, acc[m * 8 + 2], false);
;               acc[m * 8 + 3] = __builtin_amdgcn_sdot4((int)__builtin_amdgcn_perm(p23h, p01h, 0x07060302u), W4, acc[m * 8 + 3], false);
;             }
;             {
;               const unsigned p01l = __builtin_amdgcn_perm(hi[1], hi[0], 0x05010400u), p01h = __builtin_amdgcn_perm(hi[1], hi[0], 0x07030602u);
;               const unsigned p23l = __builtin_amdgcn_perm(hi[3], hi[2], 0x05010400u), p23h = __builtin_amdgcn_perm(hi[3], hi[2], 0x07030602u);
;               acc[m * 8 + 4] = __builtin_amdgcn_sdot4((int)__builtin_amdgcn_perm(p23l, p01l, 0x05040100u), W4, acc[m * 8 + 4], false);
;               acc[m * 8 + 5] = __builtin_amdgcn_sdot4((int)__builtin_amdgcn_perm(p23l, p01l, 0x07060302u), W4, acc[m * 8 + 5], false);
;               acc[m * 8 + 6] = __builtin_amdgcn_sdot4((int)__builtin_amdgcn_perm(p23h, p01h, 0x05040100u), W4, acc[m * 8 + 6], false);
;               acc[m * 8 + 7] = __builtin_amdgcn_sdot4((int)__builtin_amdgcn_perm(p23h, p01h, 0x07060302u), W4, acc[m * 8 + 7], false);
;             }
;           }
;         }
	v_and_b32_e32 v99, 0xf0f0f0f, v76
	v_perm_b32 v97, v99, v98, s33
	v_lshrrev_b32_e32 v76, 4, v76
	v_perm_b32 v98, v99, v98, s52
	v_perm_b32 v99, v97, v100, s53
	v_perm_b32 v97, v97, v100, s54
	v_and_b32_e32 v76, 0xf0f0f0f, v76
	v_dot4c_i32_i8_e32 v164, s0, v97
	v_perm_b32 v97, v98, v96, s53
	v_perm_b32 v96, v98, v96, s54
	v_dot4c_i32_i8_e32 v162, s0, v96
	v_perm_b32 v96, v68, v64, s33
	v_perm_b32 v64, v68, v64, s52
	v_perm_b32 v68, v76, v72, s33
	v_perm_b32 v72, v76, v72, s52
	v_perm_b32 v76, v68, v96, s53
	v_perm_b32 v68, v68, v96, s54
	v_dot4c_i32_i8_e32 v160, s0, v68
	v_perm_b32 v68, v72, v64, s53
	v_perm_b32 v64, v72, v64, s54
	v_dot4c_i32_i8_e32 v159, s0, v76
	v_dot4c_i32_i8_e32 v157, s0, v68
	v_dot4c_i32_i8_e32 v158, s0, v64
	v_and_b32_e32 v64, 0xf0f0f0f, v65
	v_and_b32_e32 v68, 0xf0f0f0f, v69
	v_and_b32_e32 v72, 0xf0f0f0f, v73
	v_and_b32_e32 v76, 0xf0f0f0f, v77
	v_perm_b32 v96, v68, v64, s33
	v_perm_b32 v64, v68, v64, s52
	v_perm_b32 v68, v76, v72, s33
	v_lshrrev_b32_e32 v65, 4, v65
	v_lshrrev_b32_e32 v69, 4, v69
	v_lshrrev_b32_e32 v73, 4, v73
	v_lshrrev_b32_e32 v77, 4, v77
	v_perm_b32 v72, v76, v72, s52
	v_perm_b32 v76, v68, v96, s53
	v_perm_b32 v68, v68, v96, s54
	v_and_b32_e32 v65, 0xf0f0f0f, v65
	v_and_b32_e32 v69, 0xf0f0f0f, v69
	v_and_b32_e32 v73, 0xf0f0f0f, v73
	v_and_b32_e32 v77, 0xf0f0f0f, v77
	v_dot4c_i32_i8_e32 v154, s0, v68
	v_perm_b32 v68, v72, v64, s53
	v_perm_b32 v64, v72, v64, s54
	v_dot4c_i32_i8_e32 v149, s0, v68
	v_dot4c_i32_i8_e32 v150, s0, v64
	v_perm_b32 v64, v69, v65, s33
	v_perm_b32 v68, v77, v73, s33
	v_perm_b32 v65, v69, v65, s52
	v_perm_b32 v69, v77, v73, s52
	v_perm_b32 v72, v68, v64, s53
	v_perm_b32 v64, v68, v64, s54
	v_dot4c_i32_i8_e32 v146, s0, v64
	v_perm_b32 v64, v69, v65, s53
	v_dot4c_i32_i8_e32 v155, s0, v64
	v_perm_b32 v64, v69, v65, s54
	v_dot4c_i32_i8_e32 v144, s0, v72
	v_dot4c_i32_i8_e32 v156, s0, v64
	v_and_b32_e32 v64, 0xf0f0f0f, v66
	v_lshrrev_b32_e32 v65, 4, v66
	v_and_b32_e32 v66, 0xf0f0f0f, v70
	v_and_b32_e32 v69, 0xf0f0f0f, v74
	v_and_b32_e32 v72, 0xf0f0f0f, v78
	v_lshrrev_b32_e32 v68, 4, v70
	v_lshrrev_b32_e32 v70, 4, v74
	v_perm_b32 v74, v66, v64, s33
	v_perm_b32 v64, v66, v64, s52
	v_perm_b32 v66, v72, v69, s33
	v_lshrrev_b32_e32 v73, 4, v78
	v_perm_b32 v69, v72, v69, s52
	v_perm_b32 v72, v66, v74, s53
	v_perm_b32 v66, v66, v74, s54
	v_and_b32_e32 v65, 0xf0f0f0f, v65
	v_and_b32_e32 v68, 0xf0f0f0f, v68
	v_and_b32_e32 v70, 0xf0f0f0f, v70
	v_and_b32_e32 v73, 0xf0f0f0f, v73
	v_dot4c_i32_i8_e32 v153, s0, v66
	v_perm_b32 v66, v69, v64, s53
	v_perm_b32 v64, v69, v64, s54
	v_dot4c_i32_i8_e32 v147, s0, v66
	v_dot4c_i32_i8_e32 v148, s0, v64
	v_perm_b32 v64, v68, v65, s33
	v_perm_b32 v66, v73, v70, s33
	v_perm_b32 v65, v68, v65, s52
	v_perm_b32 v68, v73, v70, s52
	v_perm_b32 v69, v66, v64, s53
	v_perm_b32 v64, v66, v64, s54
	v_dot4c_i32_i8_e32 v145, s0, v64
	v_perm_b32 v64, v68, v65, s53
	v_dot4c_i32_i8_e32 v141, s0, v64
	v_perm_b32 v64, v68, v65, s54
	v_dot4c_i32_i8_e32 v142, s0, v64
	v_and_b32_e32 v64, 0xf0f0f0f, v67
	v_and_b32_e32 v66, 0xf0f0f0f, v71
	v_and_b32_e32 v68, 0xf0f0f0f, v75
	v_and_b32_e32 v70, 0xf0f0f0f, v79
	v_dot4c_i32_i8_e32 v151, s0, v72
	v_perm_b32 v72, v66, v64, s33
	v_perm_b32 v64, v66, v64, s52
	v_perm_b32 v66, v70, v68, s33
	v_dot4c_i32_i8_e32 v143, s0, v69
	v_lshrrev_b32_e32 v65, 4, v67
	v_lshrrev_b32_e32 v67, 4, v71
	v_lshrrev_b32_e32 v69, 4, v75
	v_lshrrev_b32_e32 v71, 4, v79
	v_perm_b32 v68, v70, v68, s52
	v_perm_b32 v70, v66, v72, s53
	v_perm_b32 v66, v66, v72, s54
	v_and_b32_e32 v65, 0xf0f0f0f, v65
	v_and_b32_e32 v67, 0xf0f0f0f, v67
	v_and_b32_e32 v69, 0xf0f0f0f, v69
	v_and_b32_e32 v71, 0xf0f0f0f, v71
	v_dot4c_i32_i8_e32 v140, s0, v66
	v_perm_b32 v66, v68, v64, s53
	v_perm_b32 v64, v68, v64, s54
	v_dot4c_i32_i8_e32 v137, s0, v66
	v_dot4c_i32_i8_e32 v139, s0, v64
	v_perm_b32 v64, v67, v65, s33
	v_perm_b32 v66, v71, v69, s33
	v_perm_b32 v65, v67, v65, s52
	v_perm_b32 v67, v71, v69, s52
	v_perm_b32 v68, v66, v64, s53
	v_perm_b32 v64, v66, v64, s54
	v_dot4c_i32_i8_e32 v135, s0, v64
	v_perm_b32 v64, v67, v65, s53
	v_dot4c_i32_i8_e32 v123, s0, v64
	v_perm_b32 v64, v67, v65, s54
	v_dot4c_i32_i8_e32 v125, s0, v64
	s_waitcnt vmcnt(7)
	v_and_b32_e32 v64, 0xf0f0f0f, v48
	s_waitcnt vmcnt(5)
	v_and_b32_e32 v65, 0xf0f0f0f, v52
	s_waitcnt vmcnt(3)
	v_and_b32_e32 v66, 0xf0f0f0f, v56
	s_waitcnt vmcnt(1)
; __device__ void phase_gather(const Params& p) {
;     ...
; #pragma unroll
;         for (int sub = 0; sub < GROWS / 4; ++sub) {
;           const int W4 = __builtin_amdgcn_readlane(pkv, j0 + 4 * sub);
; #pragma unroll
;           for (int m = 0; m < 4; ++m) {
;             unsigned lo[4], hi[4];
; #pragma unroll
;             for (int k = 0; k < 4; ++k) {
;               const unsigned w = rr[gi % 3][sub * 4 + k][m];
;               lo[k] = w & 0x0f0f0f0fu;
;               hi[k] = (w >> 4) & 0x0f0f0f0fu;
;             }
;             {
;               const unsigned p01l = __builtin_amdgcn_perm(lo[1], lo[0], 0x05010400u), p01h = __builtin_amdgcn_perm(lo[1], lo[0], 0x07030602u);
;               const unsigned p23l = __builtin_amdgcn_perm(lo[3], lo[2], 0x05010400u), p23h = __builtin_amdgcn_perm(lo[3], lo[2], 0x07030602u);
;               acc[m * 8 + 0] = __builtin_amdgcn_sdot4((int)__builtin_amdgcn_perm(p23l, p01l, 0x05040100u), W4, acc[m * 8 + 0], false);
;               acc[m * 8 + 1] = __builtin_amdgcn_sdot4((int)__builtin_amdgcn_perm(p23l, p01l, 0x07060302u), W4, acc[m * 8 + 1], false);
;               acc[m * 8 + 2] = __builtin_amdgcn_sdot4((int)__builtin_amdgcn_perm(p23h, p01h, 0x05040100u), W4, acc[m * 8 + 2], false);
;               acc[m * 8 + 3] = __builtin_amdgcn_sdot4((int)__builtin_amdgcn_perm(p23h, p01h, 0x07060302u), W4, acc[m * 8 + 3], false);
;             }
;             {
;               const unsigned p01l = __builtin_amdgcn_perm(hi[1], hi[0], 0x05010400u), p01h = __builtin_amdgcn_perm(hi[1], hi[0], 0x07030602u);
;               const unsigned p23l = __builtin_amdgcn_perm(hi[3], hi[2], 0x05010400u), p23h = __builtin_amdgcn_perm(hi[3], hi[2], 0x07030602u);
;               acc[m * 8 + 4] = __builtin_amdgcn_sdot4((int)__builtin_amdgcn_perm(p23l, p01l, 0x05040100u), W4, acc[m * 8 + 4], false);
;               acc[m * 8 + 5] = __builtin_amdgcn_sdot4((int)__builtin_amdgcn_perm(p23l, p01l, 0x07060302u), W4, acc[m * 8 + 5], false);
;               acc[m * 8 + 6] = __builtin_amdgcn_sdot4((int)__builtin_amdgcn_perm(p23h, p01h, 0x05040100u), W4, acc[m * 8 + 6], false);
;               acc[m * 8 + 7] = __builtin_amdgcn_sdot4((int)__builtin_amdgcn_perm(p23h, p01h, 0x07060302u), W4, acc[m * 8 + 7], false);
;             }
;           }
;         }
	v_and_b32_e32 v67, 0xf0f0f0f, v60
	v_dot4c_i32_i8_e32 v134, s0, v68
	v_perm_b32 v68, v65, v64, s33
	v_perm_b32 v64, v65, v64, s52
	v_perm_b32 v65, v67, v66, s33
	v_dot4c_i32_i8_e32 v163, s0, v99
	v_dot4c_i32_i8_e32 v161, s0, v97
	v_dot4c_i32_i8_e32 v152, s0, v76
	v_dot4c_i32_i8_e32 v136, s0, v70
	v_readlane_b32 s0, v170, 4
	v_lshrrev_b32_e32 v48, 4, v48
	v_lshrrev_b32_e32 v52, 4, v52
	v_lshrrev_b32_e32 v56, 4, v56
	v_lshrrev_b32_e32 v60, 4, v60
	v_perm_b32 v66, v67, v66, s52
	v_perm_b32 v67, v65, v68, s53
	v_perm_b32 v65, v65, v68, s54
	v_and_b32_e32 v48, 0xf0f0f0f, v48
	v_and_b32_e32 v52, 0xf0f0f0f, v52
	v_and_b32_e32 v56, 0xf0f0f0f, v56
	v_and_b32_e32 v60, 0xf0f0f0f, v60
	v_dot4c_i32_i8_e32 v164, s0, v65
	v_perm_b32 v65, v66, v64, s53
	v_perm_b32 v64, v66, v64, s54
	v_dot4c_i32_i8_e32 v162, s0, v64
	v_perm_b32 v64, v52, v48, s33
	v_perm_b32 v48, v52, v48, s52
	v_perm_b32 v52, v60, v56, s33
	v_perm_b32 v56, v60, v56, s52
	v_perm_b32 v60, v52, v64, s53
	v_perm_b32 v52, v52, v64, s54
	v_dot4c_i32_i8_e32 v160, s0, v52
	v_perm_b32 v52, v56, v48, s53
	v_perm_b32 v48, v56, v48, s54
	v_dot4c_i32_i8_e32 v159, s0, v60
	v_dot4c_i32_i8_e32 v157, s0, v52
	v_dot4c_i32_i8_e32 v158, s0, v48
	v_and_b32_e32 v48, 0xf0f0f0f, v49
	v_and_b32_e32 v52, 0xf0f0f0f, v53
	v_and_b32_e32 v56, 0xf0f0f0f, v57
	v_and_b32_e32 v60, 0xf0f0f0f, v61
	v_perm_b32 v64, v52, v48, s33
	v_perm_b32 v48, v52, v48, s52
	v_perm_b32 v52, v60, v56, s33
	v_lshrrev_b32_e32 v49, 4, v49
	v_lshrrev_b32_e32 v53, 4, v53
	v_lshrrev_b32_e32 v57, 4, v57
	v_lshrrev_b32_e32 v61, 4, v61
	v_perm_b32 v56, v60, v56, s52
	v_perm_b32 v60, v52, v64, s53
	v_perm_b32 v52, v52, v64, s54
	v_and_b32_e32 v49, 0xf0f0f0f, v49
	v_and_b32_e32 v53, 0xf0f0f0f, v53
	v_and_b32_e32 v57, 0xf0f0f0f, v57
	v_and_b32_e32 v61, 0xf0f0f0f, v61
	v_dot4c_i32_i8_e32 v154, s0, v52
	v_perm_b32 v52, v56, v48, s53
	v_perm_b32 v48, v56, v48, s54
	v_dot4c_i32_i8_e32 v149, s0, v52
	v_dot4c_i32_i8_e32 v150, s0, v48
	v_perm_b32 v48, v53, v49, s33
	v_perm_b32 v52, v61, v57, s33
	v_perm_b32 v49, v53, v49, s52
	v_perm_b32 v53, v61, v57, s52
	v_perm_b32 v56, v52, v48, s53
	v_perm_b32 v48, v52, v48, s54
	v_dot4c_i32_i8_e32 v146, s0, v48
	v_perm_b32 v48, v53, v49, s53
	v_dot4c_i32_i8_e32 v155, s0, v48
	v_perm_b32 v48, v53, v49, s54
	v_dot4c_i32_i8_e32 v144, s0, v56
	v_dot4c_i32_i8_e32 v156, s0, v48
	v_and_b32_e32 v48, 0xf0f0f0f, v50
	v_lshrrev_b32_e32 v49, 4, v50
	v_and_b32_e32 v50, 0xf0f0f0f, v54
	v_and_b32_e32 v53, 0xf0f0f0f, v58
	v_and_b32_e32 v56, 0xf0f0f0f, v62
	v_lshrrev_b32_e32 v52, 4, v54
	v_lshrrev_b32_e32 v54, 4, v58
	v_perm_b32 v58, v50, v48, s33
	v_perm_b32 v48, v50, v48, s52
	v_perm_b32 v50, v56, v53, s33
	v_lshrrev_b32_e32 v57, 4, v62
	v_perm_b32 v53, v56, v53, s52
	v_perm_b32 v56, v50, v58, s53
	v_perm_b32 v50, v50, v58, s54
	v_and_b32_e32 v49, 0xf0f0f0f, v49
	v_and_b32_e32 v52, 0xf0f0f0f, v52
	v_and_b32_e32 v54, 0xf0f0f0f, v54
	v_and_b32_e32 v57, 0xf0f0f0f, v57
	v_dot4c_i32_i8_e32 v153, s0, v50
	v_perm_b32 v50, v53, v48, s53
	v_perm_b32 v48, v53, v48, s54
	v_dot4c_i32_i8_e32 v147, s0, v50
	v_dot4c_i32_i8_e32 v148, s0, v48
	v_perm_b32 v48, v52, v49, s33
	v_perm_b32 v50, v57, v54, s33
	v_perm_b32 v49, v52, v49, s52
	v_perm_b32 v52, v57, v54, s52
	v_perm_b32 v53, v50, v48, s53
	v_perm_b32 v48, v50, v48, s54
	v_dot4c_i32_i8_e32 v145, s0, v48
	v_perm_b32 v48, v52, v49, s53
	v_dot4c_i32_i8_e32 v141, s0, v48
	v_perm_b32 v48, v52, v49, s54
	v_dot4c_i32_i8_e32 v142, s0, v48
	v_and_b32_e32 v48, 0xf0f0f0f, v51
	v_and_b32_e32 v50, 0xf0f0f0f, v55
	v_and_b32_e32 v52, 0xf0f0f0f, v59
	v_and_b32_e32 v54, 0xf0f0f0f, v63
	v_dot4c_i32_i8_e32 v151, s0, v56
	v_perm_b32 v56, v50, v48, s33
	v_perm_b32 v48, v50, v48, s52
	v_perm_b32 v50, v54, v52, s33
	v_dot4c_i32_i8_e32 v143, s0, v53
	v_lshrrev_b32_e32 v49, 4, v51
	v_lshrrev_b32_e32 v51, 4, v55
	v_lshrrev_b32_e32 v53, 4, v59
	v_lshrrev_b32_e32 v55, 4, v63
	v_perm_b32 v52, v54, v52, s52
	v_perm_b32 v54, v50, v56, s53
	v_perm_b32 v50, v50, v56, s54
	v_and_b32_e32 v49, 0xf0f0f0f, v49
	v_and_b32_e32 v51, 0xf0f0f0f, v51
	v_and_b32_e32 v53, 0xf0f0f0f, v53
	v_and_b32_e32 v55, 0xf0f0f0f, v55
	v_dot4c_i32_i8_e32 v140, s0, v50
	v_perm_b32 v50, v52, v48, s53
	v_perm_b32 v48, v52, v48, s54
	v_dot4c_i32_i8_e32 v137, s0, v50
	v_dot4c_i32_i8_e32 v139, s0, v48
	v_perm_b32 v48, v51, v49, s33
	v_perm_b32 v50, v55, v53, s33
	v_perm_b32 v49, v51, v49, s52
	v_perm_b32 v51, v55, v53, s52
	v_perm_b32 v52, v50, v48, s53
	v_perm_b32 v48, v50, v48, s54
	v_dot4c_i32_i8_e32 v135, s0, v48
	v_perm_b32 v48, v51, v49, s53
	v_and_b32_e32 v96, 0xf0f0f0f, v80
	v_and_b32_e32 v97, 0xf0f0f0f, v84
	v_and_b32_e32 v98, 0xf0f0f0f, v88
	v_and_b32_e32 v99, 0xf0f0f0f, v92
	v_dot4c_i32_i8_e32 v123, s0, v48
	v_perm_b32 v48, v51, v49, s54
	v_perm_b32 v100, v97, v96, s33
	v_perm_b32 v96, v97, v96, s52
	v_perm_b32 v97, v99, v98, s33
	v_dot4c_i32_i8_e32 v163, s0, v67
	v_dot4c_i32_i8_e32 v161, s0, v65
	v_dot4c_i32_i8_e32 v152, s0, v60
	v_dot4c_i32_i8_e32 v136, s0, v54
	v_dot4c_i32_i8_e32 v134, s0, v52
	v_dot4c_i32_i8_e32 v125, s0, v48
	v_readlane_b32 s0, v170, 8
	v_lshrrev_b32_e32 v80, 4, v80
	v_lshrrev_b32_e32 v84, 4, v84
	v_lshrrev_b32_e32 v88, 4, v88
	v_lshrrev_b32_e32 v92, 4, v92
	v_perm_b32 v98, v99, v98, s52
	v_perm_b32 v99, v97, v100, s53
	v_perm_b32 v97, v97, v100, s54
	v_and_b32_e32 v80, 0xf0f0f0f, v80
	v_and_b32_e32 v84, 0xf0f0f0f, v84
	v_and_b32_e32 v88, 0xf0f0f0f, v88
	v_and_b32_e32 v92, 0xf0f0f0f, v92
	v_dot4c_i32_i8_e32 v164, s0, v97
	v_perm_b32 v97, v98, v96, s53
	v_perm_b32 v96, v98, v96, s54
	v_dot4c_i32_i8_e32 v162, s0, v96
	v_perm_b32 v96, v84, v80, s33
	v_perm_b32 v80, v84, v80, s52
	v_perm_b32 v84, v92, v88, s33
; __device__ void phase_gather(const Params& p) {
;     ...
;       for (int gi = 0; gi < 64 / GROWS; ++gi) {
;         const int j0 = gi * GROWS;
;         if (gi + 2 < 64 / GROWS) {
; #pragma unroll
;           for (int k = 0; k < GROWS; ++k) {
;             const int e = __builtin_amdgcn_readlane(idv, j0 + 2 * GROWS + k);
;             rr[(gi + 2) % 3][k] = *(const u32x4*)(vb + (size_t)e * 1024 + lane * 16);
;           }
;         }
; #pragma unroll
;         for (int sub = 0; sub < GROWS / 4; ++sub) {
;           const int W4 = __builtin_amdgcn_readlane(pkv, j0 + 4 * sub);
; #pragma unroll
;           for (int m = 0; m < 4; ++m) {
;             unsigned lo[4], hi[4];
; #pragma unroll
;             for (int k = 0; k < 4; ++k) {
;               const unsigned w = rr[gi % 3][sub * 4 + k][m];
;               lo[k] = w & 0x0f0f0f0fu;
;               hi[k] = (w >> 4) & 0x0f0f0f0fu;
;             }
;             {
;               const unsigned p01l = __builtin_amdgcn_perm(lo[1], lo[0], 0x05010400u), p01h = __builtin_amdgcn_perm(lo[1], lo[0], 0x07030602u);
;               const unsigned p23l = __builtin_amdgcn_perm(lo[3], lo[2], 0x05010400u), p23h = __builtin_amdgcn_perm(lo[3], lo[2], 0x07030602u);
;               acc[m * 8 + 0] = __builtin_amdgcn_sdot4((int)__builtin_amdgcn_perm(p23l, p01l, 0x05040100u), W4, acc[m * 8 + 0], false);
;               acc[m * 8 + 1] = __builtin_amdgcn_sdot4((int)__builtin_amdgcn_perm(p23l, p01l, 0x07060302u), W4, acc[m * 8 + 1], false);
;               acc[m * 8 + 2] = __builtin_amdgcn_sdot4((int)__builtin_amdgcn_perm(p23h, p01h, 0x05040100u), W4, acc[m * 8 + 2], false);
;               acc[m * 8 + 3] = __builtin_amdgcn_sdot4((int)__builtin_amdgcn_perm(p23h, p01h, 0x07060302u), W4, acc[m * 8 + 3], false);
;             }
;             {
;               const unsigned p01l = __builtin_amdgcn_perm(hi[1], hi[0], 0x05010400u), p01h = __builtin_amdgcn_perm(hi[1], hi[0], 0x07030602u);
;               const unsigned p23l = __builtin_amdgcn_perm(hi[3], hi[2], 0x05010400u), p23h = __builtin_amdgcn_perm(hi[3], hi[2], 0x07030602u);
;               acc[m * 8 + 4] = __builtin_amdgcn_sdot4((int)__builtin_amdgcn_perm(p23l, p01l, 0x05040100u), W4, acc[m * 8 + 4], false);
;               acc[m * 8 + 5] = __builtin_amdgcn_sdot4((int)__builtin_amdgcn_perm(p23l, p01l, 0x07060302u), W4, acc[m * 8 + 5], false);
	v_perm_b32 v88, v92, v88, s52
	v_perm_b32 v92, v84, v96, s53
	v_perm_b32 v84, v84, v96, s54
	v_dot4c_i32_i8_e32 v160, s0, v84
	v_perm_b32 v84, v88, v80, s53
	v_perm_b32 v80, v88, v80, s54
	v_dot4c_i32_i8_e32 v159, s0, v92
	v_dot4c_i32_i8_e32 v157, s0, v84
	v_dot4c_i32_i8_e32 v158, s0, v80
	v_and_b32_e32 v80, 0xf0f0f0f, v81
	v_and_b32_e32 v84, 0xf0f0f0f, v85
	v_and_b32_e32 v88, 0xf0f0f0f, v89
	v_and_b32_e32 v92, 0xf0f0f0f, v93
	v_perm_b32 v96, v84, v80, s33
	v_perm_b32 v80, v84, v80, s52
	v_perm_b32 v84, v92, v88, s33
	v_lshrrev_b32_e32 v81, 4, v81
	v_lshrrev_b32_e32 v85, 4, v85
	v_lshrrev_b32_e32 v89, 4, v89
	v_lshrrev_b32_e32 v93, 4, v93
	v_perm_b32 v88, v92, v88, s52
	v_perm_b32 v92, v84, v96, s53
	v_perm_b32 v84, v84, v96, s54
	v_and_b32_e32 v81, 0xf0f0f0f, v81
	v_and_b32_e32 v85, 0xf0f0f0f, v85
	v_and_b32_e32 v89, 0xf0f0f0f, v89
	v_and_b32_e32 v93, 0xf0f0f0f, v93
	v_dot4c_i32_i8_e32 v154, s0, v84
	v_perm_b32 v84, v88, v80, s53
	v_perm_b32 v80, v88, v80, s54
	v_dot4c_i32_i8_e32 v149, s0, v84
	v_dot4c_i32_i8_e32 v150, s0, v80
	v_perm_b32 v80, v85, v81, s33
	v_perm_b32 v84, v93, v89, s33
	v_perm_b32 v81, v85, v81, s52
	v_perm_b32 v85, v93, v89, s52
	v_perm_b32 v88, v84, v80, s53
	v_perm_b32 v80, v84, v80, s54
	v_dot4c_i32_i8_e32 v146, s0, v80
	v_perm_b32 v80, v85, v81, s53
	v_dot4c_i32_i8_e32 v155, s0, v80
	v_perm_b32 v80, v85, v81, s54
	v_dot4c_i32_i8_e32 v144, s0, v88
	v_dot4c_i32_i8_e32 v156, s0, v80
	v_and_b32_e32 v80, 0xf0f0f0f, v82
	v_lshrrev_b32_e32 v81, 4, v82
	v_and_b32_e32 v82, 0xf0f0f0f, v86
	v_and_b32_e32 v85, 0xf0f0f0f, v90
	v_and_b32_e32 v88, 0xf0f0f0f, v94
	v_lshrrev_b32_e32 v84, 4, v86
	v_lshrrev_b32_e32 v86, 4, v90
	v_perm_b32 v90, v82, v80, s33
	v_perm_b32 v80, v82, v80, s52
	v_perm_b32 v82, v88, v85, s33
	v_lshrrev_b32_e32 v89, 4, v94
	v_perm_b32 v85, v88, v85, s52
	v_perm_b32 v88, v82, v90, s53
	v_perm_b32 v82, v82, v90, s54
	v_and_b32_e32 v81, 0xf0f0f0f, v81
	v_and_b32_e32 v84, 0xf0f0f0f, v84
	v_and_b32_e32 v86, 0xf0f0f0f, v86
	v_and_b32_e32 v89, 0xf0f0f0f, v89
	v_dot4c_i32_i8_e32 v153, s0, v82
	v_perm_b32 v82, v85, v80, s53
	v_perm_b32 v80, v85, v80, s54
	v_dot4c_i32_i8_e32 v147, s0, v82
	v_dot4c_i32_i8_e32 v148, s0, v80
	v_perm_b32 v80, v84, v81, s33
	v_perm_b32 v82, v89, v86, s33
	v_perm_b32 v81, v84, v81, s52
	v_perm_b32 v84, v89, v86, s52
	v_perm_b32 v85, v82, v80, s53
	v_perm_b32 v80, v82, v80, s54
	v_dot4c_i32_i8_e32 v145, s0, v80
	v_perm_b32 v80, v84, v81, s53
	v_dot4c_i32_i8_e32 v141, s0, v80
	v_perm_b32 v80, v84, v81, s54
	v_dot4c_i32_i8_e32 v142, s0, v80
	v_and_b32_e32 v80, 0xf0f0f0f, v83
	v_and_b32_e32 v82, 0xf0f0f0f, v87
	v_and_b32_e32 v84, 0xf0f0f0f, v91
	v_and_b32_e32 v86, 0xf0f0f0f, v95
	v_dot4c_i32_i8_e32 v151, s0, v88
	v_perm_b32 v88, v82, v80, s33
	v_perm_b32 v80, v82, v80, s52
	v_perm_b32 v82, v86, v84, s33
	v_dot4c_i32_i8_e32 v143, s0, v85
	v_lshrrev_b32_e32 v81, 4, v83
	v_lshrrev_b32_e32 v83, 4, v87
	v_lshrrev_b32_e32 v85, 4, v91
	v_lshrrev_b32_e32 v87, 4, v95
	v_perm_b32 v84, v86, v84, s52
	v_perm_b32 v86, v82, v88, s53
	v_perm_b32 v82, v82, v88, s54
	v_and_b32_e32 v81, 0xf0f0f0f, v81
	v_and_b32_e32 v83, 0xf0f0f0f, v83
	v_and_b32_e32 v85, 0xf0f0f0f, v85
	v_and_b32_e32 v87, 0xf0f0f0f, v87
	v_dot4c_i32_i8_e32 v140, s0, v82
	v_perm_b32 v82, v84, v80, s53
	v_perm_b32 v80, v84, v80, s54
	v_dot4c_i32_i8_e32 v137, s0, v82
	v_dot4c_i32_i8_e32 v139, s0, v80
	v_perm_b32 v80, v83, v81, s33
	v_perm_b32 v82, v87, v85, s33
	v_perm_b32 v81, v83, v81, s52
	v_perm_b32 v83, v87, v85, s52
	v_perm_b32 v84, v82, v80, s53
	v_perm_b32 v80, v82, v80, s54
	v_dot4c_i32_i8_e32 v135, s0, v80
	v_perm_b32 v80, v83, v81, s53
	v_lshl_add_u64 v[48:49], v[116:117], 0, s[84:85]
	v_dot4c_i32_i8_e32 v123, s0, v80
	v_perm_b32 v80, v83, v81, s54
	global_load_dwordx4 v[72:75], v[48:49], off
	v_dot4c_i32_i8_e32 v125, s0, v80
	v_and_b32_e32 v80, 0xf0f0f0f, v32
	v_and_b32_e32 v81, 0xf0f0f0f, v36
	v_and_b32_e32 v82, 0xf0f0f0f, v40
	s_waitcnt vmcnt(1)
	v_and_b32_e32 v83, 0xf0f0f0f, v44
	v_dot4c_i32_i8_e32 v134, s0, v84
	v_perm_b32 v84, v81, v80, s33
	v_perm_b32 v80, v81, v80, s52
	v_perm_b32 v81, v83, v82, s33
	v_dot4c_i32_i8_e32 v163, s0, v99
	v_dot4c_i32_i8_e32 v161, s0, v97
	v_dot4c_i32_i8_e32 v152, s0, v92
	v_dot4c_i32_i8_e32 v136, s0, v86
	v_readlane_b32 s0, v170, 12
	v_lshrrev_b32_e32 v32, 4, v32
	v_lshrrev_b32_e32 v36, 4, v36
	v_lshrrev_b32_e32 v40, 4, v40
	v_lshrrev_b32_e32 v44, 4, v44
	v_perm_b32 v82, v83, v82, s52
	v_perm_b32 v83, v81, v84, s53
	v_perm_b32 v81, v81, v84, s54
	v_and_b32_e32 v32, 0xf0f0f0f, v32
	v_and_b32_e32 v36, 0xf0f0f0f, v36
	v_and_b32_e32 v40, 0xf0f0f0f, v40
	v_and_b32_e32 v44, 0xf0f0f0f, v44
	v_dot4c_i32_i8_e32 v164, s0, v81
	v_perm_b32 v81, v82, v80, s53
	v_perm_b32 v80, v82, v80, s54
	v_dot4c_i32_i8_e32 v162, s0, v80
	v_perm_b32 v80, v36, v32, s33
	v_perm_b32 v32, v36, v32, s52
	v_perm_b32 v36, v44, v40, s33
	v_perm_b32 v40, v44, v40, s52
	v_perm_b32 v44, v36, v80, s53
	v_perm_b32 v36, v36, v80, s54
	v_dot4c_i32_i8_e32 v160, s0, v36
	v_perm_b32 v36, v40, v32, s53
	v_perm_b32 v32, v40, v32, s54
	v_dot4c_i32_i8_e32 v159, s0, v44
	v_dot4c_i32_i8_e32 v157, s0, v36
	v_dot4c_i32_i8_e32 v158, s0, v32
	v_and_b32_e32 v32, 0xf0f0f0f, v33
	v_and_b32_e32 v36, 0xf0f0f0f, v37
	v_and_b32_e32 v40, 0xf0f0f0f, v41
	v_and_b32_e32 v44, 0xf0f0f0f, v45
	v_perm_b32 v80, v36, v32, s33
	v_perm_b32 v32, v36, v32, s52
	v_perm_b32 v36, v44, v40, s33
	v_lshrrev_b32_e32 v33, 4, v33
	v_lshrrev_b32_e32 v37, 4, v37
	v_lshrrev_b32_e32 v41, 4, v41
	v_lshrrev_b32_e32 v45, 4, v45
	v_perm_b32 v40, v44, v40, s52
	v_perm_b32 v44, v36, v80, s53
	v_perm_b32 v36, v36, v80, s54
	v_and_b32_e32 v33, 0xf0f0f0f, v33
	v_and_b32_e32 v37, 0xf0f0f0f, v37
; __device__ void phase_gather(const Params& p) {
;     ...
;       for (int gi = 0; gi < 64 / GROWS; ++gi) {
;         const int j0 = gi * GROWS;
;         if (gi + 2 < 64 / GROWS) {
; #pragma unroll
;           for (int k = 0; k < GROWS; ++k) {
;             const int e = __builtin_amdgcn_readlane(idv, j0 + 2 * GROWS + k);
;             rr[(gi + 2) % 3][k] = *(const u32x4*)(vb + (size_t)e * 1024 + lane * 16);
;           }
;         }
; #pragma unroll
;         for (int sub = 0; sub < GROWS / 4; ++sub) {
;           const int W4 = __builtin_amdgcn_readlane(pkv, j0 + 4 * sub);
; #pragma unroll
;           for (int m = 0; m < 4; ++m) {
;             unsigned lo[4], hi[4];
; #pragma unroll
;             for (int k = 0; k < 4; ++k) {
;               const unsigned w = rr[gi % 3][sub * 4 + k][m];
;               lo[k] = w & 0x0f0f0f0fu;
;               hi[k] = (w >> 4) & 0x0f0f0f0fu;
;             }
;             {
;               const unsigned p01l = __builtin_amdgcn_perm(lo[1], lo[0], 0x05010400u), p01h = __builtin_amdgcn_perm(lo[1], lo[0], 0x07030602u);
;               const unsigned p23l = __builtin_amdgcn_perm(lo[3], lo[2], 0x05010400u), p23h = __builtin_amdgcn_perm(lo[3], lo[2], 0x07030602u);
;               acc[m * 8 + 0] = __builtin_amdgcn_sdot4((int)__builtin_amdgcn_perm(p23l, p01l, 0x05040100u), W4, acc[m * 8 + 0], false);
;               acc[m * 8 + 1] = __builtin_amdgcn_sdot4((int)__builtin_amdgcn_perm(p23l, p01l, 0x07060302u), W4, acc[m * 8 + 1], false);
;               acc[m * 8 + 2] = __builtin_amdgcn_sdot4((int)__builtin_amdgcn_perm(p23h, p01h, 0x05040100u), W4, acc[m * 8 + 2], false);
;               acc[m * 8 + 3] = __builtin_amdgcn_sdot4((int)__builtin_amdgcn_perm(p23h, p01h, 0x07060302u), W4, acc[m * 8 + 3], false);
;             }
;             {
;               const unsigned p01l = __builtin_amdgcn_perm(hi[1], hi[0], 0x05010400u), p01h = __builtin_amdgcn_perm(hi[1], hi[0], 0x07030602u);
;               const unsigned p23l = __builtin_amdgcn_perm(hi[3], hi[2], 0x05010400u), p23h = __builtin_amdgcn_perm(hi[3], hi[2], 0x07030602u);
;               acc[m * 8 + 4] = __builtin_amdgcn_sdot4((int)__builtin_amdgcn_perm(p23l, p01l, 0x05040100u), W4, acc[m * 8 + 4], false);
;               acc[m * 8 + 5] = __builtin_amdgcn_sdot4((int)__builtin_amdgcn_perm(p23l, p01l, 0x07060302u), W4, acc[m * 8 + 5], false);
	v_and_b32_e32 v41, 0xf0f0f0f, v41
	v_and_b32_e32 v45, 0xf0f0f0f, v45
	v_dot4c_i32_i8_e32 v154, s0, v36
	v_perm_b32 v36, v40, v32, s53
	v_perm_b32 v32, v40, v32, s54
	v_dot4c_i32_i8_e32 v149, s0, v36
	v_dot4c_i32_i8_e32 v150, s0, v32
	v_perm_b32 v32, v37, v33, s33
	v_perm_b32 v36, v45, v41, s33
	v_perm_b32 v33, v37, v33, s52
	v_perm_b32 v37, v45, v41, s52
	v_perm_b32 v40, v36, v32, s53
	v_perm_b32 v32, v36, v32, s54
	v_dot4c_i32_i8_e32 v146, s0, v32
	v_perm_b32 v32, v37, v33, s53
	v_dot4c_i32_i8_e32 v155, s0, v32
	v_perm_b32 v32, v37, v33, s54
	v_dot4c_i32_i8_e32 v144, s0, v40
	v_dot4c_i32_i8_e32 v156, s0, v32
	v_and_b32_e32 v32, 0xf0f0f0f, v34
	v_lshrrev_b32_e32 v33, 4, v34
	v_and_b32_e32 v34, 0xf0f0f0f, v38
	v_and_b32_e32 v37, 0xf0f0f0f, v42
	v_and_b32_e32 v40, 0xf0f0f0f, v46
	v_lshrrev_b32_e32 v36, 4, v38
	v_lshrrev_b32_e32 v38, 4, v42
	v_perm_b32 v42, v34, v32, s33
	v_perm_b32 v32, v34, v32, s52
	v_perm_b32 v34, v40, v37, s33
	v_lshrrev_b32_e32 v41, 4, v46
	v_perm_b32 v37, v40, v37, s52
	v_perm_b32 v40, v34, v42, s53
	v_perm_b32 v34, v34, v42, s54
	v_and_b32_e32 v33, 0xf0f0f0f, v33
	v_and_b32_e32 v36, 0xf0f0f0f, v36
	v_and_b32_e32 v38, 0xf0f0f0f, v38
	v_and_b32_e32 v41, 0xf0f0f0f, v41
	v_dot4c_i32_i8_e32 v153, s0, v34
	v_perm_b32 v34, v37, v32, s53
	v_perm_b32 v32, v37, v32, s54
	v_dot4c_i32_i8_e32 v147, s0, v34
	v_dot4c_i32_i8_e32 v148, s0, v32
	v_perm_b32 v32, v36, v33, s33
	v_perm_b32 v34, v41, v38, s33
	v_perm_b32 v33, v36, v33, s52
	v_perm_b32 v36, v41, v38, s52
	v_perm_b32 v37, v34, v32, s53
	v_perm_b32 v32, v34, v32, s54
	v_dot4c_i32_i8_e32 v145, s0, v32
	v_perm_b32 v32, v36, v33, s53
	v_dot4c_i32_i8_e32 v141, s0, v32
	v_perm_b32 v32, v36, v33, s54
	v_dot4c_i32_i8_e32 v142, s0, v32
	v_and_b32_e32 v32, 0xf0f0f0f, v35
	v_and_b32_e32 v34, 0xf0f0f0f, v39
	v_and_b32_e32 v36, 0xf0f0f0f, v43
	v_and_b32_e32 v38, 0xf0f0f0f, v47
	v_dot4c_i32_i8_e32 v151, s0, v40
	v_perm_b32 v40, v34, v32, s33
	v_perm_b32 v32, v34, v32, s52
	v_perm_b32 v34, v38, v36, s33
	v_dot4c_i32_i8_e32 v143, s0, v37
	v_lshrrev_b32_e32 v33, 4, v35
	v_lshrrev_b32_e32 v35, 4, v39
	v_lshrrev_b32_e32 v37, 4, v43
	v_lshrrev_b32_e32 v39, 4, v47
	v_perm_b32 v36, v38, v36, s52
	v_perm_b32 v38, v34, v40, s53
	v_perm_b32 v34, v34, v40, s54
	v_and_b32_e32 v33, 0xf0f0f0f, v33
	v_and_b32_e32 v35, 0xf0f0f0f, v35
	v_and_b32_e32 v37, 0xf0f0f0f, v37
	v_and_b32_e32 v39, 0xf0f0f0f, v39
	v_dot4c_i32_i8_e32 v140, s0, v34
	v_perm_b32 v34, v36, v32, s53
	v_perm_b32 v32, v36, v32, s54
	v_dot4c_i32_i8_e32 v137, s0, v34
	v_dot4c_i32_i8_e32 v139, s0, v32
	v_perm_b32 v32, v35, v33, s33
	v_perm_b32 v34, v39, v37, s33
	v_perm_b32 v33, v35, v33, s52
	v_perm_b32 v35, v39, v37, s52
	v_perm_b32 v36, v34, v32, s53
	v_perm_b32 v32, v34, v32, s54
	v_dot4c_i32_i8_e32 v135, s0, v32
	v_perm_b32 v32, v35, v33, s53
	v_dot4c_i32_i8_e32 v123, s0, v32
	v_perm_b32 v32, v35, v33, s54
	v_lshl_add_u64 v[0:1], v[116:117], 0, s[16:17]
	v_dot4c_i32_i8_e32 v125, s0, v32
	v_lshl_add_u64 v[32:33], v[116:117], 0, s[66:67]
	global_load_dwordx4 v[28:31], v[0:1], off
	global_load_dwordx4 v[108:111], v[32:33], off
	v_lshl_add_u64 v[0:1], v[116:117], 0, s[14:15]
	v_lshl_add_u64 v[32:33], v[116:117], 0, s[68:69]
	global_load_dwordx4 v[24:27], v[0:1], off
	global_load_dwordx4 v[104:107], v[32:33], off
	v_lshl_add_u64 v[0:1], v[116:117], 0, s[12:13]
	v_lshl_add_u64 v[32:33], v[116:117], 0, s[70:71]
	global_load_dwordx4 v[20:23], v[0:1], off
	global_load_dwordx4 v[100:103], v[32:33], off
	v_lshl_add_u64 v[0:1], v[116:117], 0, s[10:11]
	global_load_dwordx4 v[16:19], v[0:1], off
	v_lshl_add_u64 v[32:33], v[116:117], 0, s[72:73]
	v_dot4c_i32_i8_e32 v163, s0, v83
	v_dot4c_i32_i8_e32 v161, s0, v81
	global_load_dwordx4 v[96:99], v[32:33], off
	v_dot4c_i32_i8_e32 v152, s0, v44
	v_dot4c_i32_i8_e32 v136, s0, v38
	v_dot4c_i32_i8_e32 v134, s0, v36
	v_readlane_b32 s0, v170, 16
	v_lshl_add_u64 v[0:1], v[116:117], 0, s[8:9]
	global_load_dwordx4 v[12:15], v[0:1], off
	v_lshl_add_u64 v[32:33], v[116:117], 0, s[74:75]
	global_load_dwordx4 v[44:47], v[32:33], off
	v_lshl_add_u64 v[32:33], v[116:117], 0, s[76:77]
	v_lshl_add_u64 v[48:49], v[116:117], 0, s[82:83]
	global_load_dwordx4 v[40:43], v[32:33], off
	v_lshl_add_u64 v[32:33], v[116:117], 0, s[78:79]
	global_load_dwordx4 v[76:79], v[48:49], off
	global_load_dwordx4 v[36:39], v[32:33], off
	v_lshl_add_u64 v[48:49], v[116:117], 0, s[86:87]
	v_lshl_add_u64 v[32:33], v[116:117], 0, s[80:81]
	global_load_dwordx4 v[68:71], v[48:49], off
	s_waitcnt vmcnt(13)
	v_and_b32_e32 v80, 0xf0f0f0f, v28
	v_lshrrev_b32_e32 v28, 4, v28
	v_and_b32_e32 v28, 0xf0f0f0f, v28
	global_load_dwordx4 v[32:35], v[32:33], off
	s_waitcnt vmcnt(12)
	v_and_b32_e32 v81, 0xf0f0f0f, v24
	v_perm_b32 v84, v81, v80, s33
	v_perm_b32 v80, v81, v80, s52
	v_lshrrev_b32_e32 v24, 4, v24
	s_waitcnt vmcnt(10)
	v_and_b32_e32 v82, 0xf0f0f0f, v20
	v_lshrrev_b32_e32 v20, 4, v20
	v_and_b32_e32 v24, 0xf0f0f0f, v24
	s_waitcnt vmcnt(8)
; __device__ void phase_gather(const Params& p) {
;     ...
;       for (int gi = 0; gi < 64 / GROWS; ++gi) {
;         const int j0 = gi * GROWS;
;         if (gi + 2 < 64 / GROWS) {
; #pragma unroll
;           for (int k = 0; k < GROWS; ++k) {
;             const int e = __builtin_amdgcn_readlane(idv, j0 + 2 * GROWS + k);
;             rr[(gi + 2) % 3][k] = *(const u32x4*)(vb + (size_t)e * 1024 + lane * 16);
;           }
;         }
; #pragma unroll
;         for (int sub = 0; sub < GROWS / 4; ++sub) {
;           const int W4 = __builtin_amdgcn_readlane(pkv, j0 + 4 * sub);
; #pragma unroll
;           for (int m = 0; m < 4; ++m) {
;             unsigned lo[4], hi[4];
; #pragma unroll
;             for (int k = 0; k < 4; ++k) {
;               const unsigned w = rr[gi % 3][sub * 4 + k][m];
;               lo[k] = w & 0x0f0f0f0fu;
;               hi[k] = (w >> 4) & 0x0f0f0f0fu;
;             }
;             {
;               const unsigned p01l = __builtin_amdgcn_perm(lo[1], lo[0], 0x05010400u), p01h = __builtin_amdgcn_perm(lo[1], lo[0], 0x07030602u);
;               const unsigned p23l = __builtin_amdgcn_perm(lo[3], lo[2], 0x05010400u), p23h = __builtin_amdgcn_perm(lo[3], lo[2], 0x07030602u);
;               acc[m * 8 + 0] = __builtin_amdgcn_sdot4((int)__builtin_amdgcn_perm(p23l, p01l, 0x05040100u), W4, acc[m * 8 + 0], false);
;               acc[m * 8 + 1] = __builtin_amdgcn_sdot4((int)__builtin_amdgcn_perm(p23l, p01l, 0x07060302u), W4, acc[m * 8 + 1], false);
;               acc[m * 8 + 2] = __builtin_amdgcn_sdot4((int)__builtin_amdgcn_perm(p23h, p01h, 0x05040100u), W4, acc[m * 8 + 2], false);
;               acc[m * 8 + 3] = __builtin_amdgcn_sdot4((int)__builtin_amdgcn_perm(p23h, p01h, 0x07060302u), W4, acc[m * 8 + 3], false);
;             }
;             {
;               const unsigned p01l = __builtin_amdgcn_perm(hi[1], hi[0], 0x05010400u), p01h = __builtin_amdgcn_perm(hi[1], hi[0], 0x07030602u);
;               const unsigned p23l = __builtin_amdgcn_perm(hi[3], hi[2], 0x05010400u), p23h = __builtin_amdgcn_perm(hi[3], hi[2], 0x07030602u);
;               acc[m * 8 + 4] = __builtin_amdgcn_sdot4((int)__builtin_amdgcn_perm(p23l, p01l, 0x05040100u), W4, acc[m * 8 + 4], false);
;               acc[m * 8 + 5] = __builtin_amdgcn_sdot4((int)__builtin_amdgcn_perm(p23l, p01l, 0x07060302u), W4, acc[m * 8 + 5], false);
	v_and_b32_e32 v83, 0xf0f0f0f, v16
	v_perm_b32 v81, v83, v82, s33
	v_lshrrev_b32_e32 v16, 4, v16
	v_perm_b32 v82, v83, v82, s52
	v_perm_b32 v83, v81, v84, s53
	v_perm_b32 v81, v81, v84, s54
	v_and_b32_e32 v20, 0xf0f0f0f, v20
	v_and_b32_e32 v16, 0xf0f0f0f, v16
	v_dot4c_i32_i8_e32 v164, s0, v81
	v_perm_b32 v81, v82, v80, s53
	v_perm_b32 v80, v82, v80, s54
	v_dot4c_i32_i8_e32 v162, s0, v80
	v_perm_b32 v80, v24, v28, s33
	v_perm_b32 v24, v24, v28, s52
	v_perm_b32 v28, v16, v20, s33
	v_perm_b32 v16, v16, v20, s52
	v_perm_b32 v20, v28, v80, s53
	v_dot4c_i32_i8_e32 v159, s0, v20
	v_perm_b32 v20, v28, v80, s54
	v_dot4c_i32_i8_e32 v160, s0, v20
	v_perm_b32 v20, v16, v24, s53
	v_perm_b32 v16, v16, v24, s54
	v_dot4c_i32_i8_e32 v157, s0, v20
	v_dot4c_i32_i8_e32 v158, s0, v16
	v_and_b32_e32 v16, 0xf0f0f0f, v29
	v_lshrrev_b32_e32 v20, 4, v29
	v_and_b32_e32 v24, 0xf0f0f0f, v25
	v_and_b32_e32 v28, 0xf0f0f0f, v21
	v_and_b32_e32 v29, 0xf0f0f0f, v17
	v_perm_b32 v80, v24, v16, s33
	v_perm_b32 v16, v24, v16, s52
	v_perm_b32 v24, v29, v28, s33
	v_lshrrev_b32_e32 v25, 4, v25
	v_lshrrev_b32_e32 v21, 4, v21
	v_lshrrev_b32_e32 v17, 4, v17
	v_perm_b32 v28, v29, v28, s52
	v_perm_b32 v29, v24, v80, s53
	v_perm_b32 v24, v24, v80, s54
	v_and_b32_e32 v20, 0xf0f0f0f, v20
	v_and_b32_e32 v25, 0xf0f0f0f, v25
	v_and_b32_e32 v21, 0xf0f0f0f, v21
	v_and_b32_e32 v17, 0xf0f0f0f, v17
	v_dot4c_i32_i8_e32 v154, s0, v24
	v_perm_b32 v24, v28, v16, s53
	v_perm_b32 v16, v28, v16, s54
	v_dot4c_i32_i8_e32 v149, s0, v24
	v_dot4c_i32_i8_e32 v150, s0, v16
	v_perm_b32 v16, v25, v20, s33
	v_perm_b32 v24, v17, v21, s33
	v_perm_b32 v20, v25, v20, s52
	v_perm_b32 v17, v17, v21, s52
	v_perm_b32 v21, v24, v16, s53
	v_perm_b32 v16, v24, v16, s54
	v_dot4c_i32_i8_e32 v146, s0, v16
	v_perm_b32 v16, v17, v20, s53
	v_dot4c_i32_i8_e32 v155, s0, v16
	v_perm_b32 v16, v17, v20, s54
	v_dot4c_i32_i8_e32 v156, s0, v16
	v_and_b32_e32 v16, 0xf0f0f0f, v30
	v_and_b32_e32 v20, 0xf0f0f0f, v26
	v_and_b32_e32 v24, 0xf0f0f0f, v22
	v_and_b32_e32 v25, 0xf0f0f0f, v18
	v_dot4c_i32_i8_e32 v144, s0, v21
	v_lshrrev_b32_e32 v21, 4, v26
	v_perm_b32 v26, v20, v16, s33
	v_perm_b32 v16, v20, v16, s52
	v_perm_b32 v20, v25, v24, s33
	v_lshrrev_b32_e32 v17, 4, v30
	v_lshrrev_b32_e32 v22, 4, v22
	v_lshrrev_b32_e32 v18, 4, v18
	v_perm_b32 v24, v25, v24, s52
	v_perm_b32 v25, v20, v26, s53
	v_perm_b32 v20, v20, v26, s54
	v_and_b32_e32 v17, 0xf0f0f0f, v17
	v_and_b32_e32 v21, 0xf0f0f0f, v21
	v_and_b32_e32 v22, 0xf0f0f0f, v22
	v_and_b32_e32 v18, 0xf0f0f0f, v18
	v_dot4c_i32_i8_e32 v153, s0, v20
	v_perm_b32 v20, v24, v16, s53
	v_perm_b32 v16, v24, v16, s54
	v_dot4c_i32_i8_e32 v147, s0, v20
	v_dot4c_i32_i8_e32 v148, s0, v16
	v_perm_b32 v16, v21, v17, s33
	v_perm_b32 v20, v18, v22, s33
	v_perm_b32 v17, v21, v17, s52
	v_perm_b32 v18, v18, v22, s52
	v_perm_b32 v21, v20, v16, s53
	v_perm_b32 v16, v20, v16, s54
	v_dot4c_i32_i8_e32 v145, s0, v16
	v_perm_b32 v16, v18, v17, s53
	v_dot4c_i32_i8_e32 v141, s0, v16
	v_perm_b32 v16, v18, v17, s54
	v_dot4c_i32_i8_e32 v143, s0, v21
	v_dot4c_i32_i8_e32 v142, s0, v16
	v_and_b32_e32 v16, 0xf0f0f0f, v31
	v_and_b32_e32 v18, 0xf0f0f0f, v27
	v_and_b32_e32 v21, 0xf0f0f0f, v23
	v_lshrrev_b32_e32 v22, 4, v23
	v_and_b32_e32 v23, 0xf0f0f0f, v19
	v_perm_b32 v24, v18, v16, s33
	v_perm_b32 v16, v18, v16, s52
	v_perm_b32 v18, v23, v21, s33
	v_dot4c_i32_i8_e32 v151, s0, v25
	v_perm_b32 v21, v23, v21, s52
	v_perm_b32 v23, v18, v24, s53
	v_perm_b32 v18, v18, v24, s54
	v_lshl_add_u64 v[24:25], v[116:117], 0, s[62:63]
	v_dot4c_i32_i8_e32 v152, s0, v29
	v_lshrrev_b32_e32 v20, 4, v27
	global_load_dwordx4 v[24:27], v[24:25], off
	v_lshl_add_u64 v[0:1], v[116:117], 0, s[6:7]
	v_lshl_add_u64 v[28:29], v[116:117], 0, s[64:65]
	global_load_dwordx4 v[8:11], v[0:1], off
	v_lshrrev_b32_e32 v17, 4, v31
	global_load_dwordx4 v[28:31], v[28:29], off
	v_lshl_add_u64 v[0:1], v[116:117], 0, s[4:5]
	global_load_dwordx4 v[4:7], v[0:1], off
	v_lshl_add_u64 v[0:1], v[116:117], 0, s[2:3]
	global_load_dwordx4 v[0:3], v[0:1], off
	v_lshl_add_u64 v[48:49], v[116:117], 0, s[88:89]
	global_load_dwordx4 v[64:67], v[48:49], off
	v_lshl_add_u64 v[48:49], v[116:117], 0, s[90:91]
	global_load_dwordx4 v[60:63], v[48:49], off
	v_lshl_add_u64 v[48:49], v[116:117], 0, s[92:93]
	global_load_dwordx4 v[56:59], v[48:49], off
	v_lshl_add_u64 v[48:49], v[116:117], 0, s[94:95]
	global_load_dwordx4 v[52:55], v[48:49], off
	v_lshl_add_u64 v[48:49], v[116:117], 0, s[96:97]
	global_load_dwordx4 v[48:51], v[48:49], off
	v_lshrrev_b32_e32 v19, 4, v19
	v_and_b32_e32 v17, 0xf0f0f0f, v17
	v_and_b32_e32 v20, 0xf0f0f0f, v20
	v_and_b32_e32 v22, 0xf0f0f0f, v22
	v_and_b32_e32 v19, 0xf0f0f0f, v19
	v_dot4c_i32_i8_e32 v140, s0, v18
	v_perm_b32 v18, v21, v16, s53
	v_perm_b32 v16, v21, v16, s54
	v_dot4c_i32_i8_e32 v137, s0, v18
	v_dot4c_i32_i8_e32 v139, s0, v16
	v_perm_b32 v16, v20, v17, s33
	v_perm_b32 v18, v19, v22, s33
	v_perm_b32 v17, v20, v17, s52
	v_perm_b32 v19, v19, v22, s52
	v_perm_b32 v20, v18, v16, s53
	v_perm_b32 v16, v18, v16, s54
	v_dot4c_i32_i8_e32 v135, s0, v16
	v_perm_b32 v16, v19, v17, s53
	v_dot4c_i32_i8_e32 v123, s0, v16
	v_perm_b32 v16, v19, v17, s54
	v_dot4c_i32_i8_e32 v125, s0, v16
	s_waitcnt vmcnt(16)
	v_and_b32_e32 v16, 0xf0f0f0f, v12
	v_dot4c_i32_i8_e32 v134, s0, v20
	v_dot4c_i32_i8_e32 v163, s0, v83
	v_dot4c_i32_i8_e32 v161, s0, v81
	v_dot4c_i32_i8_e32 v136, s0, v23
	v_readlane_b32 s0, v170, 20
	v_lshrrev_b32_e32 v12, 4, v12
	v_and_b32_e32 v12, 0xf0f0f0f, v12
	v_and_b32_e32 v80, 0xf0f0f0f, v72
	s_waitcnt vmcnt(13)
	v_and_b32_e32 v81, 0xf0f0f0f, v76
	s_waitcnt vmcnt(11)
; __device__ void phase_gather(const Params& p) {
;     ...
; #pragma unroll
;         for (int sub = 0; sub < GROWS / 4; ++sub) {
;           const int W4 = __builtin_amdgcn_readlane(pkv, j0 + 4 * sub);
; #pragma unroll
;           for (int m = 0; m < 4; ++m) {
;             unsigned lo[4], hi[4];
; #pragma unroll
;             for (int k = 0; k < 4; ++k) {
;               const unsigned w = rr[gi % 3][sub * 4 + k][m];
;               lo[k] = w & 0x0f0f0f0fu;
;               hi[k] = (w >> 4) & 0x0f0f0f0fu;
;             }
;             {
;               const unsigned p01l = __builtin_amdgcn_perm(lo[1], lo[0], 0x05010400u), p01h = __builtin_amdgcn_perm(lo[1], lo[0], 0x07030602u);
;               const unsigned p23l = __builtin_amdgcn_perm(lo[3], lo[2], 0x05010400u), p23h = __builtin_amdgcn_perm(lo[3], lo[2], 0x07030602u);
;               acc[m * 8 + 0] = __builtin_amdgcn_sdot4((int)__builtin_amdgcn_perm(p23l, p01l, 0x05040100u), W4, acc[m * 8 + 0], false);
;               acc[m * 8 + 1] = __builtin_amdgcn_sdot4((int)__builtin_amdgcn_perm(p23l, p01l, 0x07060302u), W4, acc[m * 8 + 1], false);
;               acc[m * 8 + 2] = __builtin_amdgcn_sdot4((int)__builtin_amdgcn_perm(p23h, p01h, 0x05040100u), W4, acc[m * 8 + 2], false);
;               acc[m * 8 + 3] = __builtin_amdgcn_sdot4((int)__builtin_amdgcn_perm(p23h, p01h, 0x07060302u), W4, acc[m * 8 + 3], false);
;             }
;             {
;               const unsigned p01l = __builtin_amdgcn_perm(hi[1], hi[0], 0x05010400u), p01h = __builtin_amdgcn_perm(hi[1], hi[0], 0x07030602u);
;               const unsigned p23l = __builtin_amdgcn_perm(hi[3], hi[2], 0x05010400u), p23h = __builtin_amdgcn_perm(hi[3], hi[2], 0x07030602u);
;               acc[m * 8 + 4] = __builtin_amdgcn_sdot4((int)__builtin_amdgcn_perm(p23l, p01l, 0x05040100u), W4, acc[m * 8 + 4], false);
;               acc[m * 8 + 5] = __builtin_amdgcn_sdot4((int)__builtin_amdgcn_perm(p23l, p01l, 0x07060302u), W4, acc[m * 8 + 5], false);
;               acc[m * 8 + 6] = __builtin_amdgcn_sdot4((int)__builtin_amdgcn_perm(p23h, p01h, 0x05040100u), W4, acc[m * 8 + 6], false);
;               acc[m * 8 + 7] = __builtin_amdgcn_sdot4((int)__builtin_amdgcn_perm(p23h, p01h, 0x07060302u), W4, acc[m * 8 + 7], false);
;             }
;           }
;         }
	v_and_b32_e32 v82, 0xf0f0f0f, v68
	v_perm_b32 v84, v81, v80, s33
	v_perm_b32 v80, v81, v80, s52
	v_lshrrev_b32_e32 v72, 4, v72
	v_lshrrev_b32_e32 v76, 4, v76
	v_lshrrev_b32_e32 v68, 4, v68
	v_and_b32_e32 v72, 0xf0f0f0f, v72
	v_and_b32_e32 v76, 0xf0f0f0f, v76
	v_and_b32_e32 v68, 0xf0f0f0f, v68
	v_readlane_b32 s2, v170, 48
	v_readlane_b32 s3, v170, 52
	s_waitcnt vmcnt(8)
	v_and_b32_e32 v17, 0xf0f0f0f, v8
	v_perm_b32 v20, v17, v16, s33
	v_perm_b32 v16, v17, v16, s52
	v_lshrrev_b32_e32 v8, 4, v8
	s_waitcnt vmcnt(6)
	v_and_b32_e32 v18, 0xf0f0f0f, v4
	v_lshrrev_b32_e32 v4, 4, v4
	s_waitcnt vmcnt(5)
	v_and_b32_e32 v19, 0xf0f0f0f, v0
	v_perm_b32 v17, v19, v18, s33
	v_lshrrev_b32_e32 v0, 4, v0
	v_perm_b32 v18, v19, v18, s52
	v_perm_b32 v19, v17, v20, s53
	v_perm_b32 v17, v17, v20, s54
	v_and_b32_e32 v8, 0xf0f0f0f, v8
	v_and_b32_e32 v4, 0xf0f0f0f, v4
	v_and_b32_e32 v0, 0xf0f0f0f, v0
	v_dot4c_i32_i8_e32 v164, s0, v17
	v_perm_b32 v17, v18, v16, s53
	v_perm_b32 v16, v18, v16, s54
	v_dot4c_i32_i8_e32 v162, s0, v16
	v_perm_b32 v16, v8, v12, s33
	v_perm_b32 v8, v8, v12, s52
	v_perm_b32 v12, v0, v4, s33
	v_perm_b32 v0, v0, v4, s52
	v_perm_b32 v4, v12, v16, s53
	v_dot4c_i32_i8_e32 v159, s0, v4
	v_perm_b32 v4, v12, v16, s54
	v_dot4c_i32_i8_e32 v160, s0, v4
	v_perm_b32 v4, v0, v8, s53
	v_perm_b32 v0, v0, v8, s54
	v_dot4c_i32_i8_e32 v157, s0, v4
	v_dot4c_i32_i8_e32 v158, s0, v0
	v_and_b32_e32 v0, 0xf0f0f0f, v13
	v_lshrrev_b32_e32 v4, 4, v13
	v_and_b32_e32 v8, 0xf0f0f0f, v9
	v_and_b32_e32 v12, 0xf0f0f0f, v5
	v_and_b32_e32 v13, 0xf0f0f0f, v1
	v_perm_b32 v16, v8, v0, s33
	v_perm_b32 v0, v8, v0, s52
	v_perm_b32 v8, v13, v12, s33
	v_lshrrev_b32_e32 v9, 4, v9
	v_lshrrev_b32_e32 v5, 4, v5
	v_lshrrev_b32_e32 v1, 4, v1
	v_perm_b32 v12, v13, v12, s52
	v_perm_b32 v13, v8, v16, s53
	v_perm_b32 v8, v8, v16, s54
	v_and_b32_e32 v4, 0xf0f0f0f, v4
	v_and_b32_e32 v9, 0xf0f0f0f, v9
	v_and_b32_e32 v5, 0xf0f0f0f, v5
	v_and_b32_e32 v1, 0xf0f0f0f, v1
	v_dot4c_i32_i8_e32 v154, s0, v8
	v_perm_b32 v8, v12, v0, s53
	v_perm_b32 v0, v12, v0, s54
	v_dot4c_i32_i8_e32 v149, s0, v8
	v_dot4c_i32_i8_e32 v150, s0, v0
	v_perm_b32 v0, v9, v4, s33
	v_perm_b32 v8, v1, v5, s33
	v_perm_b32 v4, v9, v4, s52
	v_perm_b32 v1, v1, v5, s52
	v_perm_b32 v5, v8, v0, s53
	v_perm_b32 v0, v8, v0, s54
	v_dot4c_i32_i8_e32 v146, s0, v0
	v_perm_b32 v0, v1, v4, s53
	v_dot4c_i32_i8_e32 v155, s0, v0
	v_perm_b32 v0, v1, v4, s54
	v_dot4c_i32_i8_e32 v156, s0, v0
	v_and_b32_e32 v0, 0xf0f0f0f, v14
	v_and_b32_e32 v4, 0xf0f0f0f, v10
	v_and_b32_e32 v8, 0xf0f0f0f, v6
	v_and_b32_e32 v9, 0xf0f0f0f, v2
	v_dot4c_i32_i8_e32 v144, s0, v5
	v_lshrrev_b32_e32 v5, 4, v10
	v_perm_b32 v10, v4, v0, s33
	v_perm_b32 v0, v4, v0, s52
	v_perm_b32 v4, v9, v8, s33
	v_lshrrev_b32_e32 v1, 4, v14
	v_lshrrev_b32_e32 v6, 4, v6
	v_lshrrev_b32_e32 v2, 4, v2
	v_perm_b32 v8, v9, v8, s52
	v_perm_b32 v9, v4, v10, s53
	v_perm_b32 v4, v4, v10, s54
	v_and_b32_e32 v1, 0xf0f0f0f, v1
	v_and_b32_e32 v5, 0xf0f0f0f, v5
	v_and_b32_e32 v6, 0xf0f0f0f, v6
	v_and_b32_e32 v2, 0xf0f0f0f, v2
	v_dot4c_i32_i8_e32 v153, s0, v4
	v_perm_b32 v4, v8, v0, s53
	v_perm_b32 v0, v8, v0, s54
	v_dot4c_i32_i8_e32 v147, s0, v4
	v_dot4c_i32_i8_e32 v148, s0, v0
	v_perm_b32 v0, v5, v1, s33
	v_perm_b32 v4, v2, v6, s33
	v_perm_b32 v1, v5, v1, s52
	v_perm_b32 v2, v2, v6, s52
	v_perm_b32 v5, v4, v0, s53
	v_perm_b32 v0, v4, v0, s54
	v_dot4c_i32_i8_e32 v145, s0, v0
	v_perm_b32 v0, v2, v1, s53
	v_dot4c_i32_i8_e32 v141, s0, v0
	v_perm_b32 v0, v2, v1, s54
	v_dot4c_i32_i8_e32 v143, s0, v5
	v_dot4c_i32_i8_e32 v142, s0, v0
	v_and_b32_e32 v0, 0xf0f0f0f, v15
	v_and_b32_e32 v2, 0xf0f0f0f, v11
	v_and_b32_e32 v5, 0xf0f0f0f, v7
	v_lshrrev_b32_e32 v6, 4, v7
	v_and_b32_e32 v7, 0xf0f0f0f, v3
	v_perm_b32 v8, v2, v0, s33
	v_perm_b32 v0, v2, v0, s52
	v_perm_b32 v2, v7, v5, s33
	v_lshrrev_b32_e32 v1, 4, v15
	v_lshrrev_b32_e32 v4, 4, v11
	v_lshrrev_b32_e32 v3, 4, v3
	v_perm_b32 v5, v7, v5, s52
	v_perm_b32 v7, v2, v8, s53
	v_perm_b32 v2, v2, v8, s54
	v_and_b32_e32 v1, 0xf0f0f0f, v1
	v_and_b32_e32 v4, 0xf0f0f0f, v4
	v_and_b32_e32 v6, 0xf0f0f0f, v6
	v_and_b32_e32 v3, 0xf0f0f0f, v3
	v_dot4c_i32_i8_e32 v140, s0, v2
	v_perm_b32 v2, v5, v0, s53
	v_perm_b32 v0, v5, v0, s54
	v_dot4c_i32_i8_e32 v137, s0, v2
	v_dot4c_i32_i8_e32 v139, s0, v0
	v_perm_b32 v0, v4, v1, s33
	v_perm_b32 v2, v3, v6, s33
	v_perm_b32 v1, v4, v1, s52
	v_perm_b32 v3, v3, v6, s52
	v_perm_b32 v4, v2, v0, s53
	v_perm_b32 v0, v2, v0, s54
	v_dot4c_i32_i8_e32 v135, s0, v0
	v_perm_b32 v0, v3, v1, s53
	v_dot4c_i32_i8_e32 v123, s0, v0
	v_perm_b32 v0, v3, v1, s54
	v_dot4c_i32_i8_e32 v163, s0, v19
	v_dot4c_i32_i8_e32 v161, s0, v17
	v_dot4c_i32_i8_e32 v152, s0, v13
	v_dot4c_i32_i8_e32 v151, s0, v9
	v_dot4c_i32_i8_e32 v136, s0, v7
	v_dot4c_i32_i8_e32 v134, s0, v4
	v_dot4c_i32_i8_e32 v125, s0, v0
	v_readlane_b32 s0, v250, 34
	v_readlane_b32 s1, v250, 35
	s_waitcnt vmcnt(4)
; __device__ void phase_gather(const Params& p) {
;     ...
;       for (int gi = 0; gi < 64 / GROWS; ++gi) {
;         const int j0 = gi * GROWS;
;         if (gi + 2 < 64 / GROWS) {
; #pragma unroll
;           for (int k = 0; k < GROWS; ++k) {
;             const int e = __builtin_amdgcn_readlane(idv, j0 + 2 * GROWS + k);
;             rr[(gi + 2) % 3][k] = *(const u32x4*)(vb + (size_t)e * 1024 + lane * 16);
;           }
;         }
; #pragma unroll
;         for (int sub = 0; sub < GROWS / 4; ++sub) {
;           const int W4 = __builtin_amdgcn_readlane(pkv, j0 + 4 * sub);
; #pragma unroll
;           for (int m = 0; m < 4; ++m) {
;             unsigned lo[4], hi[4];
; #pragma unroll
;             for (int k = 0; k < 4; ++k) {
;               const unsigned w = rr[gi % 3][sub * 4 + k][m];
;               lo[k] = w & 0x0f0f0f0fu;
;               hi[k] = (w >> 4) & 0x0f0f0f0fu;
;             }
;             {
;               const unsigned p01l = __builtin_amdgcn_perm(lo[1], lo[0], 0x05010400u), p01h = __builtin_amdgcn_perm(lo[1], lo[0], 0x07030602u);
;               const unsigned p23l = __builtin_amdgcn_perm(lo[3], lo[2], 0x05010400u), p23h = __builtin_amdgcn_perm(lo[3], lo[2], 0x07030602u);
;               acc[m * 8 + 0] = __builtin_amdgcn_sdot4((int)__builtin_amdgcn_perm(p23l, p01l, 0x05040100u), W4, acc[m * 8 + 0], false);
;               acc[m * 8 + 1] = __builtin_amdgcn_sdot4((int)__builtin_amdgcn_perm(p23l, p01l, 0x07060302u), W4, acc[m * 8 + 1], false);
;               acc[m * 8 + 2] = __builtin_amdgcn_sdot4((int)__builtin_amdgcn_perm(p23h, p01h, 0x05040100u), W4, acc[m * 8 + 2], false);
;               acc[m * 8 + 3] = __builtin_amdgcn_sdot4((int)__builtin_amdgcn_perm(p23h, p01h, 0x07060302u), W4, acc[m * 8 + 3], false);
;             }
;             {
;               const unsigned p01l = __builtin_amdgcn_perm(hi[1], hi[0], 0x05010400u), p01h = __builtin_amdgcn_perm(hi[1], hi[0], 0x07030602u);
;               const unsigned p23l = __builtin_amdgcn_perm(hi[3], hi[2], 0x05010400u), p23h = __builtin_amdgcn_perm(hi[3], hi[2], 0x07030602u);
;               acc[m * 8 + 4] = __builtin_amdgcn_sdot4((int)__builtin_amdgcn_perm(p23l, p01l, 0x05040100u), W4, acc[m * 8 + 4], false);
;               acc[m * 8 + 5] = __builtin_amdgcn_sdot4((int)__builtin_amdgcn_perm(p23l, p01l, 0x07060302u), W4, acc[m * 8 + 5], false);
	v_and_b32_e32 v83, 0xf0f0f0f, v64
	v_perm_b32 v81, v83, v82, s33
	v_lshl_add_u64 v[0:1], v[116:117], 0, s[0:1]
	v_readlane_b32 s0, v250, 36
	v_readlane_b32 s1, v250, 37
	v_lshrrev_b32_e32 v64, 4, v64
	v_perm_b32 v82, v83, v82, s52
	v_lshl_add_u64 v[4:5], v[116:117], 0, s[0:1]
	v_readlane_b32 s0, v250, 38
	v_readlane_b32 s1, v250, 39
	v_perm_b32 v83, v81, v84, s53
	v_perm_b32 v81, v81, v84, s54
	v_lshl_add_u64 v[8:9], v[116:117], 0, s[0:1]
	v_readlane_b32 s0, v170, 24
	v_and_b32_e32 v64, 0xf0f0f0f, v64
	v_lshl_add_u64 v[12:13], v[116:117], 0, s[56:57]
	v_dot4c_i32_i8_e32 v164, s0, v81
	v_perm_b32 v81, v82, v80, s53
	v_perm_b32 v80, v82, v80, s54
	v_dot4c_i32_i8_e32 v162, s0, v80
	v_perm_b32 v80, v76, v72, s33
	v_perm_b32 v72, v76, v72, s52
	v_perm_b32 v76, v64, v68, s33
	v_perm_b32 v64, v64, v68, s52
	v_perm_b32 v68, v76, v80, s53
	v_dot4c_i32_i8_e32 v159, s0, v68
	v_perm_b32 v68, v76, v80, s54
	v_dot4c_i32_i8_e32 v160, s0, v68
	v_perm_b32 v68, v64, v72, s53
	v_perm_b32 v64, v64, v72, s54
	v_dot4c_i32_i8_e32 v157, s0, v68
	v_dot4c_i32_i8_e32 v158, s0, v64
	v_and_b32_e32 v64, 0xf0f0f0f, v73
	v_lshrrev_b32_e32 v68, 4, v73
	v_and_b32_e32 v72, 0xf0f0f0f, v77
	v_lshrrev_b32_e32 v73, 4, v77
	v_and_b32_e32 v76, 0xf0f0f0f, v69
	v_and_b32_e32 v77, 0xf0f0f0f, v65
	v_perm_b32 v80, v72, v64, s33
	v_perm_b32 v64, v72, v64, s52
	v_perm_b32 v72, v77, v76, s33
	v_lshrrev_b32_e32 v69, 4, v69
	v_lshrrev_b32_e32 v65, 4, v65
	v_perm_b32 v76, v77, v76, s52
	v_perm_b32 v77, v72, v80, s53
	v_perm_b32 v72, v72, v80, s54
	v_and_b32_e32 v68, 0xf0f0f0f, v68
	v_and_b32_e32 v73, 0xf0f0f0f, v73
	v_and_b32_e32 v69, 0xf0f0f0f, v69
	v_and_b32_e32 v65, 0xf0f0f0f, v65
	v_dot4c_i32_i8_e32 v154, s0, v72
	v_perm_b32 v72, v76, v64, s53
	v_perm_b32 v64, v76, v64, s54
	v_dot4c_i32_i8_e32 v149, s0, v72
	v_dot4c_i32_i8_e32 v150, s0, v64
	v_perm_b32 v64, v73, v68, s33
	v_perm_b32 v72, v65, v69, s33
	v_perm_b32 v68, v73, v68, s52
	v_perm_b32 v65, v65, v69, s52
	v_perm_b32 v69, v72, v64, s53
	v_perm_b32 v64, v72, v64, s54
	v_dot4c_i32_i8_e32 v146, s0, v64
	v_perm_b32 v64, v65, v68, s53
	v_dot4c_i32_i8_e32 v155, s0, v64
	v_perm_b32 v64, v65, v68, s54
	v_dot4c_i32_i8_e32 v156, s0, v64
	v_and_b32_e32 v64, 0xf0f0f0f, v74
	v_and_b32_e32 v68, 0xf0f0f0f, v78
	v_and_b32_e32 v72, 0xf0f0f0f, v70
	v_and_b32_e32 v73, 0xf0f0f0f, v66
	v_lshrrev_b32_e32 v65, 4, v74
	v_perm_b32 v74, v68, v64, s33
	v_perm_b32 v64, v68, v64, s52
	v_perm_b32 v68, v73, v72, s33
	v_dot4c_i32_i8_e32 v144, s0, v69
	v_lshrrev_b32_e32 v69, 4, v78
	v_lshrrev_b32_e32 v70, 4, v70
	v_lshrrev_b32_e32 v66, 4, v66
	v_perm_b32 v72, v73, v72, s52
	v_perm_b32 v73, v68, v74, s53
	v_perm_b32 v68, v68, v74, s54
	v_and_b32_e32 v65, 0xf0f0f0f, v65
	v_and_b32_e32 v69, 0xf0f0f0f, v69
	v_and_b32_e32 v70, 0xf0f0f0f, v70
	v_and_b32_e32 v66, 0xf0f0f0f, v66
	v_dot4c_i32_i8_e32 v153, s0, v68
	v_perm_b32 v68, v72, v64, s53
	v_perm_b32 v64, v72, v64, s54
	v_dot4c_i32_i8_e32 v147, s0, v68
	v_dot4c_i32_i8_e32 v148, s0, v64
	v_perm_b32 v64, v69, v65, s33
	v_perm_b32 v68, v66, v70, s33
	v_perm_b32 v65, v69, v65, s52
	v_perm_b32 v66, v66, v70, s52
	v_perm_b32 v69, v68, v64, s53
	v_perm_b32 v64, v68, v64, s54
	v_dot4c_i32_i8_e32 v145, s0, v64
	v_perm_b32 v64, v66, v65, s53
	v_dot4c_i32_i8_e32 v141, s0, v64
	v_perm_b32 v64, v66, v65, s54
	v_dot4c_i32_i8_e32 v143, s0, v69
	v_dot4c_i32_i8_e32 v142, s0, v64
	v_and_b32_e32 v64, 0xf0f0f0f, v75
	v_and_b32_e32 v66, 0xf0f0f0f, v79
	v_and_b32_e32 v69, 0xf0f0f0f, v71
	v_lshrrev_b32_e32 v70, 4, v71
	v_and_b32_e32 v71, 0xf0f0f0f, v67
	v_perm_b32 v72, v66, v64, s33
	v_perm_b32 v64, v66, v64, s52
	v_perm_b32 v66, v71, v69, s33
	v_lshrrev_b32_e32 v65, 4, v75
	v_lshrrev_b32_e32 v68, 4, v79
	v_lshrrev_b32_e32 v67, 4, v67
	v_perm_b32 v69, v71, v69, s52
	v_perm_b32 v71, v66, v72, s53
	v_perm_b32 v66, v66, v72, s54
	v_and_b32_e32 v65, 0xf0f0f0f, v65
	v_and_b32_e32 v68, 0xf0f0f0f, v68
	v_and_b32_e32 v70, 0xf0f0f0f, v70
	v_and_b32_e32 v67, 0xf0f0f0f, v67
	v_dot4c_i32_i8_e32 v140, s0, v66
	v_perm_b32 v66, v69, v64, s53
	v_perm_b32 v64, v69, v64, s54
	v_dot4c_i32_i8_e32 v137, s0, v66
	v_dot4c_i32_i8_e32 v139, s0, v64
	v_perm_b32 v64, v68, v65, s33
	v_perm_b32 v66, v67, v70, s33
	v_perm_b32 v65, v68, v65, s52
	v_perm_b32 v67, v67, v70, s52
	v_perm_b32 v68, v66, v64, s53
	v_perm_b32 v64, v66, v64, s54
	v_dot4c_i32_i8_e32 v135, s0, v64
	v_perm_b32 v64, v67, v65, s53
	v_dot4c_i32_i8_e32 v123, s0, v64
	v_perm_b32 v64, v67, v65, s54
	v_dot4c_i32_i8_e32 v125, s0, v64
	s_waitcnt vmcnt(3)
	v_and_b32_e32 v64, 0xf0f0f0f, v60
	s_waitcnt vmcnt(2)
	v_and_b32_e32 v65, 0xf0f0f0f, v56
	s_waitcnt vmcnt(1)
	v_and_b32_e32 v66, 0xf0f0f0f, v52
	s_waitcnt vmcnt(0)
; __device__ void phase_gather(const Params& p) {
;     ...
;       for (int gi = 0; gi < 64 / GROWS; ++gi) {
;         const int j0 = gi * GROWS;
;         if (gi + 2 < 64 / GROWS) {
; #pragma unroll
;           for (int k = 0; k < GROWS; ++k) {
;             const int e = __builtin_amdgcn_readlane(idv, j0 + 2 * GROWS + k);
;             rr[(gi + 2) % 3][k] = *(const u32x4*)(vb + (size_t)e * 1024 + lane * 16);
;           }
;         }
; #pragma unroll
;         for (int sub = 0; sub < GROWS / 4; ++sub) {
;           const int W4 = __builtin_amdgcn_readlane(pkv, j0 + 4 * sub);
; #pragma unroll
;           for (int m = 0; m < 4; ++m) {
;             unsigned lo[4], hi[4];
; #pragma unroll
;             for (int k = 0; k < 4; ++k) {
;               const unsigned w = rr[gi % 3][sub * 4 + k][m];
;               lo[k] = w & 0x0f0f0f0fu;
;               hi[k] = (w >> 4) & 0x0f0f0f0fu;
;             }
;             {
;               const unsigned p01l = __builtin_amdgcn_perm(lo[1], lo[0], 0x05010400u), p01h = __builtin_amdgcn_perm(lo[1], lo[0], 0x07030602u);
;               const unsigned p23l = __builtin_amdgcn_perm(lo[3], lo[2], 0x05010400u), p23h = __builtin_amdgcn_perm(lo[3], lo[2], 0x07030602u);
;               acc[m * 8 + 0] = __builtin_amdgcn_sdot4((int)__builtin_amdgcn_perm(p23l, p01l, 0x05040100u), W4, acc[m * 8 + 0], false);
;               acc[m * 8 + 1] = __builtin_amdgcn_sdot4((int)__builtin_amdgcn_perm(p23l, p01l, 0x07060302u), W4, acc[m * 8 + 1], false);
;               acc[m * 8 + 2] = __builtin_amdgcn_sdot4((int)__builtin_amdgcn_perm(p23h, p01h, 0x05040100u), W4, acc[m * 8 + 2], false);
;               acc[m * 8 + 3] = __builtin_amdgcn_sdot4((int)__builtin_amdgcn_perm(p23h, p01h, 0x07060302u), W4, acc[m * 8 + 3], false);
;             }
;             {
;               const unsigned p01l = __builtin_amdgcn_perm(hi[1], hi[0], 0x05010400u), p01h = __builtin_amdgcn_perm(hi[1], hi[0], 0x07030602u);
;               const unsigned p23l = __builtin_amdgcn_perm(hi[3], hi[2], 0x05010400u), p23h = __builtin_amdgcn_perm(hi[3], hi[2], 0x07030602u);
;               acc[m * 8 + 4] = __builtin_amdgcn_sdot4((int)__builtin_amdgcn_perm(p23l, p01l, 0x05040100u), W4, acc[m * 8 + 4], false);
;               acc[m * 8 + 5] = __builtin_amdgcn_sdot4((int)__builtin_amdgcn_perm(p23l, p01l, 0x07060302u), W4, acc[m * 8 + 5], false);
	v_and_b32_e32 v67, 0xf0f0f0f, v48
	v_dot4c_i32_i8_e32 v134, s0, v68
	v_perm_b32 v68, v65, v64, s33
	v_perm_b32 v64, v65, v64, s52
	v_perm_b32 v65, v67, v66, s33
	v_dot4c_i32_i8_e32 v163, s0, v83
	v_dot4c_i32_i8_e32 v161, s0, v81
	v_dot4c_i32_i8_e32 v152, s0, v77
	v_dot4c_i32_i8_e32 v151, s0, v73
	v_dot4c_i32_i8_e32 v136, s0, v71
	v_readlane_b32 s0, v170, 28
	v_lshrrev_b32_e32 v60, 4, v60
	v_lshrrev_b32_e32 v56, 4, v56
	v_lshrrev_b32_e32 v52, 4, v52
	v_lshrrev_b32_e32 v48, 4, v48
	v_perm_b32 v66, v67, v66, s52
	v_perm_b32 v67, v65, v68, s53
	v_perm_b32 v65, v65, v68, s54
	v_and_b32_e32 v60, 0xf0f0f0f, v60
	v_and_b32_e32 v56, 0xf0f0f0f, v56
	v_and_b32_e32 v52, 0xf0f0f0f, v52
	v_and_b32_e32 v48, 0xf0f0f0f, v48
	v_dot4c_i32_i8_e32 v164, s0, v65
	v_perm_b32 v65, v66, v64, s53
	v_perm_b32 v64, v66, v64, s54
	v_dot4c_i32_i8_e32 v162, s0, v64
	v_perm_b32 v64, v56, v60, s33
	v_perm_b32 v56, v56, v60, s52
	v_perm_b32 v60, v48, v52, s33
	v_perm_b32 v48, v48, v52, s52
	v_perm_b32 v52, v60, v64, s53
	v_dot4c_i32_i8_e32 v159, s0, v52
	v_perm_b32 v52, v60, v64, s54
	v_dot4c_i32_i8_e32 v160, s0, v52
	v_perm_b32 v52, v48, v56, s53
	v_perm_b32 v48, v48, v56, s54
	v_dot4c_i32_i8_e32 v157, s0, v52
	v_dot4c_i32_i8_e32 v158, s0, v48
	v_and_b32_e32 v48, 0xf0f0f0f, v61
	v_lshrrev_b32_e32 v52, 4, v61
	v_and_b32_e32 v56, 0xf0f0f0f, v57
	v_and_b32_e32 v60, 0xf0f0f0f, v53
	v_and_b32_e32 v61, 0xf0f0f0f, v49
	v_perm_b32 v64, v56, v48, s33
	v_perm_b32 v48, v56, v48, s52
	v_perm_b32 v56, v61, v60, s33
	v_lshrrev_b32_e32 v57, 4, v57
	v_lshrrev_b32_e32 v53, 4, v53
	v_lshrrev_b32_e32 v49, 4, v49
	v_perm_b32 v60, v61, v60, s52
	v_perm_b32 v61, v56, v64, s53
	v_perm_b32 v56, v56, v64, s54
	v_and_b32_e32 v52, 0xf0f0f0f, v52
	v_and_b32_e32 v57, 0xf0f0f0f, v57
	v_and_b32_e32 v53, 0xf0f0f0f, v53
	v_and_b32_e32 v49, 0xf0f0f0f, v49
	v_dot4c_i32_i8_e32 v154, s0, v56
	v_perm_b32 v56, v60, v48, s53
	v_perm_b32 v48, v60, v48, s54
	v_dot4c_i32_i8_e32 v149, s0, v56
	v_dot4c_i32_i8_e32 v150, s0, v48
	v_perm_b32 v48, v57, v52, s33
	v_perm_b32 v56, v49, v53, s33
	v_perm_b32 v52, v57, v52, s52
	v_perm_b32 v49, v49, v53, s52
	v_perm_b32 v53, v56, v48, s53
	v_perm_b32 v48, v56, v48, s54
	v_dot4c_i32_i8_e32 v146, s0, v48
	v_perm_b32 v48, v49, v52, s53
	v_dot4c_i32_i8_e32 v155, s0, v48
	v_perm_b32 v48, v49, v52, s54
	v_dot4c_i32_i8_e32 v156, s0, v48
	v_and_b32_e32 v48, 0xf0f0f0f, v62
	v_and_b32_e32 v52, 0xf0f0f0f, v58
	v_and_b32_e32 v56, 0xf0f0f0f, v54
	v_and_b32_e32 v57, 0xf0f0f0f, v50
	v_dot4c_i32_i8_e32 v144, s0, v53
	v_lshrrev_b32_e32 v53, 4, v58
	v_perm_b32 v58, v52, v48, s33
	v_perm_b32 v48, v52, v48, s52
	v_perm_b32 v52, v57, v56, s33
	v_lshrrev_b32_e32 v49, 4, v62
	v_lshrrev_b32_e32 v54, 4, v54
	v_lshrrev_b32_e32 v50, 4, v50
	v_perm_b32 v56, v57, v56, s52
	v_perm_b32 v57, v52, v58, s53
	v_perm_b32 v52, v52, v58, s54
	v_and_b32_e32 v49, 0xf0f0f0f, v49
	v_and_b32_e32 v53, 0xf0f0f0f, v53
	v_and_b32_e32 v54, 0xf0f0f0f, v54
	v_and_b32_e32 v50, 0xf0f0f0f, v50
	v_dot4c_i32_i8_e32 v153, s0, v52
	v_perm_b32 v52, v56, v48, s53
	v_perm_b32 v48, v56, v48, s54
	v_dot4c_i32_i8_e32 v147, s0, v52
	v_dot4c_i32_i8_e32 v148, s0, v48
	v_perm_b32 v48, v53, v49, s33
	v_perm_b32 v52, v50, v54, s33
	v_perm_b32 v49, v53, v49, s52
	v_perm_b32 v50, v50, v54, s52
	v_perm_b32 v53, v52, v48, s53
	v_perm_b32 v48, v52, v48, s54
	v_dot4c_i32_i8_e32 v145, s0, v48
	v_perm_b32 v48, v50, v49, s53
	v_dot4c_i32_i8_e32 v141, s0, v48
	v_perm_b32 v48, v50, v49, s54
	v_dot4c_i32_i8_e32 v143, s0, v53
	v_dot4c_i32_i8_e32 v142, s0, v48
	v_and_b32_e32 v48, 0xf0f0f0f, v63
	v_and_b32_e32 v50, 0xf0f0f0f, v59
	v_and_b32_e32 v53, 0xf0f0f0f, v55
	v_lshrrev_b32_e32 v54, 4, v55
	v_and_b32_e32 v55, 0xf0f0f0f, v51
	v_perm_b32 v56, v50, v48, s33
	v_perm_b32 v48, v50, v48, s52
	v_perm_b32 v50, v55, v53, s33
	v_lshrrev_b32_e32 v49, 4, v63
	v_lshrrev_b32_e32 v52, 4, v59
	v_lshrrev_b32_e32 v51, 4, v51
	v_perm_b32 v53, v55, v53, s52
	v_perm_b32 v55, v50, v56, s53
	v_perm_b32 v50, v50, v56, s54
	v_and_b32_e32 v49, 0xf0f0f0f, v49
	v_and_b32_e32 v52, 0xf0f0f0f, v52
	v_and_b32_e32 v54, 0xf0f0f0f, v54
	v_and_b32_e32 v51, 0xf0f0f0f, v51
	v_dot4c_i32_i8_e32 v140, s0, v50
	v_perm_b32 v50, v53, v48, s53
	v_perm_b32 v48, v53, v48, s54
	v_dot4c_i32_i8_e32 v137, s0, v50
	v_dot4c_i32_i8_e32 v139, s0, v48
	v_perm_b32 v48, v52, v49, s33
	v_perm_b32 v50, v51, v54, s33
	v_perm_b32 v49, v52, v49, s52
	v_perm_b32 v51, v51, v54, s52
	v_perm_b32 v52, v50, v48, s53
	v_perm_b32 v48, v50, v48, s54
	v_dot4c_i32_i8_e32 v135, s0, v48
	v_perm_b32 v48, v51, v49, s53
	v_dot4c_i32_i8_e32 v123, s0, v48
	v_perm_b32 v48, v51, v49, s54
	v_dot4c_i32_i8_e32 v163, s0, v67
	v_dot4c_i32_i8_e32 v161, s0, v65
	v_dot4c_i32_i8_e32 v152, s0, v61
	v_dot4c_i32_i8_e32 v151, s0, v57
	v_dot4c_i32_i8_e32 v136, s0, v55
	v_dot4c_i32_i8_e32 v134, s0, v52
	v_dot4c_i32_i8_e32 v125, s0, v48
	v_readlane_b32 s0, v250, 40
	v_readlane_b32 s1, v250, 41
	global_load_dwordx4 v[0:3], v[0:1], off
	v_lshl_add_u64 v[16:17], v[116:117], 0, s[58:59]
	v_lshl_add_u64 v[48:49], v[116:117], 0, s[0:1]
	v_readlane_b32 s0, v250, 42
	v_readlane_b32 s1, v250, 43
	global_load_dwordx4 v[64:67], v[48:49], off
	v_lshl_add_u64 v[20:21], v[116:117], 0, s[60:61]
	v_lshl_add_u64 v[48:49], v[116:117], 0, s[0:1]
	v_readlane_b32 s0, v250, 44
	v_readlane_b32 s1, v250, 45
	global_load_dwordx4 v[68:71], v[48:49], off
	v_and_b32_e32 v50, 0xf0f0f0f, v104
	v_lshl_add_u64 v[48:49], v[116:117], 0, s[0:1]
	v_readlane_b32 s0, v250, 46
	v_readlane_b32 s1, v250, 47
	global_load_dwordx4 v[72:75], v[48:49], off
	v_and_b32_e32 v52, 0xf0f0f0f, v100
	v_lshl_add_u64 v[48:49], v[116:117], 0, s[0:1]
	v_readlane_b32 s0, v250, 48
	v_readlane_b32 s1, v250, 49
; __device__ void phase_gather(const Params& p) {
;     ...
;       for (int gi = 0; gi < 64 / GROWS; ++gi) {
;         const int j0 = gi * GROWS;
;         if (gi + 2 < 64 / GROWS) {
; #pragma unroll
;           for (int k = 0; k < GROWS; ++k) {
;             const int e = __builtin_amdgcn_readlane(idv, j0 + 2 * GROWS + k);
;             rr[(gi + 2) % 3][k] = *(const u32x4*)(vb + (size_t)e * 1024 + lane * 16);
;           }
;         }
; #pragma unroll
;         for (int sub = 0; sub < GROWS / 4; ++sub) {
;           const int W4 = __builtin_amdgcn_readlane(pkv, j0 + 4 * sub);
; #pragma unroll
;           for (int m = 0; m < 4; ++m) {
;             unsigned lo[4], hi[4];
; #pragma unroll
;             for (int k = 0; k < 4; ++k) {
;               const unsigned w = rr[gi % 3][sub * 4 + k][m];
;               lo[k] = w & 0x0f0f0f0fu;
;               hi[k] = (w >> 4) & 0x0f0f0f0fu;
;             }
;             {
;               const unsigned p01l = __builtin_amdgcn_perm(lo[1], lo[0], 0x05010400u), p01h = __builtin_amdgcn_perm(lo[1], lo[0], 0x07030602u);
;               const unsigned p23l = __builtin_amdgcn_perm(lo[3], lo[2], 0x05010400u), p23h = __builtin_amdgcn_perm(lo[3], lo[2], 0x07030602u);
;               acc[m * 8 + 0] = __builtin_amdgcn_sdot4((int)__builtin_amdgcn_perm(p23l, p01l, 0x05040100u), W4, acc[m * 8 + 0], false);
;               acc[m * 8 + 1] = __builtin_amdgcn_sdot4((int)__builtin_amdgcn_perm(p23l, p01l, 0x07060302u), W4, acc[m * 8 + 1], false);
;               acc[m * 8 + 2] = __builtin_amdgcn_sdot4((int)__builtin_amdgcn_perm(p23h, p01h, 0x05040100u), W4, acc[m * 8 + 2], false);
;               acc[m * 8 + 3] = __builtin_amdgcn_sdot4((int)__builtin_amdgcn_perm(p23h, p01h, 0x07060302u), W4, acc[m * 8 + 3], false);
;             }
;             {
;               const unsigned p01l = __builtin_amdgcn_perm(hi[1], hi[0], 0x05010400u), p01h = __builtin_amdgcn_perm(hi[1], hi[0], 0x07030602u);
;               const unsigned p23l = __builtin_amdgcn_perm(hi[3], hi[2], 0x05010400u), p23h = __builtin_amdgcn_perm(hi[3], hi[2], 0x07030602u);
;               acc[m * 8 + 4] = __builtin_amdgcn_sdot4((int)__builtin_amdgcn_perm(p23l, p01l, 0x05040100u), W4, acc[m * 8 + 4], false);
;               acc[m * 8 + 5] = __builtin_amdgcn_sdot4((int)__builtin_amdgcn_perm(p23l, p01l, 0x07060302u), W4, acc[m * 8 + 5], false);
	global_load_dwordx4 v[76:79], v[48:49], off
	v_and_b32_e32 v54, 0xf0f0f0f, v96
	v_lshl_add_u64 v[48:49], v[116:117], 0, s[0:1]
	v_readlane_b32 s0, v250, 50
	v_readlane_b32 s1, v250, 51
	global_load_dwordx4 v[80:83], v[48:49], off
	v_lshrrev_b32_e32 v51, 4, v104
	v_lshl_add_u64 v[48:49], v[116:117], 0, s[0:1]
	v_readlane_b32 s0, v250, 52
	v_readlane_b32 s1, v250, 53
	global_load_dwordx4 v[4:7], v[4:5], off
	v_lshrrev_b32_e32 v53, 4, v100
	global_load_dwordx4 v[8:11], v[8:9], off
	v_lshrrev_b32_e32 v55, 4, v96
	global_load_dwordx4 v[12:15], v[12:13], off
	v_and_b32_e32 v51, 0xf0f0f0f, v51
	global_load_dwordx4 v[84:87], v[48:49], off
	v_lshl_add_u64 v[48:49], v[116:117], 0, s[0:1]
	v_readlane_b32 s0, v250, 54
	global_load_dwordx4 v[16:19], v[16:17], off
	v_readlane_b32 s1, v250, 55
	global_load_dwordx4 v[20:23], v[20:21], off
	v_and_b32_e32 v53, 0xf0f0f0f, v53
	global_load_dwordx4 v[88:91], v[48:49], off
	v_lshl_add_u64 v[48:49], v[116:117], 0, s[0:1]
	global_load_dwordx4 v[92:95], v[48:49], off
	v_and_b32_e32 v48, 0xf0f0f0f, v108
	v_perm_b32 v56, v50, v48, s33
	v_perm_b32 v48, v50, v48, s52
	v_perm_b32 v50, v54, v52, s33
	v_readlane_b32 s0, v170, 32
	v_lshrrev_b32_e32 v49, 4, v108
	v_perm_b32 v52, v54, v52, s52
	v_perm_b32 v54, v50, v56, s53
	v_perm_b32 v50, v50, v56, s54
	v_and_b32_e32 v49, 0xf0f0f0f, v49
	v_and_b32_e32 v55, 0xf0f0f0f, v55
	v_dot4c_i32_i8_e32 v164, s0, v50
	v_perm_b32 v50, v52, v48, s53
	v_perm_b32 v48, v52, v48, s54
	v_dot4c_i32_i8_e32 v161, s0, v50
	v_dot4c_i32_i8_e32 v162, s0, v48
	v_perm_b32 v48, v51, v49, s33
	v_perm_b32 v50, v55, v53, s33
	v_perm_b32 v49, v51, v49, s52
	v_perm_b32 v51, v55, v53, s52
	v_perm_b32 v52, v50, v48, s53
	v_perm_b32 v48, v50, v48, s54
	v_dot4c_i32_i8_e32 v160, s0, v48
	v_perm_b32 v48, v51, v49, s53
	v_dot4c_i32_i8_e32 v157, s0, v48
	v_perm_b32 v48, v51, v49, s54
	v_dot4c_i32_i8_e32 v163, s0, v54
	v_dot4c_i32_i8_e32 v159, s0, v52
	v_dot4c_i32_i8_e32 v158, s0, v48
	v_and_b32_e32 v48, 0xf0f0f0f, v109
	v_and_b32_e32 v50, 0xf0f0f0f, v105
	v_and_b32_e32 v52, 0xf0f0f0f, v101
	v_and_b32_e32 v54, 0xf0f0f0f, v97
	v_perm_b32 v56, v50, v48, s33
	v_perm_b32 v48, v50, v48, s52
	v_perm_b32 v50, v54, v52, s33
	v_lshrrev_b32_e32 v49, 4, v109
	v_lshrrev_b32_e32 v51, 4, v105
	v_lshrrev_b32_e32 v53, 4, v101
	v_lshrrev_b32_e32 v55, 4, v97
	v_perm_b32 v52, v54, v52, s52
	v_perm_b32 v54, v50, v56, s53
	v_perm_b32 v50, v50, v56, s54
	v_and_b32_e32 v49, 0xf0f0f0f, v49
	v_and_b32_e32 v51, 0xf0f0f0f, v51
	v_and_b32_e32 v53, 0xf0f0f0f, v53
	v_and_b32_e32 v55, 0xf0f0f0f, v55
	v_dot4c_i32_i8_e32 v154, s0, v50
	v_perm_b32 v50, v52, v48, s53
	v_perm_b32 v48, v52, v48, s54
	v_dot4c_i32_i8_e32 v149, s0, v50
	v_dot4c_i32_i8_e32 v150, s0, v48
	v_perm_b32 v48, v51, v49, s33
	v_perm_b32 v50, v55, v53, s33
	v_perm_b32 v49, v51, v49, s52
	v_perm_b32 v51, v55, v53, s52
	v_perm_b32 v52, v50, v48, s53
	v_perm_b32 v48, v50, v48, s54
	v_dot4c_i32_i8_e32 v146, s0, v48
	v_perm_b32 v48, v51, v49, s53
	v_dot4c_i32_i8_e32 v155, s0, v48
	v_perm_b32 v48, v51, v49, s54
	v_dot4c_i32_i8_e32 v152, s0, v54
	v_dot4c_i32_i8_e32 v144, s0, v52
	v_dot4c_i32_i8_e32 v156, s0, v48
	v_and_b32_e32 v48, 0xf0f0f0f, v110
	v_and_b32_e32 v50, 0xf0f0f0f, v106
	v_and_b32_e32 v52, 0xf0f0f0f, v102
	v_and_b32_e32 v54, 0xf0f0f0f, v98
	v_perm_b32 v56, v50, v48, s33
	v_perm_b32 v48, v50, v48, s52
	v_perm_b32 v50, v54, v52, s33
	v_lshrrev_b32_e32 v49, 4, v110
	v_lshrrev_b32_e32 v51, 4, v106
	v_lshrrev_b32_e32 v53, 4, v102
	v_lshrrev_b32_e32 v55, 4, v98
	v_perm_b32 v52, v54, v52, s52
	v_perm_b32 v54, v50, v56, s53
	v_perm_b32 v50, v50, v56, s54
	v_and_b32_e32 v49, 0xf0f0f0f, v49
	v_and_b32_e32 v51, 0xf0f0f0f, v51
	v_and_b32_e32 v53, 0xf0f0f0f, v53
	v_and_b32_e32 v55, 0xf0f0f0f, v55
	v_dot4c_i32_i8_e32 v153, s0, v50
	v_perm_b32 v50, v52, v48, s53
	v_perm_b32 v48, v52, v48, s54
	v_dot4c_i32_i8_e32 v147, s0, v50
	v_dot4c_i32_i8_e32 v148, s0, v48
	v_perm_b32 v48, v51, v49, s33
	v_perm_b32 v50, v55, v53, s33
	v_perm_b32 v49, v51, v49, s52
	v_perm_b32 v51, v55, v53, s52
	v_perm_b32 v52, v50, v48, s53
	v_perm_b32 v48, v50, v48, s54
	v_dot4c_i32_i8_e32 v145, s0, v48
	v_perm_b32 v48, v51, v49, s53
	v_dot4c_i32_i8_e32 v141, s0, v48
	v_perm_b32 v48, v51, v49, s54
	v_dot4c_i32_i8_e32 v151, s0, v54
	v_dot4c_i32_i8_e32 v143, s0, v52
	v_dot4c_i32_i8_e32 v142, s0, v48
	v_and_b32_e32 v48, 0xf0f0f0f, v111
	v_and_b32_e32 v50, 0xf0f0f0f, v107
	v_and_b32_e32 v52, 0xf0f0f0f, v103
	v_and_b32_e32 v54, 0xf0f0f0f, v99
	v_perm_b32 v56, v50, v48, s33
	v_perm_b32 v48, v50, v48, s52
	v_perm_b32 v50, v54, v52, s33
	v_lshrrev_b32_e32 v49, 4, v111
	v_lshrrev_b32_e32 v51, 4, v107
	v_lshrrev_b32_e32 v53, 4, v103
	v_lshrrev_b32_e32 v55, 4, v99
	v_perm_b32 v52, v54, v52, s52
	v_perm_b32 v54, v50, v56, s53
	v_perm_b32 v50, v50, v56, s54
	v_and_b32_e32 v49, 0xf0f0f0f, v49
	v_and_b32_e32 v51, 0xf0f0f0f, v51
	v_and_b32_e32 v53, 0xf0f0f0f, v53
	v_and_b32_e32 v55, 0xf0f0f0f, v55
	v_dot4c_i32_i8_e32 v140, s0, v50
	v_perm_b32 v50, v52, v48, s53
	v_perm_b32 v48, v52, v48, s54
	v_dot4c_i32_i8_e32 v137, s0, v50
	v_dot4c_i32_i8_e32 v139, s0, v48
	v_perm_b32 v48, v51, v49, s33
	v_perm_b32 v50, v55, v53, s33
	v_perm_b32 v49, v51, v49, s52
	v_perm_b32 v51, v55, v53, s52
	v_perm_b32 v52, v50, v48, s53
	v_perm_b32 v48, v50, v48, s54
	v_dot4c_i32_i8_e32 v135, s0, v48
	v_perm_b32 v48, v51, v49, s53
	v_dot4c_i32_i8_e32 v123, s0, v48
	v_perm_b32 v48, v51, v49, s54
	v_dot4c_i32_i8_e32 v125, s0, v48
	v_and_b32_e32 v48, 0xf0f0f0f, v44
	v_and_b32_e32 v49, 0xf0f0f0f, v40
	v_and_b32_e32 v50, 0xf0f0f0f, v36
	v_and_b32_e32 v51, 0xf0f0f0f, v32
	v_dot4c_i32_i8_e32 v134, s0, v52
	v_perm_b32 v52, v49, v48, s33
	v_perm_b32 v48, v49, v48, s52
; __device__ void phase_gather(const Params& p) {
;     ...
;       for (int gi = 0; gi < 64 / GROWS; ++gi) {
;         const int j0 = gi * GROWS;
;         if (gi + 2 < 64 / GROWS) {
; #pragma unroll
;           for (int k = 0; k < GROWS; ++k) {
;             const int e = __builtin_amdgcn_readlane(idv, j0 + 2 * GROWS + k);
;             rr[(gi + 2) % 3][k] = *(const u32x4*)(vb + (size_t)e * 1024 + lane * 16);
;           }
;         }
; #pragma unroll
;         for (int sub = 0; sub < GROWS / 4; ++sub) {
;           const int W4 = __builtin_amdgcn_readlane(pkv, j0 + 4 * sub);
; #pragma unroll
;           for (int m = 0; m < 4; ++m) {
;             unsigned lo[4], hi[4];
; #pragma unroll
;             for (int k = 0; k < 4; ++k) {
;               const unsigned w = rr[gi % 3][sub * 4 + k][m];
;               lo[k] = w & 0x0f0f0f0fu;
;               hi[k] = (w >> 4) & 0x0f0f0f0fu;
;             }
;             {
;               const unsigned p01l = __builtin_amdgcn_perm(lo[1], lo[0], 0x05010400u), p01h = __builtin_amdgcn_perm(lo[1], lo[0], 0x07030602u);
;               const unsigned p23l = __builtin_amdgcn_perm(lo[3], lo[2], 0x05010400u), p23h = __builtin_amdgcn_perm(lo[3], lo[2], 0x07030602u);
;               acc[m * 8 + 0] = __builtin_amdgcn_sdot4((int)__builtin_amdgcn_perm(p23l, p01l, 0x05040100u), W4, acc[m * 8 + 0], false);
;               acc[m * 8 + 1] = __builtin_amdgcn_sdot4((int)__builtin_amdgcn_perm(p23l, p01l, 0x07060302u), W4, acc[m * 8 + 1], false);
;               acc[m * 8 + 2] = __builtin_amdgcn_sdot4((int)__builtin_amdgcn_perm(p23h, p01h, 0x05040100u), W4, acc[m * 8 + 2], false);
;               acc[m * 8 + 3] = __builtin_amdgcn_sdot4((int)__builtin_amdgcn_perm(p23h, p01h, 0x07060302u), W4, acc[m * 8 + 3], false);
;             }
;             {
;               const unsigned p01l = __builtin_amdgcn_perm(hi[1], hi[0], 0x05010400u), p01h = __builtin_amdgcn_perm(hi[1], hi[0], 0x07030602u);
;               const unsigned p23l = __builtin_amdgcn_perm(hi[3], hi[2], 0x05010400u), p23h = __builtin_amdgcn_perm(hi[3], hi[2], 0x07030602u);
;               acc[m * 8 + 4] = __builtin_amdgcn_sdot4((int)__builtin_amdgcn_perm(p23l, p01l, 0x05040100u), W4, acc[m * 8 + 4], false);
;               acc[m * 8 + 5] = __builtin_amdgcn_sdot4((int)__builtin_amdgcn_perm(p23l, p01l, 0x07060302u), W4, acc[m * 8 + 5], false);
	v_perm_b32 v49, v51, v50, s33
	v_dot4c_i32_i8_e32 v136, s0, v54
	v_readlane_b32 s0, v170, 36
	v_lshrrev_b32_e32 v44, 4, v44
	v_lshrrev_b32_e32 v40, 4, v40
	v_lshrrev_b32_e32 v36, 4, v36
	v_lshrrev_b32_e32 v32, 4, v32
	v_perm_b32 v50, v51, v50, s52
	v_perm_b32 v51, v49, v52, s53
	v_perm_b32 v49, v49, v52, s54
	v_and_b32_e32 v44, 0xf0f0f0f, v44
	v_and_b32_e32 v40, 0xf0f0f0f, v40
	v_and_b32_e32 v36, 0xf0f0f0f, v36
	v_and_b32_e32 v32, 0xf0f0f0f, v32
	v_dot4c_i32_i8_e32 v164, s0, v49
	v_perm_b32 v49, v50, v48, s53
	v_perm_b32 v48, v50, v48, s54
	v_dot4c_i32_i8_e32 v162, s0, v48
	v_perm_b32 v48, v40, v44, s33
	v_perm_b32 v40, v40, v44, s52
	v_perm_b32 v44, v32, v36, s33
	v_perm_b32 v32, v32, v36, s52
	v_perm_b32 v36, v44, v48, s53
	v_dot4c_i32_i8_e32 v159, s0, v36
	v_perm_b32 v36, v44, v48, s54
	v_dot4c_i32_i8_e32 v160, s0, v36
	v_perm_b32 v36, v32, v40, s53
	v_perm_b32 v32, v32, v40, s54
	v_dot4c_i32_i8_e32 v157, s0, v36
	v_dot4c_i32_i8_e32 v158, s0, v32
	v_and_b32_e32 v32, 0xf0f0f0f, v45
	v_lshrrev_b32_e32 v36, 4, v45
	v_and_b32_e32 v40, 0xf0f0f0f, v41
	v_and_b32_e32 v44, 0xf0f0f0f, v37
	v_and_b32_e32 v45, 0xf0f0f0f, v33
	v_perm_b32 v48, v40, v32, s33
	v_perm_b32 v32, v40, v32, s52
	v_perm_b32 v40, v45, v44, s33
	v_lshrrev_b32_e32 v41, 4, v41
	v_lshrrev_b32_e32 v37, 4, v37
	v_lshrrev_b32_e32 v33, 4, v33
	v_perm_b32 v44, v45, v44, s52
	v_perm_b32 v45, v40, v48, s53
	v_perm_b32 v40, v40, v48, s54
	v_and_b32_e32 v36, 0xf0f0f0f, v36
	v_and_b32_e32 v41, 0xf0f0f0f, v41
	v_and_b32_e32 v37, 0xf0f0f0f, v37
	v_and_b32_e32 v33, 0xf0f0f0f, v33
	v_dot4c_i32_i8_e32 v154, s0, v40
	v_perm_b32 v40, v44, v32, s53
	v_perm_b32 v32, v44, v32, s54
	v_dot4c_i32_i8_e32 v149, s0, v40
	v_dot4c_i32_i8_e32 v150, s0, v32
	v_perm_b32 v32, v41, v36, s33
	v_perm_b32 v40, v33, v37, s33
	v_perm_b32 v36, v41, v36, s52
	v_perm_b32 v33, v33, v37, s52
	v_perm_b32 v37, v40, v32, s53
	v_perm_b32 v32, v40, v32, s54
	v_dot4c_i32_i8_e32 v146, s0, v32
	v_perm_b32 v32, v33, v36, s53
	v_dot4c_i32_i8_e32 v155, s0, v32
	v_perm_b32 v32, v33, v36, s54
	v_dot4c_i32_i8_e32 v156, s0, v32
	v_and_b32_e32 v32, 0xf0f0f0f, v46
	v_and_b32_e32 v36, 0xf0f0f0f, v42
	v_and_b32_e32 v40, 0xf0f0f0f, v38
	v_and_b32_e32 v41, 0xf0f0f0f, v34
	v_dot4c_i32_i8_e32 v144, s0, v37
	v_lshrrev_b32_e32 v37, 4, v42
	v_perm_b32 v42, v36, v32, s33
	v_perm_b32 v32, v36, v32, s52
	v_perm_b32 v36, v41, v40, s33
	v_lshrrev_b32_e32 v33, 4, v46
	v_lshrrev_b32_e32 v38, 4, v38
	v_lshrrev_b32_e32 v34, 4, v34
	v_perm_b32 v40, v41, v40, s52
	v_perm_b32 v41, v36, v42, s53
	v_perm_b32 v36, v36, v42, s54
	v_and_b32_e32 v33, 0xf0f0f0f, v33
	v_and_b32_e32 v37, 0xf0f0f0f, v37
	v_and_b32_e32 v38, 0xf0f0f0f, v38
	v_and_b32_e32 v34, 0xf0f0f0f, v34
	v_dot4c_i32_i8_e32 v153, s0, v36
	v_perm_b32 v36, v40, v32, s53
	v_perm_b32 v32, v40, v32, s54
	v_dot4c_i32_i8_e32 v147, s0, v36
	v_dot4c_i32_i8_e32 v148, s0, v32
	v_perm_b32 v32, v37, v33, s33
	v_perm_b32 v36, v34, v38, s33
	v_perm_b32 v33, v37, v33, s52
	v_perm_b32 v34, v34, v38, s52
	v_perm_b32 v37, v36, v32, s53
	v_perm_b32 v32, v36, v32, s54
	v_dot4c_i32_i8_e32 v145, s0, v32
	v_perm_b32 v32, v34, v33, s53
	v_dot4c_i32_i8_e32 v141, s0, v32
	v_perm_b32 v32, v34, v33, s54
	v_dot4c_i32_i8_e32 v143, s0, v37
	v_dot4c_i32_i8_e32 v142, s0, v32
	v_and_b32_e32 v32, 0xf0f0f0f, v47
	v_and_b32_e32 v34, 0xf0f0f0f, v43
	v_and_b32_e32 v37, 0xf0f0f0f, v39
	v_lshrrev_b32_e32 v38, 4, v39
	v_and_b32_e32 v39, 0xf0f0f0f, v35
	v_perm_b32 v40, v34, v32, s33
	v_perm_b32 v32, v34, v32, s52
	v_perm_b32 v34, v39, v37, s33
	v_lshrrev_b32_e32 v33, 4, v47
	v_lshrrev_b32_e32 v36, 4, v43
	v_lshrrev_b32_e32 v35, 4, v35
	v_perm_b32 v37, v39, v37, s52
	v_perm_b32 v39, v34, v40, s53
	v_perm_b32 v34, v34, v40, s54
	v_and_b32_e32 v33, 0xf0f0f0f, v33
	v_and_b32_e32 v36, 0xf0f0f0f, v36
	v_and_b32_e32 v38, 0xf0f0f0f, v38
	v_and_b32_e32 v35, 0xf0f0f0f, v35
	v_dot4c_i32_i8_e32 v140, s0, v34
	v_perm_b32 v34, v37, v32, s53
	v_perm_b32 v32, v37, v32, s54
	v_dot4c_i32_i8_e32 v137, s0, v34
	v_dot4c_i32_i8_e32 v139, s0, v32
	v_perm_b32 v32, v36, v33, s33
	v_perm_b32 v34, v35, v38, s33
	v_perm_b32 v33, v36, v33, s52
	v_perm_b32 v35, v35, v38, s52
	v_perm_b32 v36, v34, v32, s53
	v_perm_b32 v32, v34, v32, s54
	v_dot4c_i32_i8_e32 v135, s0, v32
	v_perm_b32 v32, v35, v33, s53
	v_dot4c_i32_i8_e32 v123, s0, v32
	v_perm_b32 v32, v35, v33, s54
	v_dot4c_i32_i8_e32 v163, s0, v51
	v_dot4c_i32_i8_e32 v161, s0, v49
	v_dot4c_i32_i8_e32 v152, s0, v45
	v_dot4c_i32_i8_e32 v151, s0, v41
	v_dot4c_i32_i8_e32 v136, s0, v39
	v_dot4c_i32_i8_e32 v134, s0, v36
	v_dot4c_i32_i8_e32 v125, s0, v32
	v_readlane_b32 s0, v250, 6
	v_readlane_b32 s1, v250, 7
	s_waitcnt vmcnt(5)
	v_lshrrev_b32_e32 v176, 4, v15
	v_lshrrev_b32_e32 v177, 4, v11
	v_lshl_add_u64 v[32:33], v[116:117], 0, s[0:1]
	v_readlane_b32 s0, v250, 4
	v_readlane_b32 s1, v250, 5
	global_load_dwordx4 v[60:63], v[32:33], off
	v_lshrrev_b32_e32 v179, 4, v7
	v_lshl_add_u64 v[32:33], v[116:117], 0, s[0:1]
	v_readlane_b32 s0, v250, 14
	v_readlane_b32 s1, v250, 15
	global_load_dwordx4 v[56:59], v[32:33], off
	v_lshrrev_b32_e32 v180, 4, v3
	v_lshl_add_u64 v[32:33], v[116:117], 0, s[0:1]
	v_readlane_b32 s0, v250, 10
	v_readlane_b32 s1, v250, 11
	global_load_dwordx4 v[52:55], v[32:33], off
	v_lshrrev_b32_e32 v110, 4, v31
	v_lshl_add_u64 v[32:33], v[116:117], 0, s[0:1]
	v_readlane_b32 s0, v250, 12
	v_readlane_b32 s1, v250, 13
	global_load_dwordx4 v[48:51], v[32:33], off
	v_lshrrev_b32_e32 v111, 4, v27
	v_lshl_add_u64 v[32:33], v[116:117], 0, s[0:1]
	v_readlane_b32 s0, v250, 2
	v_readlane_b32 s1, v250, 3
	global_load_dwordx4 v[44:47], v[32:33], off
	s_waitcnt vmcnt(7)
; __device__ void phase_gather(const Params& p) {
;     ...
;       for (int gi = 0; gi < 64 / GROWS; ++gi) {
;         const int j0 = gi * GROWS;
;         if (gi + 2 < 64 / GROWS) {
; #pragma unroll
;           for (int k = 0; k < GROWS; ++k) {
;             const int e = __builtin_amdgcn_readlane(idv, j0 + 2 * GROWS + k);
;             rr[(gi + 2) % 3][k] = *(const u32x4*)(vb + (size_t)e * 1024 + lane * 16);
;           }
;         }
; #pragma unroll
;         for (int sub = 0; sub < GROWS / 4; ++sub) {
;           const int W4 = __builtin_amdgcn_readlane(pkv, j0 + 4 * sub);
; #pragma unroll
;           for (int m = 0; m < 4; ++m) {
;             unsigned lo[4], hi[4];
; #pragma unroll
;             for (int k = 0; k < 4; ++k) {
;               const unsigned w = rr[gi % 3][sub * 4 + k][m];
;               lo[k] = w & 0x0f0f0f0fu;
;               hi[k] = (w >> 4) & 0x0f0f0f0fu;
;             }
;             {
;               const unsigned p01l = __builtin_amdgcn_perm(lo[1], lo[0], 0x05010400u), p01h = __builtin_amdgcn_perm(lo[1], lo[0], 0x07030602u);
;               const unsigned p23l = __builtin_amdgcn_perm(lo[3], lo[2], 0x05010400u), p23h = __builtin_amdgcn_perm(lo[3], lo[2], 0x07030602u);
;               acc[m * 8 + 0] = __builtin_amdgcn_sdot4((int)__builtin_amdgcn_perm(p23l, p01l, 0x05040100u), W4, acc[m * 8 + 0], false);
;               acc[m * 8 + 1] = __builtin_amdgcn_sdot4((int)__builtin_amdgcn_perm(p23l, p01l, 0x07060302u), W4, acc[m * 8 + 1], false);
;               acc[m * 8 + 2] = __builtin_amdgcn_sdot4((int)__builtin_amdgcn_perm(p23h, p01h, 0x05040100u), W4, acc[m * 8 + 2], false);
;               acc[m * 8 + 3] = __builtin_amdgcn_sdot4((int)__builtin_amdgcn_perm(p23h, p01h, 0x07060302u), W4, acc[m * 8 + 3], false);
;             }
;             {
;               const unsigned p01l = __builtin_amdgcn_perm(hi[1], hi[0], 0x05010400u), p01h = __builtin_amdgcn_perm(hi[1], hi[0], 0x07030602u);
;               const unsigned p23l = __builtin_amdgcn_perm(hi[3], hi[2], 0x05010400u), p23h = __builtin_amdgcn_perm(hi[3], hi[2], 0x07030602u);
;               acc[m * 8 + 4] = __builtin_amdgcn_sdot4((int)__builtin_amdgcn_perm(p23l, p01l, 0x05040100u), W4, acc[m * 8 + 4], false);
;               acc[m * 8 + 5] = __builtin_amdgcn_sdot4((int)__builtin_amdgcn_perm(p23l, p01l, 0x07060302u), W4, acc[m * 8 + 5], false);
	v_lshrrev_b32_e32 v172, 4, v23
	v_lshl_add_u64 v[32:33], v[116:117], 0, s[0:1]
	v_readlane_b32 s0, v250, 0
	v_readlane_b32 s1, v250, 1
	global_load_dwordx4 v[40:43], v[32:33], off
	v_lshrrev_b32_e32 v173, 4, v19
	v_lshl_add_u64 v[32:33], v[116:117], 0, s[0:1]
	v_readlane_b32 s0, v250, 16
	v_and_b32_e32 v176, 0xf0f0f0f, v176
	v_and_b32_e32 v177, 0xf0f0f0f, v177
	v_and_b32_e32 v179, 0xf0f0f0f, v179
	v_and_b32_e32 v180, 0xf0f0f0f, v180
	v_readlane_b32 s1, v250, 17
	v_lshrrev_b32_e32 v103, 4, v79
	v_lshrrev_b32_e32 v104, 4, v75
	v_lshrrev_b32_e32 v106, 4, v71
	v_lshrrev_b32_e32 v107, 4, v67
	v_and_b32_e32 v110, 0xf0f0f0f, v110
	v_and_b32_e32 v111, 0xf0f0f0f, v111
	v_and_b32_e32 v172, 0xf0f0f0f, v172
	v_and_b32_e32 v173, 0xf0f0f0f, v173
	v_perm_b32 v178, v176, v177, s52
	v_perm_b32 v181, v179, v180, s52
	global_load_dwordx4 v[36:39], v[32:33], off
	v_lshl_add_u64 v[32:33], v[116:117], 0, s[0:1]
	v_readlane_b32 s0, v170, 40
	s_waitcnt vmcnt(7)
	v_lshrrev_b32_e32 v96, 4, v95
	v_lshrrev_b32_e32 v97, 4, v91
	v_lshrrev_b32_e32 v99, 4, v87
	v_lshrrev_b32_e32 v100, 4, v83
	v_and_b32_e32 v103, 0xf0f0f0f, v103
	v_and_b32_e32 v104, 0xf0f0f0f, v104
	v_and_b32_e32 v106, 0xf0f0f0f, v106
	v_and_b32_e32 v107, 0xf0f0f0f, v107
	v_perm_b32 v171, v110, v111, s52
	v_perm_b32 v174, v172, v173, s52
	v_perm_b32 v182, v178, v181, s54
	v_readlane_b32 s1, v170, 44
	v_and_b32_e32 v96, 0xf0f0f0f, v96
	v_and_b32_e32 v97, 0xf0f0f0f, v97
	v_and_b32_e32 v99, 0xf0f0f0f, v99
	v_and_b32_e32 v100, 0xf0f0f0f, v100
	v_perm_b32 v105, v103, v104, s52
	v_perm_b32 v108, v106, v107, s52
	v_perm_b32 v175, v171, v174, s54
	v_dot4c_i32_i8_e32 v125, s0, v182
	v_perm_b32 v98, v96, v97, s52
	v_perm_b32 v101, v99, v100, s52
	v_perm_b32 v109, v105, v108, s54
	v_dot4c_i32_i8_e32 v125, s1, v175
	v_perm_b32 v102, v98, v101, s54
	v_dot4c_i32_i8_e32 v125, s2, v109
	v_perm_b32 v98, v98, v101, s53
	v_perm_b32 v101, v105, v108, s53
	v_perm_b32 v105, v178, v181, s53
	v_dot4c_i32_i8_e32 v125, s3, v102
	v_perm_b32 v102, v171, v174, s53
	v_dot4c_i32_i8_e32 v123, s0, v105
	v_perm_b32 v96, v96, v97, s33
	v_perm_b32 v97, v99, v100, s33
	v_perm_b32 v100, v106, v107, s33
	v_perm_b32 v105, v176, v177, s33
	v_perm_b32 v106, v179, v180, s33
	v_dot4c_i32_i8_e32 v123, s1, v102
	v_perm_b32 v99, v103, v104, s33
	v_perm_b32 v102, v110, v111, s33
	v_perm_b32 v103, v172, v173, s33
	v_perm_b32 v107, v105, v106, s54
	v_perm_b32 v104, v102, v103, s54
	v_dot4c_i32_i8_e32 v135, s0, v107
	v_dot4c_i32_i8_e32 v123, s2, v101
	v_perm_b32 v101, v99, v100, s54
	v_dot4c_i32_i8_e32 v135, s1, v104
	v_dot4c_i32_i8_e32 v123, s3, v98
	v_perm_b32 v98, v96, v97, s54
	v_dot4c_i32_i8_e32 v135, s2, v101
	v_perm_b32 v96, v96, v97, s53
	v_perm_b32 v97, v99, v100, s53
	v_perm_b32 v99, v105, v106, s53
	v_and_b32_e32 v15, 0xf0f0f0f, v15
	v_and_b32_e32 v11, 0xf0f0f0f, v11
	v_and_b32_e32 v7, 0xf0f0f0f, v7
	v_and_b32_e32 v3, 0xf0f0f0f, v3
	v_dot4c_i32_i8_e32 v135, s3, v98
	v_perm_b32 v98, v102, v103, s53
	v_dot4c_i32_i8_e32 v134, s0, v99
	v_and_b32_e32 v31, 0xf0f0f0f, v31
	v_and_b32_e32 v27, 0xf0f0f0f, v27
	v_and_b32_e32 v23, 0xf0f0f0f, v23
	v_and_b32_e32 v19, 0xf0f0f0f, v19
	v_perm_b32 v105, v15, v11, s52
	v_perm_b32 v106, v7, v3, s52
	v_dot4c_i32_i8_e32 v134, s1, v98
	v_and_b32_e32 v79, 0xf0f0f0f, v79
	v_and_b32_e32 v75, 0xf0f0f0f, v75
	v_and_b32_e32 v71, 0xf0f0f0f, v71
	v_and_b32_e32 v67, 0xf0f0f0f, v67
	v_perm_b32 v102, v31, v27, s52
	v_perm_b32 v103, v23, v19, s52
	v_perm_b32 v107, v105, v106, s54
	v_dot4c_i32_i8_e32 v134, s2, v97
	v_and_b32_e32 v95, 0xf0f0f0f, v95
	v_and_b32_e32 v91, 0xf0f0f0f, v91
	v_and_b32_e32 v87, 0xf0f0f0f, v87
	v_and_b32_e32 v83, 0xf0f0f0f, v83
	v_perm_b32 v99, v79, v75, s52
	v_perm_b32 v100, v71, v67, s52
	v_perm_b32 v104, v102, v103, s54
	v_dot4c_i32_i8_e32 v139, s0, v107
	v_dot4c_i32_i8_e32 v134, s3, v96
	v_perm_b32 v96, v95, v91, s52
	v_perm_b32 v97, v87, v83, s52
	v_perm_b32 v101, v99, v100, s54
	v_dot4c_i32_i8_e32 v139, s1, v104
	v_perm_b32 v98, v96, v97, s54
	v_dot4c_i32_i8_e32 v139, s2, v101
	v_perm_b32 v96, v96, v97, s53
	v_perm_b32 v97, v99, v100, s53
	v_perm_b32 v99, v105, v106, s53
	v_perm_b32 v11, v15, v11, s33
	v_perm_b32 v3, v7, v3, s33
	v_dot4c_i32_i8_e32 v139, s3, v98
	v_perm_b32 v98, v102, v103, s53
	v_dot4c_i32_i8_e32 v137, s0, v99
	v_perm_b32 v27, v31, v27, s33
	v_perm_b32 v19, v23, v19, s33
	v_perm_b32 v7, v11, v3, s54
	v_perm_b32 v3, v11, v3, s53
	v_dot4c_i32_i8_e32 v137, s1, v98
	v_perm_b32 v91, v95, v91, s33
	v_perm_b32 v83, v87, v83, s33
	v_perm_b32 v75, v79, v75, s33
	v_perm_b32 v67, v71, v67, s33
	v_perm_b32 v23, v27, v19, s54
	v_perm_b32 v19, v27, v19, s53
	v_dot4c_i32_i8_e32 v136, s0, v3
	v_lshrrev_b32_e32 v101, 4, v14
	v_lshrrev_b32_e32 v102, 4, v10
	v_lshrrev_b32_e32 v104, 4, v6
	v_lshrrev_b32_e32 v105, 4, v2
	v_dot4c_i32_i8_e32 v137, s2, v97
	v_perm_b32 v87, v91, v83, s54
	v_dot4c_i32_i8_e32 v140, s0, v7
	v_perm_b32 v7, v91, v83, s53
	v_perm_b32 v15, v75, v67, s53
	v_dot4c_i32_i8_e32 v136, s1, v19
	v_lshrrev_b32_e32 v91, 4, v30
	v_lshrrev_b32_e32 v95, 4, v26
	v_lshrrev_b32_e32 v97, 4, v22
	v_lshrrev_b32_e32 v98, 4, v18
	v_and_b32_e32 v101, 0xf0f0f0f, v101
	v_and_b32_e32 v102, 0xf0f0f0f, v102
	v_and_b32_e32 v104, 0xf0f0f0f, v104
	v_and_b32_e32 v105, 0xf0f0f0f, v105
	v_perm_b32 v71, v75, v67, s54
	v_dot4c_i32_i8_e32 v136, s2, v15
	v_lshrrev_b32_e32 v31, 4, v78
	v_lshrrev_b32_e32 v67, 4, v74
	v_lshrrev_b32_e32 v75, 4, v70
	v_lshrrev_b32_e32 v79, 4, v66
	v_and_b32_e32 v91, 0xf0f0f0f, v91
	v_and_b32_e32 v95, 0xf0f0f0f, v95
	v_and_b32_e32 v97, 0xf0f0f0f, v97
	v_and_b32_e32 v98, 0xf0f0f0f, v98
	v_perm_b32 v103, v101, v102, s52
	v_perm_b32 v106, v104, v105, s52
	v_dot4c_i32_i8_e32 v137, s3, v96
; __device__ void phase_gather(const Params& p) {
;     ...
;       for (int gi = 0; gi < 64 / GROWS; ++gi) {
;         const int j0 = gi * GROWS;
;         if (gi + 2 < 64 / GROWS) {
; #pragma unroll
;           for (int k = 0; k < GROWS; ++k) {
;             const int e = __builtin_amdgcn_readlane(idv, j0 + 2 * GROWS + k);
;             rr[(gi + 2) % 3][k] = *(const u32x4*)(vb + (size_t)e * 1024 + lane * 16);
;           }
;         }
; #pragma unroll
;         for (int sub = 0; sub < GROWS / 4; ++sub) {
;           const int W4 = __builtin_amdgcn_readlane(pkv, j0 + 4 * sub);
; #pragma unroll
;           for (int m = 0; m < 4; ++m) {
;             unsigned lo[4], hi[4];
; #pragma unroll
;             for (int k = 0; k < 4; ++k) {
;               const unsigned w = rr[gi % 3][sub * 4 + k][m];
;               lo[k] = w & 0x0f0f0f0fu;
;               hi[k] = (w >> 4) & 0x0f0f0f0fu;
;             }
;             {
;               const unsigned p01l = __builtin_amdgcn_perm(lo[1], lo[0], 0x05010400u), p01h = __builtin_amdgcn_perm(lo[1], lo[0], 0x07030602u);
;               const unsigned p23l = __builtin_amdgcn_perm(lo[3], lo[2], 0x05010400u), p23h = __builtin_amdgcn_perm(lo[3], lo[2], 0x07030602u);
;               acc[m * 8 + 0] = __builtin_amdgcn_sdot4((int)__builtin_amdgcn_perm(p23l, p01l, 0x05040100u), W4, acc[m * 8 + 0], false);
;               acc[m * 8 + 1] = __builtin_amdgcn_sdot4((int)__builtin_amdgcn_perm(p23l, p01l, 0x07060302u), W4, acc[m * 8 + 1], false);
;               acc[m * 8 + 2] = __builtin_amdgcn_sdot4((int)__builtin_amdgcn_perm(p23h, p01h, 0x05040100u), W4, acc[m * 8 + 2], false);
;               acc[m * 8 + 3] = __builtin_amdgcn_sdot4((int)__builtin_amdgcn_perm(p23h, p01h, 0x07060302u), W4, acc[m * 8 + 3], false);
;             }
;             {
;               const unsigned p01l = __builtin_amdgcn_perm(hi[1], hi[0], 0x05010400u), p01h = __builtin_amdgcn_perm(hi[1], hi[0], 0x07030602u);
;               const unsigned p23l = __builtin_amdgcn_perm(hi[3], hi[2], 0x05010400u), p23h = __builtin_amdgcn_perm(hi[3], hi[2], 0x07030602u);
;               acc[m * 8 + 4] = __builtin_amdgcn_sdot4((int)__builtin_amdgcn_perm(p23l, p01l, 0x05040100u), W4, acc[m * 8 + 4], false);
;               acc[m * 8 + 5] = __builtin_amdgcn_sdot4((int)__builtin_amdgcn_perm(p23l, p01l, 0x07060302u), W4, acc[m * 8 + 5], false);
	v_dot4c_i32_i8_e32 v140, s1, v23
	v_dot4c_i32_i8_e32 v136, s3, v7
	v_lshrrev_b32_e32 v3, 4, v94
	v_lshrrev_b32_e32 v7, 4, v90
	v_lshrrev_b32_e32 v15, 4, v86
	v_lshrrev_b32_e32 v19, 4, v82
	v_and_b32_e32 v31, 0xf0f0f0f, v31
	v_and_b32_e32 v67, 0xf0f0f0f, v67
	v_and_b32_e32 v75, 0xf0f0f0f, v75
	v_and_b32_e32 v79, 0xf0f0f0f, v79
	v_perm_b32 v96, v91, v95, s52
	v_perm_b32 v99, v97, v98, s52
	v_perm_b32 v107, v103, v106, s54
	v_dot4c_i32_i8_e32 v140, s2, v71
	v_and_b32_e32 v3, 0xf0f0f0f, v3
	v_and_b32_e32 v7, 0xf0f0f0f, v7
	v_and_b32_e32 v15, 0xf0f0f0f, v15
	v_and_b32_e32 v19, 0xf0f0f0f, v19
	v_perm_b32 v71, v31, v67, s52
	v_perm_b32 v83, v75, v79, s52
	v_perm_b32 v100, v96, v99, s54
	v_dot4c_i32_i8_e32 v142, s0, v107
	v_dot4c_i32_i8_e32 v140, s3, v87
	v_perm_b32 v11, v3, v7, s52
	v_perm_b32 v23, v15, v19, s52
	v_perm_b32 v87, v71, v83, s54
	v_dot4c_i32_i8_e32 v142, s1, v100
	v_perm_b32 v27, v11, v23, s54
	v_dot4c_i32_i8_e32 v142, s2, v87
	v_perm_b32 v11, v11, v23, s53
	v_perm_b32 v23, v71, v83, s53
	v_perm_b32 v71, v103, v106, s53
	v_dot4c_i32_i8_e32 v142, s3, v27
	v_perm_b32 v27, v96, v99, s53
	v_dot4c_i32_i8_e32 v141, s0, v71
	v_perm_b32 v3, v3, v7, s33
	v_perm_b32 v7, v15, v19, s33
	v_perm_b32 v19, v75, v79, s33
	v_perm_b32 v71, v101, v102, s33
	v_perm_b32 v75, v104, v105, s33
	v_dot4c_i32_i8_e32 v141, s1, v27
	v_perm_b32 v15, v31, v67, s33
	v_perm_b32 v27, v91, v95, s33
	v_perm_b32 v31, v97, v98, s33
	v_perm_b32 v79, v71, v75, s54
	v_perm_b32 v67, v27, v31, s54
	v_dot4c_i32_i8_e32 v145, s0, v79
	v_dot4c_i32_i8_e32 v141, s2, v23
	v_perm_b32 v23, v15, v19, s54
	v_dot4c_i32_i8_e32 v145, s1, v67
	v_dot4c_i32_i8_e32 v141, s3, v11
	v_perm_b32 v11, v3, v7, s54
	v_dot4c_i32_i8_e32 v145, s2, v23
	v_perm_b32 v3, v3, v7, s53
	v_perm_b32 v7, v15, v19, s53
	v_perm_b32 v15, v71, v75, s53
	v_dot4c_i32_i8_e32 v145, s3, v11
	v_perm_b32 v11, v27, v31, s53
	v_dot4c_i32_i8_e32 v143, s0, v15
	v_and_b32_e32 v14, 0xf0f0f0f, v14
	v_and_b32_e32 v10, 0xf0f0f0f, v10
	v_and_b32_e32 v6, 0xf0f0f0f, v6
	v_and_b32_e32 v2, 0xf0f0f0f, v2
	v_dot4c_i32_i8_e32 v143, s1, v11
	v_and_b32_e32 v15, 0xf0f0f0f, v86
	v_and_b32_e32 v30, 0xf0f0f0f, v30
	v_and_b32_e32 v26, 0xf0f0f0f, v26
	v_and_b32_e32 v22, 0xf0f0f0f, v22
	v_and_b32_e32 v18, 0xf0f0f0f, v18
	v_perm_b32 v83, v14, v10, s52
	v_perm_b32 v86, v6, v2, s52
	v_dot4c_i32_i8_e32 v143, s2, v7
	v_and_b32_e32 v31, 0xf0f0f0f, v78
	v_and_b32_e32 v67, 0xf0f0f0f, v74
	v_and_b32_e32 v70, 0xf0f0f0f, v70
	v_and_b32_e32 v66, 0xf0f0f0f, v66
	v_perm_b32 v78, v30, v26, s52
	v_perm_b32 v79, v22, v18, s52
	v_perm_b32 v87, v83, v86, s54
	v_dot4c_i32_i8_e32 v143, s3, v3
	v_and_b32_e32 v3, 0xf0f0f0f, v94
	v_and_b32_e32 v7, 0xf0f0f0f, v90
	v_and_b32_e32 v19, 0xf0f0f0f, v82
	v_perm_b32 v71, v31, v67, s52
	v_perm_b32 v74, v70, v66, s52
	v_perm_b32 v82, v78, v79, s54
	v_dot4c_i32_i8_e32 v148, s0, v87
	v_perm_b32 v11, v3, v7, s52
	v_perm_b32 v23, v15, v19, s52
	v_perm_b32 v75, v71, v74, s54
	v_dot4c_i32_i8_e32 v148, s1, v82
	v_perm_b32 v27, v11, v23, s54
	v_dot4c_i32_i8_e32 v148, s2, v75
	v_perm_b32 v11, v11, v23, s53
	v_perm_b32 v23, v71, v74, s53
	v_perm_b32 v71, v83, v86, s53
	global_load_dwordx4 v[32:35], v[32:33], off
	v_dot4c_i32_i8_e32 v148, s3, v27
	v_perm_b32 v27, v78, v79, s53
	v_dot4c_i32_i8_e32 v147, s0, v71
	v_dot4c_i32_i8_e32 v147, s1, v27
	v_perm_b32 v10, v14, v10, s33
	v_perm_b32 v2, v6, v2, s33
	v_dot4c_i32_i8_e32 v147, s2, v23
	v_perm_b32 v3, v3, v7, s33
	v_perm_b32 v7, v15, v19, s33
	v_perm_b32 v26, v30, v26, s33
	v_perm_b32 v18, v22, v18, s33
	v_perm_b32 v6, v10, v2, s54
	v_perm_b32 v2, v10, v2, s53
	v_dot4c_i32_i8_e32 v147, s3, v11
	v_perm_b32 v11, v3, v7, s54
	v_perm_b32 v15, v31, v67, s33
	v_perm_b32 v19, v70, v66, s33
	v_perm_b32 v22, v26, v18, s54
	v_dot4c_i32_i8_e32 v153, s0, v6
	v_perm_b32 v3, v3, v7, s53
	v_perm_b32 v7, v26, v18, s53
	v_dot4c_i32_i8_e32 v151, s0, v2
	v_lshrrev_b32_e32 v75, 4, v13
	v_lshrrev_b32_e32 v78, 4, v9
	v_lshrrev_b32_e32 v82, 4, v5
	v_lshrrev_b32_e32 v83, 4, v1
	v_perm_b32 v23, v15, v19, s54
	v_dot4c_i32_i8_e32 v153, s1, v22
	v_perm_b32 v6, v15, v19, s53
	v_dot4c_i32_i8_e32 v151, s1, v7
	v_lshrrev_b32_e32 v30, 4, v29
	v_lshrrev_b32_e32 v31, 4, v25
	v_lshrrev_b32_e32 v67, 4, v21
	v_lshrrev_b32_e32 v70, 4, v17
	v_and_b32_e32 v75, 0xf0f0f0f, v75
	v_and_b32_e32 v78, 0xf0f0f0f, v78
	v_and_b32_e32 v82, 0xf0f0f0f, v82
	v_and_b32_e32 v83, 0xf0f0f0f, v83
	v_dot4c_i32_i8_e32 v153, s2, v23
	v_dot4c_i32_i8_e32 v151, s2, v6
	v_lshrrev_b32_e32 v15, 4, v77
	v_lshrrev_b32_e32 v18, 4, v73
	v_lshrrev_b32_e32 v22, 4, v69
	v_lshrrev_b32_e32 v23, 4, v65
	v_and_b32_e32 v30, 0xf0f0f0f, v30
	v_and_b32_e32 v31, 0xf0f0f0f, v31
	v_and_b32_e32 v67, 0xf0f0f0f, v67
	v_and_b32_e32 v70, 0xf0f0f0f, v70
	v_perm_b32 v79, v75, v78, s52
	v_perm_b32 v86, v82, v83, s52
	v_dot4c_i32_i8_e32 v151, s3, v3
	v_lshrrev_b32_e32 v2, 4, v93
	v_lshrrev_b32_e32 v3, 4, v89
	v_lshrrev_b32_e32 v7, 4, v85
	v_lshrrev_b32_e32 v10, 4, v81
	v_and_b32_e32 v15, 0xf0f0f0f, v15
	v_and_b32_e32 v18, 0xf0f0f0f, v18
	v_and_b32_e32 v22, 0xf0f0f0f, v22
	v_and_b32_e32 v23, 0xf0f0f0f, v23
	v_perm_b32 v66, v30, v31, s52
	v_perm_b32 v71, v67, v70, s52
	v_perm_b32 v87, v79, v86, s54
	v_and_b32_e32 v2, 0xf0f0f0f, v2
	v_and_b32_e32 v3, 0xf0f0f0f, v3
	v_and_b32_e32 v7, 0xf0f0f0f, v7
	v_and_b32_e32 v10, 0xf0f0f0f, v10
	v_perm_b32 v19, v15, v18, s52
	v_perm_b32 v26, v22, v23, s52
	v_perm_b32 v74, v66, v71, s54
	v_dot4c_i32_i8_e32 v156, s0, v87
	v_dot4c_i32_i8_e32 v153, s3, v11
	v_perm_b32 v6, v2, v3, s52
	v_perm_b32 v11, v7, v10, s52
	v_perm_b32 v27, v19, v26, s54
	v_dot4c_i32_i8_e32 v156, s1, v74
	v_perm_b32 v14, v6, v11, s54
	v_dot4c_i32_i8_e32 v156, s2, v27
; __device__ void phase_gather(const Params& p) {
;     ...
; #pragma unroll
;         for (int sub = 0; sub < GROWS / 4; ++sub) {
;           const int W4 = __builtin_amdgcn_readlane(pkv, j0 + 4 * sub);
; #pragma unroll
;           for (int m = 0; m < 4; ++m) {
;             unsigned lo[4], hi[4];
; #pragma unroll
;             for (int k = 0; k < 4; ++k) {
;               const unsigned w = rr[gi % 3][sub * 4 + k][m];
;               lo[k] = w & 0x0f0f0f0fu;
;               hi[k] = (w >> 4) & 0x0f0f0f0fu;
;             }
;             {
;               const unsigned p01l = __builtin_amdgcn_perm(lo[1], lo[0], 0x05010400u), p01h = __builtin_amdgcn_perm(lo[1], lo[0], 0x07030602u);
;               const unsigned p23l = __builtin_amdgcn_perm(lo[3], lo[2], 0x05010400u), p23h = __builtin_amdgcn_perm(lo[3], lo[2], 0x07030602u);
;               acc[m * 8 + 0] = __builtin_amdgcn_sdot4((int)__builtin_amdgcn_perm(p23l, p01l, 0x05040100u), W4, acc[m * 8 + 0], false);
;               acc[m * 8 + 1] = __builtin_amdgcn_sdot4((int)__builtin_amdgcn_perm(p23l, p01l, 0x07060302u), W4, acc[m * 8 + 1], false);
;               acc[m * 8 + 2] = __builtin_amdgcn_sdot4((int)__builtin_amdgcn_perm(p23h, p01h, 0x05040100u), W4, acc[m * 8 + 2], false);
;               acc[m * 8 + 3] = __builtin_amdgcn_sdot4((int)__builtin_amdgcn_perm(p23h, p01h, 0x07060302u), W4, acc[m * 8 + 3], false);
;             }
;             {
;               const unsigned p01l = __builtin_amdgcn_perm(hi[1], hi[0], 0x05010400u), p01h = __builtin_amdgcn_perm(hi[1], hi[0], 0x07030602u);
;               const unsigned p23l = __builtin_amdgcn_perm(hi[3], hi[2], 0x05010400u), p23h = __builtin_amdgcn_perm(hi[3], hi[2], 0x07030602u);
;               acc[m * 8 + 4] = __builtin_amdgcn_sdot4((int)__builtin_amdgcn_perm(p23l, p01l, 0x05040100u), W4, acc[m * 8 + 4], false);
;               acc[m * 8 + 5] = __builtin_amdgcn_sdot4((int)__builtin_amdgcn_perm(p23l, p01l, 0x07060302u), W4, acc[m * 8 + 5], false);
;               acc[m * 8 + 6] = __builtin_amdgcn_sdot4((int)__builtin_amdgcn_perm(p23h, p01h, 0x05040100u), W4, acc[m * 8 + 6], false);
;               acc[m * 8 + 7] = __builtin_amdgcn_sdot4((int)__builtin_amdgcn_perm(p23h, p01h, 0x07060302u), W4, acc[m * 8 + 7], false);
;             }
;           }
;         }
	v_perm_b32 v6, v6, v11, s53
	v_perm_b32 v11, v19, v26, s53
	v_perm_b32 v19, v79, v86, s53
	v_dot4c_i32_i8_e32 v156, s3, v14
	v_perm_b32 v14, v66, v71, s53
	v_dot4c_i32_i8_e32 v155, s0, v19
	v_perm_b32 v2, v2, v3, s33
	v_perm_b32 v3, v7, v10, s33
	v_perm_b32 v10, v22, v23, s33
	v_perm_b32 v19, v75, v78, s33
	v_perm_b32 v22, v82, v83, s33
	v_dot4c_i32_i8_e32 v155, s1, v14
	v_perm_b32 v7, v15, v18, s33
	v_perm_b32 v14, v30, v31, s33
	v_perm_b32 v15, v67, v70, s33
	v_perm_b32 v23, v19, v22, s54
	v_perm_b32 v18, v14, v15, s54
	v_dot4c_i32_i8_e32 v146, s0, v23
	v_dot4c_i32_i8_e32 v155, s2, v11
	v_perm_b32 v11, v7, v10, s54
	v_dot4c_i32_i8_e32 v146, s1, v18
	v_dot4c_i32_i8_e32 v155, s3, v6
	v_perm_b32 v6, v2, v3, s54
	v_dot4c_i32_i8_e32 v146, s2, v11
	v_perm_b32 v2, v2, v3, s53
	v_perm_b32 v3, v7, v10, s53
	v_perm_b32 v7, v19, v22, s53
	v_dot4c_i32_i8_e32 v146, s3, v6
	v_perm_b32 v6, v14, v15, s53
	v_dot4c_i32_i8_e32 v144, s0, v7
	v_and_b32_e32 v13, 0xf0f0f0f, v13
	v_and_b32_e32 v9, 0xf0f0f0f, v9
	v_and_b32_e32 v5, 0xf0f0f0f, v5
	v_and_b32_e32 v1, 0xf0f0f0f, v1
	v_dot4c_i32_i8_e32 v144, s1, v6
	v_and_b32_e32 v29, 0xf0f0f0f, v29
	v_and_b32_e32 v25, 0xf0f0f0f, v25
	v_and_b32_e32 v21, 0xf0f0f0f, v21
	v_and_b32_e32 v17, 0xf0f0f0f, v17
	v_perm_b32 v66, v13, v9, s52
	v_perm_b32 v67, v5, v1, s52
	v_dot4c_i32_i8_e32 v144, s2, v3
	v_and_b32_e32 v15, 0xf0f0f0f, v77
	v_and_b32_e32 v18, 0xf0f0f0f, v73
	v_and_b32_e32 v22, 0xf0f0f0f, v69
	v_and_b32_e32 v23, 0xf0f0f0f, v65
	v_perm_b32 v30, v29, v25, s52
	v_perm_b32 v31, v21, v17, s52
	v_perm_b32 v69, v66, v67, s54
	v_dot4c_i32_i8_e32 v144, s3, v2
	v_and_b32_e32 v2, 0xf0f0f0f, v93
	v_and_b32_e32 v3, 0xf0f0f0f, v89
	v_and_b32_e32 v7, 0xf0f0f0f, v85
	v_and_b32_e32 v10, 0xf0f0f0f, v81
	v_perm_b32 v19, v15, v18, s52
	v_perm_b32 v26, v22, v23, s52
	v_perm_b32 v65, v30, v31, s54
	v_dot4c_i32_i8_e32 v150, s0, v69
	v_perm_b32 v6, v2, v3, s52
	v_perm_b32 v11, v7, v10, s52
	v_perm_b32 v27, v19, v26, s54
	v_dot4c_i32_i8_e32 v150, s1, v65
	v_perm_b32 v14, v6, v11, s54
	v_dot4c_i32_i8_e32 v150, s2, v27
	v_perm_b32 v6, v6, v11, s53
	v_perm_b32 v11, v19, v26, s53
	v_perm_b32 v19, v66, v67, s53
	v_dot4c_i32_i8_e32 v150, s3, v14
	v_perm_b32 v14, v30, v31, s53
	v_dot4c_i32_i8_e32 v149, s0, v19
	v_perm_b32 v9, v13, v9, s33
	v_perm_b32 v1, v5, v1, s33
	v_dot4c_i32_i8_e32 v149, s1, v14
	v_perm_b32 v2, v2, v3, s33
	v_perm_b32 v3, v7, v10, s33
	v_perm_b32 v7, v15, v18, s33
	v_perm_b32 v14, v29, v25, s33
	v_perm_b32 v15, v21, v17, s33
	v_perm_b32 v5, v9, v1, s54
	v_perm_b32 v1, v9, v1, s53
	v_dot4c_i32_i8_e32 v149, s2, v11
	v_perm_b32 v10, v22, v23, s33
	v_perm_b32 v17, v14, v15, s54
	v_dot4c_i32_i8_e32 v154, s0, v5
	v_perm_b32 v5, v14, v15, s53
	v_dot4c_i32_i8_e32 v152, s0, v1
	v_lshrrev_b32_e32 v29, 4, v12
	v_lshrrev_b32_e32 v30, 4, v8
	v_lshrrev_b32_e32 v65, 4, v4
	v_lshrrev_b32_e32 v66, 4, v0
	v_dot4c_i32_i8_e32 v149, s3, v6
	v_perm_b32 v6, v2, v3, s54
	v_perm_b32 v11, v7, v10, s54
	v_dot4c_i32_i8_e32 v154, s1, v17
	v_perm_b32 v2, v2, v3, s53
	v_perm_b32 v3, v7, v10, s53
	v_dot4c_i32_i8_e32 v152, s1, v5
	v_lshrrev_b32_e32 v19, 4, v28
	v_lshrrev_b32_e32 v21, 4, v24
	v_lshrrev_b32_e32 v23, 4, v20
	v_lshrrev_b32_e32 v25, 4, v16
	v_and_b32_e32 v29, 0xf0f0f0f, v29
	v_and_b32_e32 v30, 0xf0f0f0f, v30
	v_and_b32_e32 v65, 0xf0f0f0f, v65
	v_and_b32_e32 v66, 0xf0f0f0f, v66
	v_dot4c_i32_i8_e32 v154, s2, v11
	v_dot4c_i32_i8_e32 v152, s2, v3
	v_lshrrev_b32_e32 v10, 4, v76
	v_lshrrev_b32_e32 v11, 4, v72
	v_lshrrev_b32_e32 v14, 4, v68
	v_lshrrev_b32_e32 v15, 4, v64
	v_and_b32_e32 v19, 0xf0f0f0f, v19
	v_and_b32_e32 v21, 0xf0f0f0f, v21
	v_and_b32_e32 v23, 0xf0f0f0f, v23
	v_and_b32_e32 v25, 0xf0f0f0f, v25
	v_perm_b32 v31, v29, v30, s52
	v_perm_b32 v67, v65, v66, s52
	v_dot4c_i32_i8_e32 v154, s3, v6
	v_dot4c_i32_i8_e32 v152, s3, v2
	v_lshrrev_b32_e32 v1, 4, v92
	v_lshrrev_b32_e32 v2, 4, v88
	v_lshrrev_b32_e32 v5, 4, v84
	v_lshrrev_b32_e32 v6, 4, v80
	v_and_b32_e32 v10, 0xf0f0f0f, v10
	v_and_b32_e32 v11, 0xf0f0f0f, v11
	v_and_b32_e32 v14, 0xf0f0f0f, v14
	v_and_b32_e32 v15, 0xf0f0f0f, v15
	v_perm_b32 v22, v19, v21, s52
	v_perm_b32 v26, v23, v25, s52
	v_perm_b32 v69, v31, v67, s54
	v_and_b32_e32 v1, 0xf0f0f0f, v1
	v_and_b32_e32 v2, 0xf0f0f0f, v2
	v_and_b32_e32 v5, 0xf0f0f0f, v5
	v_and_b32_e32 v6, 0xf0f0f0f, v6
	v_perm_b32 v13, v10, v11, s52
	v_perm_b32 v17, v14, v15, s52
	v_perm_b32 v27, v22, v26, s54
	v_dot4c_i32_i8_e32 v158, s0, v69
	v_perm_b32 v3, v1, v2, s52
	v_perm_b32 v7, v5, v6, s52
	v_perm_b32 v18, v13, v17, s54
	v_dot4c_i32_i8_e32 v158, s1, v27
	v_perm_b32 v9, v3, v7, s54
	v_dot4c_i32_i8_e32 v158, s2, v18
	v_perm_b32 v3, v3, v7, s53
	v_perm_b32 v7, v13, v17, s53
	v_perm_b32 v13, v31, v67, s53
	v_dot4c_i32_i8_e32 v158, s3, v9
	v_perm_b32 v9, v22, v26, s53
	v_dot4c_i32_i8_e32 v157, s0, v13
	v_perm_b32 v1, v1, v2, s33
	v_perm_b32 v2, v5, v6, s33
	v_perm_b32 v6, v14, v15, s33
	v_perm_b32 v13, v29, v30, s33
	v_perm_b32 v14, v65, v66, s33
	v_dot4c_i32_i8_e32 v157, s1, v9
	v_perm_b32 v5, v10, v11, s33
	v_perm_b32 v9, v19, v21, s33
	v_perm_b32 v10, v23, v25, s33
	v_perm_b32 v15, v13, v14, s54
	v_perm_b32 v11, v9, v10, s54
	v_dot4c_i32_i8_e32 v160, s0, v15
	v_dot4c_i32_i8_e32 v157, s2, v7
	v_perm_b32 v7, v5, v6, s54
	v_dot4c_i32_i8_e32 v160, s1, v11
	v_dot4c_i32_i8_e32 v157, s3, v3
	v_perm_b32 v3, v1, v2, s54
	v_dot4c_i32_i8_e32 v160, s2, v7
	v_perm_b32 v1, v1, v2, s53
	v_perm_b32 v2, v5, v6, s53
	v_perm_b32 v5, v13, v14, s53
	v_dot4c_i32_i8_e32 v160, s3, v3
	v_perm_b32 v3, v9, v10, s53
	v_dot4c_i32_i8_e32 v159, s0, v5
	v_and_b32_e32 v12, 0xf0f0f0f, v12
	v_and_b32_e32 v8, 0xf0f0f0f, v8
	v_and_b32_e32 v4, 0xf0f0f0f, v4
	v_and_b32_e32 v0, 0xf0f0f0f, v0
; __device__ void phase_gather(const Params& p) {
;     ...
; #pragma unroll
;         for (int sub = 0; sub < GROWS / 4; ++sub) {
;           const int W4 = __builtin_amdgcn_readlane(pkv, j0 + 4 * sub);
; #pragma unroll
;           for (int m = 0; m < 4; ++m) {
;             unsigned lo[4], hi[4];
; #pragma unroll
;             for (int k = 0; k < 4; ++k) {
;               const unsigned w = rr[gi % 3][sub * 4 + k][m];
;               lo[k] = w & 0x0f0f0f0fu;
;               hi[k] = (w >> 4) & 0x0f0f0f0fu;
;             }
;             {
;               const unsigned p01l = __builtin_amdgcn_perm(lo[1], lo[0], 0x05010400u), p01h = __builtin_amdgcn_perm(lo[1], lo[0], 0x07030602u);
;               const unsigned p23l = __builtin_amdgcn_perm(lo[3], lo[2], 0x05010400u), p23h = __builtin_amdgcn_perm(lo[3], lo[2], 0x07030602u);
;               acc[m * 8 + 0] = __builtin_amdgcn_sdot4((int)__builtin_amdgcn_perm(p23l, p01l, 0x05040100u), W4, acc[m * 8 + 0], false);
;               acc[m * 8 + 1] = __builtin_amdgcn_sdot4((int)__builtin_amdgcn_perm(p23l, p01l, 0x07060302u), W4, acc[m * 8 + 1], false);
;               acc[m * 8 + 2] = __builtin_amdgcn_sdot4((int)__builtin_amdgcn_perm(p23h, p01h, 0x05040100u), W4, acc[m * 8 + 2], false);
;               acc[m * 8 + 3] = __builtin_amdgcn_sdot4((int)__builtin_amdgcn_perm(p23h, p01h, 0x07060302u), W4, acc[m * 8 + 3], false);
;             }
;             {
;               const unsigned p01l = __builtin_amdgcn_perm(hi[1], hi[0], 0x05010400u), p01h = __builtin_amdgcn_perm(hi[1], hi[0], 0x07030602u);
;               const unsigned p23l = __builtin_amdgcn_perm(hi[3], hi[2], 0x05010400u), p23h = __builtin_amdgcn_perm(hi[3], hi[2], 0x07030602u);
;               acc[m * 8 + 4] = __builtin_amdgcn_sdot4((int)__builtin_amdgcn_perm(p23l, p01l, 0x05040100u), W4, acc[m * 8 + 4], false);
;               acc[m * 8 + 5] = __builtin_amdgcn_sdot4((int)__builtin_amdgcn_perm(p23l, p01l, 0x07060302u), W4, acc[m * 8 + 5], false);
;               acc[m * 8 + 6] = __builtin_amdgcn_sdot4((int)__builtin_amdgcn_perm(p23h, p01h, 0x05040100u), W4, acc[m * 8 + 6], false);
;               acc[m * 8 + 7] = __builtin_amdgcn_sdot4((int)__builtin_amdgcn_perm(p23h, p01h, 0x07060302u), W4, acc[m * 8 + 7], false);
;             }
;           }
;         }
	v_dot4c_i32_i8_e32 v159, s1, v3
	v_and_b32_e32 v19, 0xf0f0f0f, v28
	v_and_b32_e32 v21, 0xf0f0f0f, v24
	v_and_b32_e32 v20, 0xf0f0f0f, v20
	v_and_b32_e32 v16, 0xf0f0f0f, v16
	v_perm_b32 v25, v12, v8, s52
	v_perm_b32 v26, v4, v0, s52
	v_dot4c_i32_i8_e32 v159, s2, v2
	v_and_b32_e32 v10, 0xf0f0f0f, v76
	v_and_b32_e32 v11, 0xf0f0f0f, v72
	v_and_b32_e32 v14, 0xf0f0f0f, v68
	v_and_b32_e32 v15, 0xf0f0f0f, v64
	v_perm_b32 v22, v19, v21, s52
	v_perm_b32 v23, v20, v16, s52
	v_perm_b32 v27, v25, v26, s54
	v_dot4c_i32_i8_e32 v159, s3, v1
	v_and_b32_e32 v1, 0xf0f0f0f, v92
	v_and_b32_e32 v2, 0xf0f0f0f, v88
	v_and_b32_e32 v5, 0xf0f0f0f, v84
	v_and_b32_e32 v6, 0xf0f0f0f, v80
	v_perm_b32 v13, v10, v11, s52
	v_perm_b32 v17, v14, v15, s52
	v_perm_b32 v24, v22, v23, s54
	v_dot4c_i32_i8_e32 v162, s0, v27
	v_perm_b32 v3, v1, v2, s52
	v_perm_b32 v7, v5, v6, s52
	v_perm_b32 v18, v13, v17, s54
	v_dot4c_i32_i8_e32 v162, s1, v24
	v_perm_b32 v9, v3, v7, s54
	v_dot4c_i32_i8_e32 v162, s2, v18
	v_perm_b32 v3, v3, v7, s53
	v_perm_b32 v7, v13, v17, s53
	v_perm_b32 v13, v25, v26, s53
	v_dot4c_i32_i8_e32 v162, s3, v9
	v_perm_b32 v9, v22, v23, s53
	v_dot4c_i32_i8_e32 v161, s0, v13
	v_perm_b32 v8, v12, v8, s33
	v_perm_b32 v0, v4, v0, s33
	v_dot4c_i32_i8_e32 v161, s1, v9
	v_perm_b32 v1, v1, v2, s33
	v_perm_b32 v2, v5, v6, s33
	v_perm_b32 v5, v10, v11, s33
	v_perm_b32 v9, v19, v21, s33
	v_perm_b32 v10, v20, v16, s33
	v_perm_b32 v4, v8, v0, s54
	v_perm_b32 v6, v14, v15, s33
	v_perm_b32 v11, v9, v10, s54
	v_dot4c_i32_i8_e32 v164, s0, v4
	v_dot4c_i32_i8_e32 v161, s2, v7
	v_perm_b32 v7, v5, v6, s54
	v_dot4c_i32_i8_e32 v164, s1, v11
	v_dot4c_i32_i8_e32 v161, s3, v3
	v_perm_b32 v3, v1, v2, s54
	v_dot4c_i32_i8_e32 v164, s2, v7
	v_perm_b32 v0, v8, v0, s53
	v_dot4c_i32_i8_e32 v164, s3, v3
	v_perm_b32 v3, v9, v10, s53
	v_dot4c_i32_i8_e32 v163, s0, v0
	v_perm_b32 v1, v1, v2, s53
	v_perm_b32 v2, v5, v6, s53
	v_dot4c_i32_i8_e32 v163, s1, v3
	v_dot4c_i32_i8_e32 v163, s2, v2
	s_waitcnt vmcnt(7)
	v_and_b32_e32 v0, 0xf0f0f0f, v60
	s_waitcnt vmcnt(6)
	v_and_b32_e32 v2, 0xf0f0f0f, v56
	s_waitcnt vmcnt(5)
	v_and_b32_e32 v4, 0xf0f0f0f, v52
	s_waitcnt vmcnt(4)
	v_and_b32_e32 v6, 0xf0f0f0f, v48
	v_perm_b32 v8, v2, v0, s33
	v_perm_b32 v0, v2, v0, s52
	v_perm_b32 v2, v6, v4, s33
	v_dot4c_i32_i8_e32 v163, s3, v1
	v_readlane_b32 s0, v170, 56
	v_lshrrev_b32_e32 v1, 4, v60
	v_lshrrev_b32_e32 v3, 4, v56
	v_lshrrev_b32_e32 v5, 4, v52
	v_lshrrev_b32_e32 v7, 4, v48
	v_perm_b32 v4, v6, v4, s52
	v_perm_b32 v6, v2, v8, s53
	v_perm_b32 v2, v2, v8, s54
	v_and_b32_e32 v1, 0xf0f0f0f, v1
	v_and_b32_e32 v3, 0xf0f0f0f, v3
	v_and_b32_e32 v5, 0xf0f0f0f, v5
	v_and_b32_e32 v7, 0xf0f0f0f, v7
	v_dot4c_i32_i8_e32 v164, s0, v2
	v_perm_b32 v2, v4, v0, s53
	v_perm_b32 v0, v4, v0, s54
	v_dot4c_i32_i8_e32 v161, s0, v2
	v_dot4c_i32_i8_e32 v162, s0, v0
	v_perm_b32 v0, v3, v1, s33
	v_perm_b32 v2, v7, v5, s33
	v_perm_b32 v1, v3, v1, s52
	v_perm_b32 v3, v7, v5, s52
	v_perm_b32 v4, v2, v0, s53
	v_perm_b32 v0, v2, v0, s54
	v_dot4c_i32_i8_e32 v160, s0, v0
	v_perm_b32 v0, v3, v1, s53
	v_dot4c_i32_i8_e32 v157, s0, v0
	v_perm_b32 v0, v3, v1, s54
	v_dot4c_i32_i8_e32 v163, s0, v6
	v_dot4c_i32_i8_e32 v159, s0, v4
	v_dot4c_i32_i8_e32 v158, s0, v0
	v_and_b32_e32 v0, 0xf0f0f0f, v61
	v_and_b32_e32 v2, 0xf0f0f0f, v57
	v_and_b32_e32 v4, 0xf0f0f0f, v53
	v_and_b32_e32 v6, 0xf0f0f0f, v49
	v_perm_b32 v8, v2, v0, s33
	v_perm_b32 v0, v2, v0, s52
	v_perm_b32 v2, v6, v4, s33
	v_lshrrev_b32_e32 v1, 4, v61
	v_lshrrev_b32_e32 v3, 4, v57
	v_lshrrev_b32_e32 v5, 4, v53
	v_lshrrev_b32_e32 v7, 4, v49
	v_perm_b32 v4, v6, v4, s52
	v_perm_b32 v6, v2, v8, s53
	v_perm_b32 v2, v2, v8, s54
	v_and_b32_e32 v1, 0xf0f0f0f, v1
	v_and_b32_e32 v3, 0xf0f0f0f, v3
	v_and_b32_e32 v5, 0xf0f0f0f, v5
	v_and_b32_e32 v7, 0xf0f0f0f, v7
	v_dot4c_i32_i8_e32 v154, s0, v2
	v_perm_b32 v2, v4, v0, s53
	v_perm_b32 v0, v4, v0, s54
	v_dot4c_i32_i8_e32 v149, s0, v2
	v_dot4c_i32_i8_e32 v150, s0, v0
	v_perm_b32 v0, v3, v1, s33
	v_perm_b32 v2, v7, v5, s33
	v_perm_b32 v1, v3, v1, s52
	v_perm_b32 v3, v7, v5, s52
	v_perm_b32 v4, v2, v0, s53
	v_perm_b32 v0, v2, v0, s54
	v_dot4c_i32_i8_e32 v146, s0, v0
	v_perm_b32 v0, v3, v1, s53
	v_dot4c_i32_i8_e32 v155, s0, v0
	v_perm_b32 v0, v3, v1, s54
	v_dot4c_i32_i8_e32 v152, s0, v6
	v_dot4c_i32_i8_e32 v144, s0, v4
	v_dot4c_i32_i8_e32 v156, s0, v0
	v_and_b32_e32 v0, 0xf0f0f0f, v62
	v_and_b32_e32 v2, 0xf0f0f0f, v58
	v_and_b32_e32 v4, 0xf0f0f0f, v54
	v_and_b32_e32 v6, 0xf0f0f0f, v50
	v_perm_b32 v8, v2, v0, s33
	v_perm_b32 v0, v2, v0, s52
	v_perm_b32 v2, v6, v4, s33
	v_lshrrev_b32_e32 v1, 4, v62
	v_lshrrev_b32_e32 v3, 4, v58
	v_lshrrev_b32_e32 v5, 4, v54
	v_lshrrev_b32_e32 v7, 4, v50
	v_perm_b32 v4, v6, v4, s52
	v_perm_b32 v6, v2, v8, s53
	v_perm_b32 v2, v2, v8, s54
	v_and_b32_e32 v1, 0xf0f0f0f, v1
	v_and_b32_e32 v3, 0xf0f0f0f, v3
	v_and_b32_e32 v5, 0xf0f0f0f, v5
	v_and_b32_e32 v7, 0xf0f0f0f, v7
	v_dot4c_i32_i8_e32 v153, s0, v2
	v_perm_b32 v2, v4, v0, s53
	v_perm_b32 v0, v4, v0, s54
	v_dot4c_i32_i8_e32 v147, s0, v2
	v_dot4c_i32_i8_e32 v148, s0, v0
	v_perm_b32 v0, v3, v1, s33
	v_perm_b32 v2, v7, v5, s33
	v_perm_b32 v1, v3, v1, s52
	v_perm_b32 v3, v7, v5, s52
	v_perm_b32 v4, v2, v0, s53
	v_perm_b32 v0, v2, v0, s54
	v_dot4c_i32_i8_e32 v145, s0, v0
	v_perm_b32 v0, v3, v1, s53
	v_dot4c_i32_i8_e32 v141, s0, v0
	v_perm_b32 v0, v3, v1, s54
	v_dot4c_i32_i8_e32 v151, s0, v6
	v_dot4c_i32_i8_e32 v143, s0, v4
	v_dot4c_i32_i8_e32 v142, s0, v0
	v_and_b32_e32 v0, 0xf0f0f0f, v63
	v_and_b32_e32 v2, 0xf0f0f0f, v59
	v_and_b32_e32 v4, 0xf0f0f0f, v55
	v_and_b32_e32 v6, 0xf0f0f0f, v51
	v_perm_b32 v8, v2, v0, s33
	v_perm_b32 v0, v2, v0, s52
	v_perm_b32 v2, v6, v4, s33
	v_lshrrev_b32_e32 v1, 4, v63
	v_lshrrev_b32_e32 v3, 4, v59
	v_lshrrev_b32_e32 v5, 4, v55
	v_lshrrev_b32_e32 v7, 4, v51
	v_perm_b32 v4, v6, v4, s52
	v_perm_b32 v6, v2, v8, s53
	v_perm_b32 v2, v2, v8, s54
	v_and_b32_e32 v1, 0xf0f0f0f, v1
	v_and_b32_e32 v3, 0xf0f0f0f, v3
	v_and_b32_e32 v5, 0xf0f0f0f, v5
	v_and_b32_e32 v7, 0xf0f0f0f, v7
	v_dot4c_i32_i8_e32 v140, s0, v2
	v_perm_b32 v2, v4, v0, s53
	v_perm_b32 v0, v4, v0, s54
	v_dot4c_i32_i8_e32 v137, s0, v2
	v_dot4c_i32_i8_e32 v139, s0, v0
	v_perm_b32 v0, v3, v1, s33
	v_perm_b32 v2, v7, v5, s33
	v_perm_b32 v1, v3, v1, s52
	v_perm_b32 v3, v7, v5, s52
	v_perm_b32 v4, v2, v0, s53
	v_perm_b32 v0, v2, v0, s54
	v_dot4c_i32_i8_e32 v135, s0, v0
	v_perm_b32 v0, v3, v1, s53
	v_dot4c_i32_i8_e32 v123, s0, v0
	v_perm_b32 v0, v3, v1, s54
	v_dot4c_i32_i8_e32 v136, s0, v6
	v_dot4c_i32_i8_e32 v134, s0, v4
	v_dot4c_i32_i8_e32 v125, s0, v0
	s_waitcnt vmcnt(3)
; __device__ void phase_gather(const Params& p) {
;     ...
;           const int W4 = __builtin_amdgcn_readlane(pkv, j0 + 4 * sub);
; #pragma unroll
;           for (int m = 0; m < 4; ++m) {
;             unsigned lo[4], hi[4];
; #pragma unroll
;             for (int k = 0; k < 4; ++k) {
;               const unsigned w = rr[gi % 3][sub * 4 + k][m];
;               lo[k] = w & 0x0f0f0f0fu;
;               hi[k] = (w >> 4) & 0x0f0f0f0fu;
;             }
;             {
;               const unsigned p01l = __builtin_amdgcn_perm(lo[1], lo[0], 0x05010400u), p01h = __builtin_amdgcn_perm(lo[1], lo[0], 0x07030602u);
;               const unsigned p23l = __builtin_amdgcn_perm(lo[3], lo[2], 0x05010400u), p23h = __builtin_amdgcn_perm(lo[3], lo[2], 0x07030602u);
;               acc[m * 8 + 0] = __builtin_amdgcn_sdot4((int)__builtin_amdgcn_perm(p23l, p01l, 0x05040100u), W4, acc[m * 8 + 0], false);
;               acc[m * 8 + 1] = __builtin_amdgcn_sdot4((int)__builtin_amdgcn_perm(p23l, p01l, 0x07060302u), W4, acc[m * 8 + 1], false);
;               acc[m * 8 + 2] = __builtin_amdgcn_sdot4((int)__builtin_amdgcn_perm(p23h, p01h, 0x05040100u), W4, acc[m * 8 + 2], false);
;               acc[m * 8 + 3] = __builtin_amdgcn_sdot4((int)__builtin_amdgcn_perm(p23h, p01h, 0x07060302u), W4, acc[m * 8 + 3], false);
;             }
;             {
;               const unsigned p01l = __builtin_amdgcn_perm(hi[1], hi[0], 0x05010400u), p01h = __builtin_amdgcn_perm(hi[1], hi[0], 0x07030602u);
;               const unsigned p23l = __builtin_amdgcn_perm(hi[3], hi[2], 0x05010400u), p23h = __builtin_amdgcn_perm(hi[3], hi[2], 0x07030602u);
;               acc[m * 8 + 4] = __builtin_amdgcn_sdot4((int)__builtin_amdgcn_perm(p23l, p01l, 0x05040100u), W4, acc[m * 8 + 4], false);
;               acc[m * 8 + 5] = __builtin_amdgcn_sdot4((int)__builtin_amdgcn_perm(p23l, p01l, 0x07060302u), W4, acc[m * 8 + 5], false);
;               acc[m * 8 + 6] = __builtin_amdgcn_sdot4((int)__builtin_amdgcn_perm(p23h, p01h, 0x05040100u), W4, acc[m * 8 + 6], false);
;               acc[m * 8 + 7] = __builtin_amdgcn_sdot4((int)__builtin_amdgcn_perm(p23h, p01h, 0x07060302u), W4, acc[m * 8 + 7], false);
	v_and_b32_e32 v0, 0xf0f0f0f, v44
	s_waitcnt vmcnt(2)
	v_and_b32_e32 v2, 0xf0f0f0f, v40
	s_waitcnt vmcnt(1)
	v_and_b32_e32 v4, 0xf0f0f0f, v36
	s_waitcnt vmcnt(0)
	v_and_b32_e32 v6, 0xf0f0f0f, v32
	v_perm_b32 v8, v2, v0, s33
	v_perm_b32 v0, v2, v0, s52
	v_perm_b32 v2, v6, v4, s33
	v_readlane_b32 s0, v170, 60
	v_lshrrev_b32_e32 v1, 4, v44
	v_lshrrev_b32_e32 v3, 4, v40
	v_lshrrev_b32_e32 v5, 4, v36
	v_lshrrev_b32_e32 v7, 4, v32
	v_perm_b32 v4, v6, v4, s52
	v_perm_b32 v6, v2, v8, s53
	v_perm_b32 v2, v2, v8, s54
	v_and_b32_e32 v1, 0xf0f0f0f, v1
	v_and_b32_e32 v3, 0xf0f0f0f, v3
	v_and_b32_e32 v5, 0xf0f0f0f, v5
	v_and_b32_e32 v7, 0xf0f0f0f, v7
	v_dot4c_i32_i8_e32 v164, s0, v2
	v_perm_b32 v2, v4, v0, s53
	v_perm_b32 v0, v4, v0, s54
	v_dot4c_i32_i8_e32 v161, s0, v2
	v_dot4c_i32_i8_e32 v162, s0, v0
	v_perm_b32 v0, v3, v1, s33
	v_perm_b32 v2, v7, v5, s33
	v_perm_b32 v1, v3, v1, s52
	v_perm_b32 v3, v7, v5, s52
	v_perm_b32 v4, v2, v0, s53
	v_perm_b32 v0, v2, v0, s54
	v_dot4c_i32_i8_e32 v160, s0, v0
	v_perm_b32 v0, v3, v1, s53
	v_dot4c_i32_i8_e32 v157, s0, v0
	v_perm_b32 v0, v3, v1, s54
	v_dot4c_i32_i8_e32 v163, s0, v6
	v_dot4c_i32_i8_e32 v159, s0, v4
	v_dot4c_i32_i8_e32 v158, s0, v0
	v_and_b32_e32 v0, 0xf0f0f0f, v45
	v_and_b32_e32 v2, 0xf0f0f0f, v41
	v_and_b32_e32 v4, 0xf0f0f0f, v37
	v_and_b32_e32 v6, 0xf0f0f0f, v33
	v_perm_b32 v8, v2, v0, s33
	v_perm_b32 v0, v2, v0, s52
	v_perm_b32 v2, v6, v4, s33
	v_lshrrev_b32_e32 v1, 4, v45
	v_lshrrev_b32_e32 v3, 4, v41
	v_lshrrev_b32_e32 v5, 4, v37
	v_lshrrev_b32_e32 v7, 4, v33
	v_perm_b32 v4, v6, v4, s52
	v_perm_b32 v6, v2, v8, s53
	v_perm_b32 v2, v2, v8, s54
	v_and_b32_e32 v1, 0xf0f0f0f, v1
	v_and_b32_e32 v3, 0xf0f0f0f, v3
	v_and_b32_e32 v5, 0xf0f0f0f, v5
	v_and_b32_e32 v7, 0xf0f0f0f, v7
	v_dot4c_i32_i8_e32 v154, s0, v2
	v_perm_b32 v2, v4, v0, s53
	v_perm_b32 v0, v4, v0, s54
	v_dot4c_i32_i8_e32 v149, s0, v2
	v_dot4c_i32_i8_e32 v150, s0, v0
	v_perm_b32 v0, v3, v1, s33
	v_perm_b32 v2, v7, v5, s33
	v_perm_b32 v1, v3, v1, s52
	v_perm_b32 v3, v7, v5, s52
	v_perm_b32 v4, v2, v0, s53
	v_perm_b32 v0, v2, v0, s54
	v_dot4c_i32_i8_e32 v146, s0, v0
	v_perm_b32 v0, v3, v1, s53
	v_dot4c_i32_i8_e32 v155, s0, v0
	v_perm_b32 v0, v3, v1, s54
	v_dot4c_i32_i8_e32 v152, s0, v6
	v_dot4c_i32_i8_e32 v144, s0, v4
	v_dot4c_i32_i8_e32 v156, s0, v0
	v_and_b32_e32 v0, 0xf0f0f0f, v46
	v_and_b32_e32 v2, 0xf0f0f0f, v42
	v_and_b32_e32 v4, 0xf0f0f0f, v38
	v_and_b32_e32 v6, 0xf0f0f0f, v34
	v_perm_b32 v8, v2, v0, s33
	v_perm_b32 v0, v2, v0, s52
	v_perm_b32 v2, v6, v4, s33
	v_lshrrev_b32_e32 v1, 4, v46
	v_lshrrev_b32_e32 v3, 4, v42
	v_lshrrev_b32_e32 v5, 4, v38
	v_lshrrev_b32_e32 v7, 4, v34
	v_perm_b32 v4, v6, v4, s52
	v_perm_b32 v6, v2, v8, s53
	v_perm_b32 v2, v2, v8, s54
	v_and_b32_e32 v1, 0xf0f0f0f, v1
	v_and_b32_e32 v3, 0xf0f0f0f, v3
	v_and_b32_e32 v5, 0xf0f0f0f, v5
	v_and_b32_e32 v7, 0xf0f0f0f, v7
	v_dot4c_i32_i8_e32 v153, s0, v2
	v_perm_b32 v2, v4, v0, s53
	v_perm_b32 v0, v4, v0, s54
	v_dot4c_i32_i8_e32 v147, s0, v2
	v_dot4c_i32_i8_e32 v148, s0, v0
	v_perm_b32 v0, v3, v1, s33
	v_perm_b32 v2, v7, v5, s33
	v_perm_b32 v1, v3, v1, s52
	v_perm_b32 v3, v7, v5, s52
	v_perm_b32 v4, v2, v0, s53
	v_perm_b32 v0, v2, v0, s54
	v_dot4c_i32_i8_e32 v145, s0, v0
	v_perm_b32 v0, v3, v1, s53
	v_dot4c_i32_i8_e32 v141, s0, v0
	v_perm_b32 v0, v3, v1, s54
	v_dot4c_i32_i8_e32 v151, s0, v6
	v_dot4c_i32_i8_e32 v142, s0, v0
	v_and_b32_e32 v0, 0xf0f0f0f, v47
	v_lshrrev_b32_e32 v1, 4, v47
	v_and_b32_e32 v5, 0xf0f0f0f, v43
	v_and_b32_e32 v6, 0xf0f0f0f, v39
	v_and_b32_e32 v7, 0xf0f0f0f, v35
	v_and_b32_e32 v2, 0xf0f0f0f, v1
	v_lshrrev_b32_e32 v1, 4, v43
	v_perm_b32 v8, v5, v0, s33
	v_perm_b32 v0, v5, v0, s52
	v_perm_b32 v5, v7, v6, s33
	v_dot4c_i32_i8_e32 v143, s0, v4
	v_and_b32_e32 v4, 0xf0f0f0f, v1
	v_lshrrev_b32_e32 v1, 4, v39
	v_lshrrev_b32_e32 v3, 4, v35
	v_perm_b32 v6, v7, v6, s52
	v_perm_b32 v7, v5, v8, s53
	v_perm_b32 v5, v5, v8, s54
	v_and_b32_e32 v1, 0xf0f0f0f, v1
	v_and_b32_e32 v3, 0xf0f0f0f, v3
	v_dot4c_i32_i8_e32 v140, s0, v5
	v_perm_b32 v5, v6, v0, s53
	v_perm_b32 v0, v6, v0, s54
	v_dot4c_i32_i8_e32 v139, s0, v0
	v_perm_b32 v0, v4, v2, s33
	v_perm_b32 v2, v4, v2, s52
	v_perm_b32 v4, v3, v1, s33
	v_perm_b32 v1, v3, v1, s52
	v_perm_b32 v3, v4, v0, s53
	v_perm_b32 v0, v4, v0, s54
	v_dot4c_i32_i8_e32 v135, s0, v0
	v_perm_b32 v0, v1, v2, s53
	v_dot4c_i32_i8_e32 v123, s0, v0
	v_perm_b32 v0, v1, v2, s54
	v_dot4c_i32_i8_e32 v136, s0, v7
	v_dot4c_i32_i8_e32 v137, s0, v5
	v_dot4c_i32_i8_e32 v134, s0, v3
	v_dot4c_i32_i8_e32 v125, s0, v0
	s_mov_b64 s[0:1], 0
	s_cbranch_vccz .LBB0_1321
; __device__ void phase_gather(const Params& p) {
;     ...
;     float val[32];
;     float ss = 0.f;
;     const int off8 = 8 * wsumq;
; #pragma unroll
;     for (int q = 0; q < 8; ++q) {
;       f32x4 v = *(const f32x4*)(orow + q * 4);
; #pragma unroll
;       for (int k = 0; k < 4; ++k) {
;         val[q * 4 + k] = sw * (float)(acc[q * 4 + k] - off8) + v[k];
;         ss += val[q * 4 + k] * val[q * 4 + k];
;       }
;     }
	s_setprio 3
	v_lshlrev_b64 v[0:1], 13, v[112:113]
	v_lshl_add_u64 v[4:5], v[118:119], 0, v[0:1]
	global_load_dwordx4 v[6:9], v[4:5], off
	global_load_dwordx4 v[10:13], v[4:5], off offset:16
	global_load_dwordx4 v[14:17], v[4:5], off offset:32
	global_load_dwordx4 v[18:21], v[4:5], off offset:48
	global_load_dwordx4 v[22:25], v[4:5], off offset:64
	global_load_dwordx4 v[26:29], v[4:5], off offset:80
	global_load_dwordx4 v[0:3], v[120:121], off
	global_load_dwordx4 v[30:33], v[4:5], off offset:112
	global_load_dwordx4 v[34:37], v[4:5], off offset:96
	s_waitcnt lgkmcnt(0)
	v_add_lshl_u32 v39, v166, v167, 3
	v_sub_u32_e32 v40, v163, v39
	v_sub_u32_e32 v41, v164, v39
	v_sub_u32_e32 v42, v161, v39
	v_sub_u32_e32 v43, v162, v39
	v_cvt_f32_i32_e32 v41, v41
	v_cvt_f32_i32_e32 v40, v40
	v_cvt_f32_i32_e32 v43, v43
	v_cvt_f32_i32_e32 v42, v42
	v_sub_u32_e32 v44, v159, v39
	v_sub_u32_e32 v45, v160, v39
	v_mul_f32_e32 v38, 0x3c010204, v165
	v_cvt_f32_i32_e32 v45, v45
	v_cvt_f32_i32_e32 v44, v44
	v_sub_u32_e32 v46, v157, v39
	v_sub_u32_e32 v47, v158, v39
	v_cvt_f32_i32_e32 v47, v47
	v_cvt_f32_i32_e32 v46, v46
	v_sub_u32_e32 v48, v152, v39
	v_sub_u32_e32 v49, v154, v39
	v_cvt_f32_i32_e32 v49, v49
	v_cvt_f32_i32_e32 v48, v48
	v_sub_u32_e32 v50, v149, v39
	v_sub_u32_e32 v51, v150, v39
	v_cvt_f32_i32_e32 v51, v51
	v_cvt_f32_i32_e32 v50, v50
	v_sub_u32_e32 v52, v144, v39
	v_sub_u32_e32 v53, v146, v39
	v_cvt_f32_i32_e32 v53, v53
	v_cvt_f32_i32_e32 v52, v52
	v_sub_u32_e32 v54, v155, v39
	v_sub_u32_e32 v55, v156, v39
	v_cvt_f32_i32_e32 v55, v55
	v_cvt_f32_i32_e32 v54, v54
	v_sub_u32_e32 v56, v151, v39
	v_sub_u32_e32 v57, v153, v39
	v_cvt_f32_i32_e32 v57, v57
	v_cvt_f32_i32_e32 v56, v56
	v_sub_u32_e32 v58, v147, v39
	v_sub_u32_e32 v59, v148, v39
	v_sub_u32_e32 v62, v141, v39
	v_sub_u32_e32 v63, v142, v39
	v_cvt_f32_i32_e32 v59, v59
	v_cvt_f32_i32_e32 v58, v58
	v_sub_u32_e32 v60, v143, v39
	v_sub_u32_e32 v61, v145, v39
	v_cvt_f32_i32_e32 v63, v63
	v_cvt_f32_i32_e32 v62, v62
	v_cvt_f32_i32_e32 v61, v61
	v_cvt_f32_i32_e32 v60, v60
	v_sub_u32_e32 v64, v137, v39
	v_sub_u32_e32 v65, v139, v39
	v_cvt_f32_i32_e32 v65, v65
	v_cvt_f32_i32_e32 v64, v64
	v_sub_u32_e32 v68, v123, v39
	v_cvt_f32_i32_e32 v68, v68
	v_readlane_b32 s68, v250, 28
	s_movk_i32 s0, 0x3fff
	v_readlane_b32 s70, v250, 30
	v_add_u32_e32 v112, s68, v112
	v_readlane_b32 s71, v250, 31
	v_readlane_b32 s69, v250, 29
	s_waitcnt vmcnt(8)
	v_pk_fma_f32 v[6:7], v[38:39], v[40:41], v[6:7] op_sel_hi:[0,1,1]
	v_pk_fma_f32 v[8:9], v[38:39], v[42:43], v[8:9] op_sel_hi:[0,1,1]
	v_pk_mul_f32 v[40:41], v[6:7], v[6:7]
	v_pk_mul_f32 v[42:43], v[8:9], v[8:9]
	v_add_f32_e32 v40, v40, v41
	s_waitcnt vmcnt(7)
	v_pk_fma_f32 v[10:11], v[38:39], v[44:45], v[10:11] op_sel_hi:[0,1,1]
	v_add_f32_e32 v40, v42, v40
	v_pk_mul_f32 v[44:45], v[10:11], v[10:11]
	v_add_f32_e32 v40, v43, v40
	v_pk_fma_f32 v[12:13], v[38:39], v[46:47], v[12:13] op_sel_hi:[0,1,1]
	v_add_f32_e32 v40, v44, v40
	v_pk_mul_f32 v[46:47], v[12:13], v[12:13]
	v_add_f32_e32 v40, v45, v40
	s_waitcnt vmcnt(6)
	v_pk_fma_f32 v[14:15], v[38:39], v[48:49], v[14:15] op_sel_hi:[0,1,1]
	v_add_f32_e32 v40, v46, v40
	v_pk_mul_f32 v[48:49], v[14:15], v[14:15]
	v_add_f32_e32 v40, v47, v40
	v_pk_fma_f32 v[16:17], v[38:39], v[50:51], v[16:17] op_sel_hi:[0,1,1]
	v_add_f32_e32 v40, v48, v40
	v_pk_mul_f32 v[50:51], v[16:17], v[16:17]
	v_add_f32_e32 v40, v49, v40
	s_waitcnt vmcnt(5)
	v_pk_fma_f32 v[18:19], v[38:39], v[52:53], v[18:19] op_sel_hi:[0,1,1]
	v_add_f32_e32 v40, v50, v40
	v_pk_mul_f32 v[52:53], v[18:19], v[18:19]
	v_add_f32_e32 v40, v51, v40
	v_pk_fma_f32 v[20:21], v[38:39], v[54:55], v[20:21] op_sel_hi:[0,1,1]
	v_add_f32_e32 v40, v52, v40
	v_pk_mul_f32 v[54:55], v[20:21], v[20:21]
	v_add_f32_e32 v40, v53, v40
	s_waitcnt vmcnt(4)
	v_pk_fma_f32 v[22:23], v[38:39], v[56:57], v[22:23] op_sel_hi:[0,1,1]
	v_add_f32_e32 v40, v54, v40
	v_pk_mul_f32 v[56:57], v[22:23], v[22:23]
	v_add_f32_e32 v40, v55, v40
	v_pk_fma_f32 v[24:25], v[38:39], v[58:59], v[24:25] op_sel_hi:[0,1,1]
	v_add_f32_e32 v40, v56, v40
	s_waitcnt vmcnt(3)
; __device__ void phase_gather(const Params& p) {
;     ...
;     for (int q = 0; q < 8; ++q) {
;       f32x4 v = *(const f32x4*)(orow + q * 4);
; #pragma unroll
;       for (int k = 0; k < 4; ++k) {
;         val[q * 4 + k] = sw * (float)(acc[q * 4 + k] - off8) + v[k];
;         ss += val[q * 4 + k] * val[q * 4 + k];
;       }
;     }
;     ss = wave_sum(ss);
;     const float rs3 = rsqrtf(ss * (1.f / 2048.f) + EPSV);
; #pragma unroll
;     for (int q = 0; q < 8; ++q) {
;       f32x4 wf = *(const f32x4*)(p.norm_final_w + lane * 32 + q * 4);
;       f32x4 o = {val[q * 4 + 0] * rs3 * wf[0], val[q * 4 + 1] * rs3 * wf[1], val[q * 4 + 2] * rs3 * wf[2],
;                  val[q * 4 + 3] * rs3 * wf[3]};
;       *(f32x4*)(orow + q * 4) = o;
;     }
	v_pk_fma_f32 v[28:29], v[38:39], v[62:63], v[28:29] op_sel_hi:[0,1,1]
	v_pk_mul_f32 v[58:59], v[24:25], v[24:25]
	v_sub_u32_e32 v62, v136, v39
	v_sub_u32_e32 v63, v140, v39
	v_add_f32_e32 v40, v57, v40
	v_pk_fma_f32 v[26:27], v[38:39], v[60:61], v[26:27] op_sel_hi:[0,1,1]
	v_cvt_f32_i32_e32 v63, v63
	v_cvt_f32_i32_e32 v62, v62
	v_add_f32_e32 v40, v58, v40
	v_pk_mul_f32 v[60:61], v[26:27], v[26:27]
	v_add_f32_e32 v40, v59, v40
	v_add_f32_e32 v40, v60, v40
	v_pk_mul_f32 v[66:67], v[28:29], v[28:29]
	s_waitcnt vmcnt(0)
	v_pk_fma_f32 v[36:37], v[38:39], v[64:65], v[36:37] op_sel_hi:[0,1,1]
	v_sub_u32_e32 v64, v134, v39
	v_sub_u32_e32 v65, v135, v39
	v_add_f32_e32 v40, v61, v40
	v_pk_fma_f32 v[34:35], v[38:39], v[62:63], v[34:35] op_sel_hi:[0,1,1]
	v_cvt_f32_i32_e32 v65, v65
	v_cvt_f32_i32_e32 v64, v64
	v_add_f32_e32 v40, v66, v40
	v_pk_mul_f32 v[62:63], v[34:35], v[34:35]
	v_sub_u32_e32 v39, v125, v39
	v_add_f32_e32 v40, v67, v40
	v_cvt_f32_i32_e32 v69, v39
	v_add_f32_e32 v40, v62, v40
	v_pk_mul_f32 v[70:71], v[36:37], v[36:37]
	v_add_f32_e32 v40, v63, v40
	v_pk_fma_f32 v[30:31], v[38:39], v[64:65], v[30:31] op_sel_hi:[0,1,1]
	v_add_f32_e32 v40, v70, v40
	v_pk_mul_f32 v[64:65], v[30:31], v[30:31]
	v_add_f32_e32 v40, v71, v40
	v_pk_fma_f32 v[32:33], v[38:39], v[68:69], v[32:33] op_sel_hi:[0,1,1]
	v_add_f32_e32 v40, v64, v40
	v_pk_mul_f32 v[38:39], v[32:33], v[32:33]
	v_add_f32_e32 v40, v65, v40
	v_add_f32_e32 v38, v38, v40
	v_add_f32_e32 v38, v39, v38
	ds_bpermute_b32 v39, v126, v38
	s_waitcnt lgkmcnt(0)
	v_add_f32_e32 v38, v38, v39
	ds_bpermute_b32 v39, v127, v38
	s_waitcnt lgkmcnt(0)
	v_add_f32_e32 v38, v38, v39
	ds_bpermute_b32 v39, v128, v38
	s_waitcnt lgkmcnt(0)
	v_add_f32_e32 v38, v38, v39
	ds_bpermute_b32 v39, v129, v38
	s_waitcnt lgkmcnt(0)
	v_add_f32_e32 v38, v38, v39
	ds_bpermute_b32 v39, v130, v38
	s_waitcnt lgkmcnt(0)
	v_add_f32_e32 v38, v38, v39
	ds_bpermute_b32 v39, v131, v38
	s_waitcnt lgkmcnt(0)
	v_add_f32_e32 v38, v38, v39
	v_fmamk_f32 v38, v38, 0x3a000000, v133
	v_mul_f32_e32 v39, 0x4b800000, v38
	v_cmp_gt_f32_e32 vcc, s55, v38
	s_nop 1
	v_cndmask_b32_e32 v38, v38, v39, vcc
	v_rsq_f32_e32 v38, v38
	s_nop 0
	v_mul_f32_e32 v39, 0x45800000, v38
	v_cndmask_b32_e32 v38, v38, v39, vcc
	v_pk_mul_f32 v[6:7], v[6:7], v[38:39] op_sel_hi:[1,0]
	v_pk_mul_f32 v[8:9], v[8:9], v[38:39] op_sel_hi:[1,0]
	v_pk_mul_f32 v[0:1], v[0:1], v[6:7]
	v_pk_mul_f32 v[2:3], v[2:3], v[8:9]
	global_store_dwordx4 v[4:5], v[0:3], off
	v_pk_mul_f32 v[6:7], v[12:13], v[38:39] op_sel_hi:[1,0]
	v_pk_mul_f32 v[8:9], v[10:11], v[38:39] op_sel_hi:[1,0]
	v_cmp_lt_i32_e32 vcc, s0, v112
	v_readlane_b32 s0, v250, 32
	v_readlane_b32 s1, v250, 33
	s_or_b64 s[0:1], vcc, s[0:1]
	v_pk_mul_f32 v[0:1], v[188:189], v[8:9]
	v_pk_mul_f32 v[2:3], v[190:191], v[6:7]
	global_store_dwordx4 v[4:5], v[0:3], off offset:16
	v_pk_mul_f32 v[6:7], v[16:17], v[38:39] op_sel_hi:[1,0]
	v_pk_mul_f32 v[8:9], v[14:15], v[38:39] op_sel_hi:[1,0]
	v_pk_mul_f32 v[2:3], v[194:195], v[6:7]
	v_pk_mul_f32 v[0:1], v[192:193], v[8:9]
	global_store_dwordx4 v[4:5], v[0:3], off offset:32
	v_pk_mul_f32 v[6:7], v[20:21], v[38:39] op_sel_hi:[1,0]
	v_pk_mul_f32 v[8:9], v[18:19], v[38:39] op_sel_hi:[1,0]
	v_pk_mul_f32 v[2:3], v[198:199], v[6:7]
	v_pk_mul_f32 v[0:1], v[196:197], v[8:9]
	global_store_dwordx4 v[4:5], v[0:3], off offset:48
	v_pk_mul_f32 v[6:7], v[24:25], v[38:39] op_sel_hi:[1,0]
	v_pk_mul_f32 v[8:9], v[22:23], v[38:39] op_sel_hi:[1,0]
	v_pk_mul_f32 v[2:3], v[202:203], v[6:7]
	v_pk_mul_f32 v[0:1], v[200:201], v[8:9]
	global_store_dwordx4 v[4:5], v[0:3], off offset:64
	v_pk_mul_f32 v[6:7], v[28:29], v[38:39] op_sel_hi:[1,0]
	v_pk_mul_f32 v[8:9], v[26:27], v[38:39] op_sel_hi:[1,0]
	v_pk_mul_f32 v[2:3], v[206:207], v[6:7]
	v_pk_mul_f32 v[0:1], v[204:205], v[8:9]
	global_store_dwordx4 v[4:5], v[0:3], off offset:80
	v_pk_mul_f32 v[6:7], v[36:37], v[38:39] op_sel_hi:[1,0]
	v_pk_mul_f32 v[8:9], v[34:35], v[38:39] op_sel_hi:[1,0]
	v_pk_mul_f32 v[2:3], v[210:211], v[6:7]
	v_pk_mul_f32 v[0:1], v[208:209], v[8:9]
	global_store_dwordx4 v[4:5], v[0:3], off offset:96
	v_pk_mul_f32 v[6:7], v[32:33], v[38:39] op_sel_hi:[1,0]
	v_pk_mul_f32 v[8:9], v[30:31], v[38:39] op_sel_hi:[1,0]
	v_pk_mul_f32 v[2:3], v[214:215], v[6:7]
	v_pk_mul_f32 v[0:1], v[212:213], v[8:9]
	global_store_dwordx4 v[4:5], v[0:3], off offset:112
	s_andn2_b64 exec, exec, s[0:1]
	s_cbranch_execnz .LBB0_1318
